# B-fragment LDS read addresses: four per-iteration v_add_u32 replaced by one loop-invariant VGPR plus ds_read offset immediates (K-loop load segments now VALU-free in most loops)
# speedup vs baseline: 1.0284x; 1.0078x over previous
; #define G_STAGE(bufoff, gbase, o0, h64) do { \
;         __builtin_amdgcn_global_load_lds((const unsigned*)((const char*)(gbase) + (o0)), (LAS unsigned*)(lds + (bufoff) + ldsw), 16, 0, 0); \
;         __builtin_amdgcn_global_load_lds((const unsigned*)((const char*)(gbase) + (h64) + (o0)), (LAS unsigned*)(lds + (bufoff) + ldsw + 8192), 16, 0, 0); } while (0)
; #define G_LDA(dst, b, h) do { _Pragma("unroll") for (int m = 0; m < 4; ++m) _Pragma("unroll") for (int k = 0; k < 2; ++k) dst[m][k] = *(const LAS bf16x8*)(lds + G_SA(b, h) + aoff + m * 2048 + k * 1024); } while (0)
; #define G_LDB(dst, b, h) do { _Pragma("unroll") for (int n = 0; n < 2; ++n) _Pragma("unroll") for (int k = 0; k < 2; ++k) dst[n][k] = *(const LAS bf16x8*)(lds + G_SB(b, h) + boff + n * 2048 + k * 1024); } while (0)
; #define G_WAIT_L(n) asm volatile("s_waitcnt lgkmcnt(" #n ")" ::: "memory")
; #define G_BAR __builtin_amdgcn_s_barrier()
; #define G_SCHED __builtin_amdgcn_sched_barrier(0)
;     ...
;         for (int t = 0; t < nt; t += 2) {
;             const bool last = (t == nt - 2);
;             const char* a1 = cA + (size_t)(t + 1) * ckA;
;             const char* a2 = last ? nA : cA + (size_t)(t + 2) * ckA; const char* b2 = last ? nB : cB + (size_t)(t + 2) * kB;
;             const char* a3 = a2 + ckA; const char* b3 = b2 + kB;
;             G_LDB(B0, 0, 0); G_SCHED; G_LDA(At, 0, 0); G_STAGE(G_SA(1, 1), a1 + chA, cA0, qA);
;             G_WAIT_L(8); G_BAR; G_WAIT_L(0); G_MMA(0, 0, At, B0); G_BAR; G_SCHED;
;             G_LDB(B1, 0, 1); G_STAGE(G_SB(0, 0), b2, cB0, qB);
;             G_BAR; G_WAIT_L(0); G_MMA(0, 1, At, B1); G_BAR;
;     ...
;         for (int a = 0; a < 2; ++a)
; #pragma unroll
;             for (int b = 0; b < 2; ++b)
; #pragma unroll
;                 for (int m = 0; m < 4; ++m)
; #pragma unroll
;                     for (int n = 0; n < 2; ++n) acc[a][b][m][n] = (f32x4){0.f, 0.f, 0.f, 0.f};
.LBB0_211:
	s_add_u32 s2, s2, 0x40080
	s_addc_u32 s3, s3, 0
	s_add_u32 s7, s22, 0x100
	v_mov_b64_e32 v[8:9], 0
	s_addc_u32 s22, s23, 0
	s_mov_b32 s23, -2
	v_mov_b64_e32 v[10:11], 0
	v_mov_b64_e32 v[12:13], 0
	v_mov_b64_e32 v[14:15], 0
	v_mov_b64_e32 v[24:25], 0
	v_mov_b64_e32 v[26:27], 0
	v_mov_b64_e32 v[28:29], 0
	v_mov_b64_e32 v[30:31], 0
	v_mov_b64_e32 v[40:41], 0
	v_mov_b64_e32 v[42:43], 0
	v_mov_b64_e32 v[44:45], 0
	v_mov_b64_e32 v[46:47], 0
	v_mov_b64_e32 v[56:57], 0
	v_mov_b64_e32 v[58:59], 0
	v_mov_b64_e32 v[60:61], 0
	v_mov_b64_e32 v[62:63], 0
	v_mov_b64_e32 v[16:17], 0
	v_mov_b64_e32 v[18:19], 0
	v_mov_b64_e32 v[20:21], 0
	v_mov_b64_e32 v[22:23], 0
	v_mov_b64_e32 v[32:33], 0
	v_mov_b64_e32 v[34:35], 0
	v_mov_b64_e32 v[36:37], 0
	v_mov_b64_e32 v[38:39], 0
	v_mov_b64_e32 v[48:49], 0
	v_mov_b64_e32 v[50:51], 0
	v_mov_b64_e32 v[52:53], 0
	v_mov_b64_e32 v[54:55], 0
	v_mov_b64_e32 v[64:65], 0
	v_mov_b64_e32 v[66:67], 0
	v_mov_b64_e32 v[68:69], 0
	v_mov_b64_e32 v[70:71], 0
	v_mov_b64_e32 v[72:73], 0
	v_mov_b64_e32 v[74:75], 0
	v_mov_b64_e32 v[76:77], 0
	v_mov_b64_e32 v[78:79], 0
	v_mov_b64_e32 v[88:89], 0
	v_mov_b64_e32 v[90:91], 0
	v_mov_b64_e32 v[92:93], 0
	v_mov_b64_e32 v[94:95], 0
	v_mov_b64_e32 v[104:105], 0
	v_mov_b64_e32 v[106:107], 0
	v_mov_b64_e32 v[108:109], 0
	v_mov_b64_e32 v[110:111], 0
	v_mov_b64_e32 v[120:121], 0
	v_mov_b64_e32 v[122:123], 0
	v_mov_b64_e32 v[124:125], 0
	v_mov_b64_e32 v[126:127], 0
	v_mov_b64_e32 v[80:81], 0
	v_mov_b64_e32 v[82:83], 0
	v_mov_b64_e32 v[84:85], 0
	v_mov_b64_e32 v[86:87], 0
	v_mov_b64_e32 v[96:97], 0
	v_mov_b64_e32 v[98:99], 0
	v_mov_b64_e32 v[100:101], 0
	v_mov_b64_e32 v[102:103], 0
	v_mov_b64_e32 v[112:113], 0
	v_mov_b64_e32 v[114:115], 0
	v_mov_b64_e32 v[116:117], 0
	v_mov_b64_e32 v[118:119], 0
	v_mov_b64_e32 v[128:129], 0
	v_mov_b64_e32 v[130:131], 0
	v_mov_b64_e32 v[132:133], 0
	v_mov_b64_e32 v[134:135], 0
	s_mov_b64 s[52:53], 0x40000
	s_mov_b64 s[54:55], 0x60000
	s_mov_b64 s[58:59], 0x20080
	s_mov_b64 s[62:63], 0x40080
	s_mov_b64 s[64:65], 0x60080
	s_cmp_eq_u32 s101, 2
	s_cselect_b32 s101, 0, s101
	v_add_u32_e32 v255, 0x10000, v167
.LBB0_212:
	s_add_u32 s4, s2, 0xfffc0080
	s_addc_u32 s5, s3, -1
	s_add_i32 s41, 0, 0x10000
	ds_read_b128 v[136:139], v255 offset:0
	ds_read_b128 v[144:147], v255 offset:1024
	ds_read_b128 v[148:151], v255 offset:2048
	ds_read_b128 v[152:155], v255 offset:3072
	s_cmp_eq_u32 s23, 12
	s_cselect_b32 s43, s19, s5
	s_cselect_b32 s42, s18, s4
	s_cselect_b32 s51, s21, s22
	s_cselect_b32 s50, s20, s7
	s_add_i32 m0, s27, 0xc000
	ds_read_b128 v[156:159], v172
	ds_read_b128 v[160:163], v172 offset:1024
	ds_read_b128 v[174:177], v172 offset:2048
	ds_read_b128 v[178:181], v172 offset:3072
	ds_read_b128 v[182:185], v172 offset:4096
	ds_read_b128 v[196:199], v172 offset:5120
	ds_read_b128 v[200:203], v172 offset:6144
	ds_read_b128 v[204:207], v172 offset:7168
	global_load_lds_dwordx4 v142, s[2:3]
	s_add_i32 m0, s27, 0xe000
	s_nop 0
	s_add_u32 vcc_lo, s2, s0
	s_addc_u32 vcc_hi, s3, s1
	global_load_lds_dwordx4 v142, vcc
	s_waitcnt lgkmcnt(8)
	s_cmp_eq_u32 s101, 1
	s_cbranch_scc1 .Ldb_WIN_sk
	s_barrier
.Ldb_WIN_sk:
	s_mov_b32 s101, 0
	s_waitcnt lgkmcnt(0)
	v_mfma_f32_16x16x32_bf16 v[132:135], v[136:139], v[156:159], v[132:135]
	v_mfma_f32_16x16x32_bf16 v[128:131], v[148:151], v[156:159], v[128:131]
	v_mfma_f32_16x16x32_bf16 v[116:119], v[136:139], v[174:177], v[116:119]
	v_mfma_f32_16x16x32_bf16 v[112:115], v[148:151], v[174:177], v[112:115]
	v_mfma_f32_16x16x32_bf16 v[100:103], v[136:139], v[182:185], v[100:103]
	v_mfma_f32_16x16x32_bf16 v[96:99], v[148:151], v[182:185], v[96:99]
	v_mfma_f32_16x16x32_bf16 v[84:87], v[136:139], v[200:203], v[84:87]
	v_mfma_f32_16x16x32_bf16 v[80:83], v[148:151], v[200:203], v[80:83]
	v_mfma_f32_16x16x32_bf16 v[132:135], v[144:147], v[160:163], v[132:135]
	v_mfma_f32_16x16x32_bf16 v[128:131], v[152:155], v[160:163], v[128:131]
	v_mfma_f32_16x16x32_bf16 v[116:119], v[144:147], v[178:181], v[116:119]
	v_mfma_f32_16x16x32_bf16 v[112:115], v[152:155], v[178:181], v[112:115]
	v_mfma_f32_16x16x32_bf16 v[100:103], v[144:147], v[196:199], v[100:103]
	v_mfma_f32_16x16x32_bf16 v[96:99], v[152:155], v[196:199], v[96:99]
	v_mfma_f32_16x16x32_bf16 v[84:87], v[144:147], v[204:207], v[84:87]
	v_mfma_f32_16x16x32_bf16 v[80:83], v[152:155], v[204:207], v[80:83]
	s_barrier
	s_add_i32 s4, 0, 0x14000
	s_add_i32 s5, s41, s26
	s_mov_b32 m0, s5
	ds_read_b128 v[208:211], v255 offset:16384
	ds_read_b128 v[212:215], v255 offset:17408
	ds_read_b128 v[216:219], v255 offset:18432
	ds_read_b128 v[220:223], v255 offset:19456
	global_load_lds_dwordx4 v140, s[50:51]
	s_add_i32 m0, s5, 0x2000
	s_nop 0
	s_add_u32 vcc_lo, s50, s0
	s_addc_u32 vcc_hi, s51, s1
	global_load_lds_dwordx4 v140, vcc
	s_barrier
	s_waitcnt lgkmcnt(0)
	v_mfma_f32_16x16x32_bf16 v[124:127], v[208:211], v[156:159], v[124:127]
	v_mfma_f32_16x16x32_bf16 v[120:123], v[216:219], v[156:159], v[120:123]
	v_mfma_f32_16x16x32_bf16 v[108:111], v[208:211], v[174:177], v[108:111]
	v_mfma_f32_16x16x32_bf16 v[104:107], v[216:219], v[174:177], v[104:107]
	v_mfma_f32_16x16x32_bf16 v[92:95], v[208:211], v[182:185], v[92:95]
	v_mfma_f32_16x16x32_bf16 v[88:91], v[216:219], v[182:185], v[88:91]
	v_mfma_f32_16x16x32_bf16 v[76:79], v[208:211], v[200:203], v[76:79]
	v_mfma_f32_16x16x32_bf16 v[72:75], v[216:219], v[200:203], v[72:75]
	v_mfma_f32_16x16x32_bf16 v[124:127], v[212:215], v[160:163], v[124:127]
	v_mfma_f32_16x16x32_bf16 v[120:123], v[220:223], v[160:163], v[120:123]
	v_mfma_f32_16x16x32_bf16 v[108:111], v[212:215], v[178:181], v[108:111]
	v_mfma_f32_16x16x32_bf16 v[104:107], v[220:223], v[178:181], v[104:107]
	v_mfma_f32_16x16x32_bf16 v[92:95], v[212:215], v[196:199], v[92:95]
	v_mfma_f32_16x16x32_bf16 v[88:91], v[220:223], v[196:199], v[88:91]
	v_mfma_f32_16x16x32_bf16 v[76:79], v[212:215], v[204:207], v[76:79]
	v_mfma_f32_16x16x32_bf16 v[72:75], v[220:223], v[204:207], v[72:75]
	s_barrier
; #define G_STAGE(bufoff, gbase, o0, h64) do { \
;         __builtin_amdgcn_global_load_lds((const unsigned*)((const char*)(gbase) + (o0)), (LAS unsigned*)(lds + (bufoff) + ldsw), 16, 0, 0); \
;         __builtin_amdgcn_global_load_lds((const unsigned*)((const char*)(gbase) + (h64) + (o0)), (LAS unsigned*)(lds + (bufoff) + ldsw + 8192), 16, 0, 0); } while (0)
; #define G_LDA(dst, b, h) do { _Pragma("unroll") for (int m = 0; m < 4; ++m) _Pragma("unroll") for (int k = 0; k < 2; ++k) dst[m][k] = *(const LAS bf16x8*)(lds + G_SA(b, h) + aoff + m * 2048 + k * 1024); } while (0)
; #define G_LDB(dst, b, h) do { _Pragma("unroll") for (int n = 0; n < 2; ++n) _Pragma("unroll") for (int k = 0; k < 2; ++k) dst[n][k] = *(const LAS bf16x8*)(lds + G_SB(b, h) + boff + n * 2048 + k * 1024); } while (0)
; #define G_WAIT_V(n) asm volatile("s_waitcnt vmcnt(" #n ")" ::: "memory")
; #define G_WAIT_L(n) asm volatile("s_waitcnt lgkmcnt(" #n ")" ::: "memory")
; #define G_BAR __builtin_amdgcn_s_barrier()
; #define G_SCHED __builtin_amdgcn_sched_barrier(0)
;     ...
;             G_LDA(At, 0, 1); G_STAGE(G_SA(0, 0), a2, cA0, qA);
;             G_BAR; G_WAIT_L(0); G_MMA(1, 0, At, B0); G_BAR; G_SCHED;
;             G_STAGE(G_SB(0, 1), b2 + chB, cB0, qB);
;             G_WAIT_V(6); G_BAR; G_MMA(1, 1, At, B1); G_BAR;
;             G_LDB(B0, 1, 0); G_SCHED; G_LDA(At, 1, 0); G_STAGE(G_SA(0, 1), a2 + chA, cA0, qA);
;             G_WAIT_L(8); G_BAR; G_WAIT_L(0); G_MMA(0, 0, At, B0); G_BAR; G_SCHED;
	s_mov_b32 m0, s27
	ds_read_b128 v[156:159], v172 offset:16384
	ds_read_b128 v[160:163], v172 offset:17408
	ds_read_b128 v[174:177], v172 offset:18432
	ds_read_b128 v[178:181], v172 offset:19456
	ds_read_b128 v[182:185], v172 offset:20480
	ds_read_b128 v[196:199], v172 offset:21504
	ds_read_b128 v[200:203], v172 offset:22528
	ds_read_b128 v[204:207], v172 offset:23552
	global_load_lds_dwordx4 v2, s[42:43]
	s_mov_b32 m0, s28
	s_nop 0
	s_add_u32 vcc_lo, s42, s0
	s_addc_u32 vcc_hi, s43, s1
	global_load_lds_dwordx4 v2, vcc
	s_barrier
	s_waitcnt lgkmcnt(0)
	v_mfma_f32_16x16x32_bf16 v[68:71], v[136:139], v[156:159], v[68:71]
	v_mfma_f32_16x16x32_bf16 v[64:67], v[148:151], v[156:159], v[64:67]
	v_mfma_f32_16x16x32_bf16 v[52:55], v[136:139], v[174:177], v[52:55]
	v_mfma_f32_16x16x32_bf16 v[48:51], v[148:151], v[174:177], v[48:51]
	v_mfma_f32_16x16x32_bf16 v[36:39], v[136:139], v[182:185], v[36:39]
	v_mfma_f32_16x16x32_bf16 v[32:35], v[148:151], v[182:185], v[32:35]
	v_mfma_f32_16x16x32_bf16 v[20:23], v[136:139], v[200:203], v[20:23]
	v_mfma_f32_16x16x32_bf16 v[16:19], v[148:151], v[200:203], v[16:19]
	v_mfma_f32_16x16x32_bf16 v[68:71], v[144:147], v[160:163], v[68:71]
	v_mfma_f32_16x16x32_bf16 v[64:67], v[152:155], v[160:163], v[64:67]
	v_mfma_f32_16x16x32_bf16 v[52:55], v[144:147], v[178:181], v[52:55]
	v_mfma_f32_16x16x32_bf16 v[48:51], v[152:155], v[178:181], v[48:51]
	v_mfma_f32_16x16x32_bf16 v[36:39], v[144:147], v[196:199], v[36:39]
	v_mfma_f32_16x16x32_bf16 v[32:35], v[152:155], v[196:199], v[32:35]
	v_mfma_f32_16x16x32_bf16 v[20:23], v[144:147], v[204:207], v[20:23]
	v_mfma_f32_16x16x32_bf16 v[16:19], v[152:155], v[204:207], v[16:19]
	s_barrier
	s_add_i32 s4, s4, s26
	s_mov_b32 m0, s4
	s_nop 0
	s_add_u32 vcc_lo, s50, s52
	s_addc_u32 vcc_hi, s51, s53
	global_load_lds_dwordx4 v140, vcc
	s_add_i32 m0, s4, 0x2000
	s_nop 0
	s_add_u32 vcc_lo, s50, s54
	s_addc_u32 vcc_hi, s51, s55
	global_load_lds_dwordx4 v140, vcc
	s_waitcnt vmcnt(6)
	s_barrier
	v_mfma_f32_16x16x32_bf16 v[60:63], v[208:211], v[156:159], v[60:63]
	v_mfma_f32_16x16x32_bf16 v[56:59], v[216:219], v[156:159], v[56:59]
	v_mfma_f32_16x16x32_bf16 v[44:47], v[208:211], v[174:177], v[44:47]
	v_mfma_f32_16x16x32_bf16 v[40:43], v[216:219], v[174:177], v[40:43]
	v_mfma_f32_16x16x32_bf16 v[28:31], v[208:211], v[182:185], v[28:31]
	v_mfma_f32_16x16x32_bf16 v[24:27], v[216:219], v[182:185], v[24:27]
	v_mfma_f32_16x16x32_bf16 v[12:15], v[208:211], v[200:203], v[12:15]
	v_mfma_f32_16x16x32_bf16 v[8:11], v[216:219], v[200:203], v[8:11]
	v_mfma_f32_16x16x32_bf16 v[60:63], v[212:215], v[160:163], v[60:63]
	v_mfma_f32_16x16x32_bf16 v[56:59], v[220:223], v[160:163], v[56:59]
	v_mfma_f32_16x16x32_bf16 v[44:47], v[212:215], v[178:181], v[44:47]
	v_mfma_f32_16x16x32_bf16 v[40:43], v[220:223], v[178:181], v[40:43]
	v_mfma_f32_16x16x32_bf16 v[28:31], v[212:215], v[196:199], v[28:31]
	v_mfma_f32_16x16x32_bf16 v[24:27], v[220:223], v[196:199], v[24:27]
	v_mfma_f32_16x16x32_bf16 v[12:15], v[212:215], v[204:207], v[12:15]
	v_mfma_f32_16x16x32_bf16 v[8:11], v[220:223], v[204:207], v[8:11]
	s_barrier
	s_add_i32 s4, 0, 0x18000
	ds_read_b128 v[136:139], v255 offset:32768
	ds_read_b128 v[144:147], v255 offset:33792
	ds_read_b128 v[148:151], v255 offset:34816
	ds_read_b128 v[152:155], v255 offset:35840
	s_mov_b32 m0, s29
	ds_read_b128 v[156:159], v172 offset:32768
	ds_read_b128 v[160:163], v172 offset:33792
	ds_read_b128 v[174:177], v172 offset:34816
	ds_read_b128 v[178:181], v172 offset:35840
	ds_read_b128 v[182:185], v172 offset:36864
	ds_read_b128 v[196:199], v172 offset:37888
	ds_read_b128 v[200:203], v172 offset:38912
	ds_read_b128 v[204:207], v172 offset:39936
	s_add_u32 vcc_lo, s42, s52
	s_addc_u32 vcc_hi, s43, s53
	global_load_lds_dwordx4 v2, vcc
	s_mov_b32 m0, s30
	s_nop 0
	s_add_u32 vcc_lo, s42, s54
	s_addc_u32 vcc_hi, s43, s55
	global_load_lds_dwordx4 v2, vcc
	s_waitcnt lgkmcnt(8)
	s_barrier
	s_waitcnt lgkmcnt(0)
	v_mfma_f32_16x16x32_bf16 v[132:135], v[136:139], v[156:159], v[132:135]
	v_mfma_f32_16x16x32_bf16 v[128:131], v[148:151], v[156:159], v[128:131]
	v_mfma_f32_16x16x32_bf16 v[116:119], v[136:139], v[174:177], v[116:119]
	v_mfma_f32_16x16x32_bf16 v[112:115], v[148:151], v[174:177], v[112:115]
	v_mfma_f32_16x16x32_bf16 v[100:103], v[136:139], v[182:185], v[100:103]
	v_mfma_f32_16x16x32_bf16 v[96:99], v[148:151], v[182:185], v[96:99]
	v_mfma_f32_16x16x32_bf16 v[84:87], v[136:139], v[200:203], v[84:87]
	v_mfma_f32_16x16x32_bf16 v[80:83], v[148:151], v[200:203], v[80:83]
	v_mfma_f32_16x16x32_bf16 v[132:135], v[144:147], v[160:163], v[132:135]
	v_mfma_f32_16x16x32_bf16 v[128:131], v[152:155], v[160:163], v[128:131]
	v_mfma_f32_16x16x32_bf16 v[116:119], v[144:147], v[178:181], v[116:119]
	v_mfma_f32_16x16x32_bf16 v[112:115], v[152:155], v[178:181], v[112:115]
	v_mfma_f32_16x16x32_bf16 v[100:103], v[144:147], v[196:199], v[100:103]
	v_mfma_f32_16x16x32_bf16 v[96:99], v[152:155], v[196:199], v[96:99]
	v_mfma_f32_16x16x32_bf16 v[84:87], v[144:147], v[204:207], v[84:87]
	v_mfma_f32_16x16x32_bf16 v[80:83], v[152:155], v[204:207], v[80:83]
	s_barrier
; #define G_STAGE(bufoff, gbase, o0, h64) do { \
;         __builtin_amdgcn_global_load_lds((const unsigned*)((const char*)(gbase) + (o0)), (LAS unsigned*)(lds + (bufoff) + ldsw), 16, 0, 0); \
;         __builtin_amdgcn_global_load_lds((const unsigned*)((const char*)(gbase) + (h64) + (o0)), (LAS unsigned*)(lds + (bufoff) + ldsw + 8192), 16, 0, 0); } while (0)
; #define G_LDA(dst, b, h) do { _Pragma("unroll") for (int m = 0; m < 4; ++m) _Pragma("unroll") for (int k = 0; k < 2; ++k) dst[m][k] = *(const LAS bf16x8*)(lds + G_SA(b, h) + aoff + m * 2048 + k * 1024); } while (0)
; #define G_LDB(dst, b, h) do { _Pragma("unroll") for (int n = 0; n < 2; ++n) _Pragma("unroll") for (int k = 0; k < 2; ++k) dst[n][k] = *(const LAS bf16x8*)(lds + G_SB(b, h) + boff + n * 2048 + k * 1024); } while (0)
; #define G_WAIT_V(n) asm volatile("s_waitcnt vmcnt(" #n ")" ::: "memory")
; #define G_WAIT_L(n) asm volatile("s_waitcnt lgkmcnt(" #n ")" ::: "memory")
; #define G_BAR __builtin_amdgcn_s_barrier()
; #define G_SCHED __builtin_amdgcn_sched_barrier(0)
;     ...
;             G_LDB(B1, 1, 1); G_STAGE(G_SB(1, 0), b3, cB0, qB);
;             G_BAR; G_WAIT_L(0); G_MMA(0, 1, At, B1); G_BAR;
;             G_LDA(At, 1, 1); G_STAGE(G_SA(1, 0), a3, cA0, qA);
;             G_BAR; G_WAIT_L(0); G_MMA(1, 0, At, B0); G_BAR; G_SCHED;
;             G_STAGE(G_SB(1, 1), b3 + chB, cB0, qB);
;             G_WAIT_V(6); G_BAR; G_MMA(1, 1, At, B1); G_BAR;
	s_add_i32 s5, 0, 0x1c000
	s_add_i32 s4, s4, s26
	s_mov_b32 m0, s4
	ds_read_b128 v[208:211], v255 offset:49152
	ds_read_b128 v[212:215], v255 offset:50176
	ds_read_b128 v[216:219], v255 offset:51200
	ds_read_b128 v[220:223], v255 offset:52224
	s_add_u32 vcc_lo, s50, s46
	s_addc_u32 vcc_hi, s51, s47
	global_load_lds_dwordx4 v140, vcc
	s_add_i32 m0, s4, 0x2000
	s_nop 0
	s_add_u32 vcc_lo, s50, s58
	s_addc_u32 vcc_hi, s51, s59
	global_load_lds_dwordx4 v140, vcc
	s_barrier
	s_waitcnt lgkmcnt(0)
	v_mfma_f32_16x16x32_bf16 v[124:127], v[208:211], v[156:159], v[124:127]
	v_mfma_f32_16x16x32_bf16 v[120:123], v[216:219], v[156:159], v[120:123]
	v_mfma_f32_16x16x32_bf16 v[108:111], v[208:211], v[174:177], v[108:111]
	v_mfma_f32_16x16x32_bf16 v[104:107], v[216:219], v[174:177], v[104:107]
	v_mfma_f32_16x16x32_bf16 v[92:95], v[208:211], v[182:185], v[92:95]
	v_mfma_f32_16x16x32_bf16 v[88:91], v[216:219], v[182:185], v[88:91]
	v_mfma_f32_16x16x32_bf16 v[76:79], v[208:211], v[200:203], v[76:79]
	v_mfma_f32_16x16x32_bf16 v[72:75], v[216:219], v[200:203], v[72:75]
	v_mfma_f32_16x16x32_bf16 v[124:127], v[212:215], v[160:163], v[124:127]
	v_mfma_f32_16x16x32_bf16 v[120:123], v[220:223], v[160:163], v[120:123]
	v_mfma_f32_16x16x32_bf16 v[108:111], v[212:215], v[178:181], v[108:111]
	v_mfma_f32_16x16x32_bf16 v[104:107], v[220:223], v[178:181], v[104:107]
	v_mfma_f32_16x16x32_bf16 v[92:95], v[212:215], v[196:199], v[92:95]
	v_mfma_f32_16x16x32_bf16 v[88:91], v[220:223], v[196:199], v[88:91]
	v_mfma_f32_16x16x32_bf16 v[76:79], v[212:215], v[204:207], v[76:79]
	v_mfma_f32_16x16x32_bf16 v[72:75], v[220:223], v[204:207], v[72:75]
	s_barrier
	s_mov_b32 m0, s31
	ds_read_b128 v[156:159], v172 offset:49152
	ds_read_b128 v[160:163], v172 offset:50176
	ds_read_b128 v[174:177], v172 offset:51200
	ds_read_b128 v[178:181], v172 offset:52224
	ds_read_b128 v[182:185], v172 offset:53248
	ds_read_b128 v[196:199], v172 offset:54272
	ds_read_b128 v[200:203], v172 offset:55296
	ds_read_b128 v[204:207], v172 offset:56320
	s_add_u32 vcc_lo, s42, s46
	s_addc_u32 vcc_hi, s43, s47
	global_load_lds_dwordx4 v2, vcc
	s_mov_b32 m0, s34
	s_nop 0
	s_add_u32 vcc_lo, s42, s58
	s_addc_u32 vcc_hi, s43, s59
	global_load_lds_dwordx4 v2, vcc
	s_barrier
	s_waitcnt lgkmcnt(0)
	v_mfma_f32_16x16x32_bf16 v[68:71], v[136:139], v[156:159], v[68:71]
	v_mfma_f32_16x16x32_bf16 v[64:67], v[148:151], v[156:159], v[64:67]
	v_mfma_f32_16x16x32_bf16 v[52:55], v[136:139], v[174:177], v[52:55]
	v_mfma_f32_16x16x32_bf16 v[48:51], v[148:151], v[174:177], v[48:51]
	v_mfma_f32_16x16x32_bf16 v[36:39], v[136:139], v[182:185], v[36:39]
	v_mfma_f32_16x16x32_bf16 v[32:35], v[148:151], v[182:185], v[32:35]
	v_mfma_f32_16x16x32_bf16 v[20:23], v[136:139], v[200:203], v[20:23]
	v_mfma_f32_16x16x32_bf16 v[16:19], v[148:151], v[200:203], v[16:19]
	v_mfma_f32_16x16x32_bf16 v[68:71], v[144:147], v[160:163], v[68:71]
	v_mfma_f32_16x16x32_bf16 v[64:67], v[152:155], v[160:163], v[64:67]
	v_mfma_f32_16x16x32_bf16 v[52:55], v[144:147], v[178:181], v[52:55]
	v_mfma_f32_16x16x32_bf16 v[48:51], v[152:155], v[178:181], v[48:51]
	v_mfma_f32_16x16x32_bf16 v[36:39], v[144:147], v[196:199], v[36:39]
	v_mfma_f32_16x16x32_bf16 v[32:35], v[152:155], v[196:199], v[32:35]
	v_mfma_f32_16x16x32_bf16 v[20:23], v[144:147], v[204:207], v[20:23]
	v_mfma_f32_16x16x32_bf16 v[16:19], v[152:155], v[204:207], v[16:19]
	s_barrier
	s_add_i32 s4, s5, s26
	s_mov_b32 m0, s4
	s_nop 0
	s_add_u32 vcc_lo, s50, s62
	s_addc_u32 vcc_hi, s51, s63
	global_load_lds_dwordx4 v140, vcc
	s_add_i32 m0, s4, 0x2000
	s_nop 0
	s_add_u32 vcc_lo, s50, s64
	s_addc_u32 vcc_hi, s51, s65
	global_load_lds_dwordx4 v140, vcc
	s_add_i32 s23, s23, 2
	s_add_u32 s2, s2, 0x100
	s_addc_u32 s3, s3, 0
	s_add_u32 s7, s7, 0x100
	s_addc_u32 s22, s22, 0
	s_cmp_gt_u32 s23, 13
	s_waitcnt vmcnt(6)
	s_barrier
	v_mfma_f32_16x16x32_bf16 v[60:63], v[208:211], v[156:159], v[60:63]
	v_mfma_f32_16x16x32_bf16 v[56:59], v[216:219], v[156:159], v[56:59]
	v_mfma_f32_16x16x32_bf16 v[44:47], v[208:211], v[174:177], v[44:47]
	v_mfma_f32_16x16x32_bf16 v[40:43], v[216:219], v[174:177], v[40:43]
	v_mfma_f32_16x16x32_bf16 v[28:31], v[208:211], v[182:185], v[28:31]
	v_mfma_f32_16x16x32_bf16 v[24:27], v[216:219], v[182:185], v[24:27]
	v_mfma_f32_16x16x32_bf16 v[12:15], v[208:211], v[200:203], v[12:15]
	v_mfma_f32_16x16x32_bf16 v[8:11], v[216:219], v[200:203], v[8:11]
	v_mfma_f32_16x16x32_bf16 v[60:63], v[212:215], v[160:163], v[60:63]
	v_mfma_f32_16x16x32_bf16 v[56:59], v[220:223], v[160:163], v[56:59]
	v_mfma_f32_16x16x32_bf16 v[44:47], v[212:215], v[178:181], v[44:47]
	v_mfma_f32_16x16x32_bf16 v[40:43], v[220:223], v[178:181], v[40:43]
	v_mfma_f32_16x16x32_bf16 v[28:31], v[212:215], v[196:199], v[28:31]
	v_mfma_f32_16x16x32_bf16 v[24:27], v[220:223], v[196:199], v[24:27]
	v_mfma_f32_16x16x32_bf16 v[12:15], v[212:215], v[204:207], v[12:15]
	v_mfma_f32_16x16x32_bf16 v[8:11], v[220:223], v[204:207], v[8:11]
	s_cbranch_scc0 .Ldb_WIN_cont
	v_readfirstlane_b32 s101, v186
	s_cmpk_gt_u32 s101, 0xff
	s_cbranch_scc1 .Ldb_WIN_young
	s_barrier
	s_mov_b32 s101, 1
	s_branch .Ldb_WIN_exit

; #define G_STAGE(bufoff, gbase, o0, h64) do { \
;         __builtin_amdgcn_global_load_lds((const unsigned*)((const char*)(gbase) + (o0)), (LAS unsigned*)(lds + (bufoff) + ldsw), 16, 0, 0); \
;         __builtin_amdgcn_global_load_lds((const unsigned*)((const char*)(gbase) + (h64) + (o0)), (LAS unsigned*)(lds + (bufoff) + ldsw + 8192), 16, 0, 0); } while (0)
; #define G_LDA(dst, b, h) do { _Pragma("unroll") for (int m = 0; m < 4; ++m) _Pragma("unroll") for (int k = 0; k < 2; ++k) dst[m][k] = *(const LAS bf16x8*)(lds + G_SA(b, h) + aoff + m * 2048 + k * 1024); } while (0)
; #define G_LDB(dst, b, h) do { _Pragma("unroll") for (int n = 0; n < 2; ++n) _Pragma("unroll") for (int k = 0; k < 2; ++k) dst[n][k] = *(const LAS bf16x8*)(lds + G_SB(b, h) + boff + n * 2048 + k * 1024); } while (0)
; #define G_WAIT_L(n) asm volatile("s_waitcnt lgkmcnt(" #n ")" ::: "memory")
; #define G_BAR __builtin_amdgcn_s_barrier()
; #define G_SCHED __builtin_amdgcn_sched_barrier(0)
;     ...
;         for (int t = 0; t < nt; t += 2) {
;             const bool last = (t == nt - 2);
;             const char* a1 = cA + (size_t)(t + 1) * ckA;
;             const char* a2 = last ? nA : cA + (size_t)(t + 2) * ckA; const char* b2 = last ? nB : cB + (size_t)(t + 2) * kB;
;             const char* a3 = a2 + ckA; const char* b3 = b2 + kB;
;             G_LDB(B0, 0, 0); G_SCHED; G_LDA(At, 0, 0); G_STAGE(G_SA(1, 1), a1 + chA, cA0, qA);
;             G_WAIT_L(8); G_BAR; G_WAIT_L(0); G_MMA(0, 0, At, B0); G_BAR; G_SCHED;
;             G_LDB(B1, 0, 1); G_STAGE(G_SB(0, 0), b2, cB0, qB);
;             G_BAR; G_WAIT_L(0); G_MMA(0, 1, At, B1); G_BAR;
;     ...
;         for (int a = 0; a < 2; ++a)
; #pragma unroll
;             for (int b = 0; b < 2; ++b)
; #pragma unroll
;                 for (int m = 0; m < 4; ++m)
; #pragma unroll
;                     for (int n = 0; n < 2; ++n) acc[a][b][m][n] = (f32x4){0.f, 0.f, 0.f, 0.f};
.LBB0_449:
	s_add_u32 s6, s22, 0x20080
	s_addc_u32 s7, s23, 0
	s_add_u32 s19, s20, 0x100
	v_mov_b64_e32 v[8:9], 0
	s_addc_u32 s20, s21, 0
	s_mov_b32 s21, -2
	v_mov_b64_e32 v[10:11], 0
	v_mov_b64_e32 v[12:13], 0
	v_mov_b64_e32 v[14:15], 0
	v_mov_b64_e32 v[24:25], 0
	v_mov_b64_e32 v[26:27], 0
	v_mov_b64_e32 v[28:29], 0
	v_mov_b64_e32 v[30:31], 0
	v_mov_b64_e32 v[40:41], 0
	v_mov_b64_e32 v[42:43], 0
	v_mov_b64_e32 v[44:45], 0
	v_mov_b64_e32 v[46:47], 0
	v_mov_b64_e32 v[56:57], 0
	v_mov_b64_e32 v[58:59], 0
	v_mov_b64_e32 v[60:61], 0
	v_mov_b64_e32 v[62:63], 0
	v_mov_b64_e32 v[16:17], 0
	v_mov_b64_e32 v[18:19], 0
	v_mov_b64_e32 v[20:21], 0
	v_mov_b64_e32 v[22:23], 0
	v_mov_b64_e32 v[32:33], 0
	v_mov_b64_e32 v[34:35], 0
	v_mov_b64_e32 v[36:37], 0
	v_mov_b64_e32 v[38:39], 0
	v_mov_b64_e32 v[48:49], 0
	v_mov_b64_e32 v[50:51], 0
	v_mov_b64_e32 v[52:53], 0
	v_mov_b64_e32 v[54:55], 0
	v_mov_b64_e32 v[64:65], 0
	v_mov_b64_e32 v[66:67], 0
	v_mov_b64_e32 v[68:69], 0
	v_mov_b64_e32 v[70:71], 0
	v_mov_b64_e32 v[72:73], 0
	v_mov_b64_e32 v[74:75], 0
	v_mov_b64_e32 v[76:77], 0
	v_mov_b64_e32 v[78:79], 0
	v_mov_b64_e32 v[88:89], 0
	v_mov_b64_e32 v[90:91], 0
	v_mov_b64_e32 v[92:93], 0
	v_mov_b64_e32 v[94:95], 0
	v_mov_b64_e32 v[104:105], 0
	v_mov_b64_e32 v[106:107], 0
	v_mov_b64_e32 v[108:109], 0
	v_mov_b64_e32 v[110:111], 0
	v_mov_b64_e32 v[120:121], 0
	v_mov_b64_e32 v[122:123], 0
	v_mov_b64_e32 v[124:125], 0
	v_mov_b64_e32 v[126:127], 0
	v_mov_b64_e32 v[80:81], 0
	v_mov_b64_e32 v[82:83], 0
	v_mov_b64_e32 v[84:85], 0
	v_mov_b64_e32 v[86:87], 0
	v_mov_b64_e32 v[96:97], 0
	v_mov_b64_e32 v[98:99], 0
	v_mov_b64_e32 v[100:101], 0
	v_mov_b64_e32 v[102:103], 0
	v_mov_b64_e32 v[112:113], 0
	v_mov_b64_e32 v[114:115], 0
	v_mov_b64_e32 v[116:117], 0
	v_mov_b64_e32 v[118:119], 0
	v_mov_b64_e32 v[128:129], 0
	v_mov_b64_e32 v[130:131], 0
	v_mov_b64_e32 v[132:133], 0
	v_mov_b64_e32 v[134:135], 0
	s_mov_b64 s[50:51], 0x20080
	s_mov_b64 s[52:53], 0x10000
	s_mov_b64 s[54:55], 0x30000
	s_mov_b64 s[58:59], 0x10080
	s_mov_b64 s[62:63], 0x30080
	s_cmp_eq_u32 s101, 2
	s_cselect_b32 s101, 0, s101
	v_add_u32_e32 v255, 0x10000, v145
.LBB0_450:
	s_add_u32 s4, s6, 0xfffe0080
	s_addc_u32 s5, s7, -1
	s_add_i32 s41, 0, 0x10000
	ds_read_b128 v[140:143], v255 offset:0
	ds_read_b128 v[148:151], v255 offset:1024
	ds_read_b128 v[152:155], v255 offset:2048
	ds_read_b128 v[156:159], v255 offset:3072
	s_cmp_eq_u32 s21, 4
	s_cselect_b32 s23, s11, s5
	s_cselect_b32 s22, s10, s4
	s_cselect_b32 s43, s17, s20
	s_cselect_b32 s42, s16, s19
	s_add_i32 m0, s27, 0xc000
	ds_read_b128 v[160:163], v146
	ds_read_b128 v[164:167], v146 offset:1024
	ds_read_b128 v[172:175], v146 offset:2048
	ds_read_b128 v[176:179], v146 offset:3072
	ds_read_b128 v[180:183], v146 offset:4096
	ds_read_b128 v[196:199], v146 offset:5120
	ds_read_b128 v[200:203], v146 offset:6144
	ds_read_b128 v[204:207], v146 offset:7168
	global_load_lds_dwordx4 v138, s[6:7]
	s_add_i32 m0, s27, 0xe000
	s_nop 0
	s_add_u32 vcc_lo, s6, s52
	s_addc_u32 vcc_hi, s7, s53
	global_load_lds_dwordx4 v138, vcc
	s_waitcnt lgkmcnt(8)
	s_cmp_eq_u32 s101, 1
	s_cbranch_scc1 .Ldb_SSM1_sk
	s_barrier
.Ldb_SSM1_sk:
	s_mov_b32 s101, 0
	s_waitcnt lgkmcnt(0)
	v_mfma_f32_16x16x32_bf16 v[132:135], v[140:143], v[160:163], v[132:135]
	v_mfma_f32_16x16x32_bf16 v[128:131], v[152:155], v[160:163], v[128:131]
	v_mfma_f32_16x16x32_bf16 v[116:119], v[140:143], v[172:175], v[116:119]
	v_mfma_f32_16x16x32_bf16 v[112:115], v[152:155], v[172:175], v[112:115]
	v_mfma_f32_16x16x32_bf16 v[100:103], v[140:143], v[180:183], v[100:103]
	v_mfma_f32_16x16x32_bf16 v[96:99], v[152:155], v[180:183], v[96:99]
	v_mfma_f32_16x16x32_bf16 v[84:87], v[140:143], v[200:203], v[84:87]
	v_mfma_f32_16x16x32_bf16 v[80:83], v[152:155], v[200:203], v[80:83]
	v_mfma_f32_16x16x32_bf16 v[132:135], v[148:151], v[164:167], v[132:135]
	v_mfma_f32_16x16x32_bf16 v[128:131], v[156:159], v[164:167], v[128:131]
	v_mfma_f32_16x16x32_bf16 v[116:119], v[148:151], v[176:179], v[116:119]
	v_mfma_f32_16x16x32_bf16 v[112:115], v[156:159], v[176:179], v[112:115]
	v_mfma_f32_16x16x32_bf16 v[100:103], v[148:151], v[196:199], v[100:103]
	v_mfma_f32_16x16x32_bf16 v[96:99], v[156:159], v[196:199], v[96:99]
	v_mfma_f32_16x16x32_bf16 v[84:87], v[148:151], v[204:207], v[84:87]
	v_mfma_f32_16x16x32_bf16 v[80:83], v[156:159], v[204:207], v[80:83]
	s_barrier
	s_add_i32 s4, 0, 0x14000
	s_add_i32 s5, s41, s26
	s_mov_b32 m0, s5
	ds_read_b128 v[208:211], v255 offset:16384
	ds_read_b128 v[212:215], v255 offset:17408
	ds_read_b128 v[216:219], v255 offset:18432
	ds_read_b128 v[220:223], v255 offset:19456
	global_load_lds_dwordx4 v136, s[42:43]
	s_add_i32 m0, s5, 0x2000
	s_nop 0
	s_add_u32 vcc_lo, s42, s52
	s_addc_u32 vcc_hi, s43, s53
	global_load_lds_dwordx4 v136, vcc
	s_barrier
	s_waitcnt lgkmcnt(0)
	v_mfma_f32_16x16x32_bf16 v[124:127], v[208:211], v[160:163], v[124:127]
	v_mfma_f32_16x16x32_bf16 v[120:123], v[216:219], v[160:163], v[120:123]
	v_mfma_f32_16x16x32_bf16 v[108:111], v[208:211], v[172:175], v[108:111]
	v_mfma_f32_16x16x32_bf16 v[104:107], v[216:219], v[172:175], v[104:107]
	v_mfma_f32_16x16x32_bf16 v[92:95], v[208:211], v[180:183], v[92:95]
	v_mfma_f32_16x16x32_bf16 v[88:91], v[216:219], v[180:183], v[88:91]
	v_mfma_f32_16x16x32_bf16 v[76:79], v[208:211], v[200:203], v[76:79]
	v_mfma_f32_16x16x32_bf16 v[72:75], v[216:219], v[200:203], v[72:75]
	v_mfma_f32_16x16x32_bf16 v[124:127], v[212:215], v[164:167], v[124:127]
	v_mfma_f32_16x16x32_bf16 v[120:123], v[220:223], v[164:167], v[120:123]
	v_mfma_f32_16x16x32_bf16 v[108:111], v[212:215], v[176:179], v[108:111]
	v_mfma_f32_16x16x32_bf16 v[104:107], v[220:223], v[176:179], v[104:107]
	v_mfma_f32_16x16x32_bf16 v[92:95], v[212:215], v[196:199], v[92:95]
	v_mfma_f32_16x16x32_bf16 v[88:91], v[220:223], v[196:199], v[88:91]
	v_mfma_f32_16x16x32_bf16 v[76:79], v[212:215], v[204:207], v[76:79]
	v_mfma_f32_16x16x32_bf16 v[72:75], v[220:223], v[204:207], v[72:75]
	s_barrier
; #define G_STAGE(bufoff, gbase, o0, h64) do { \
;         __builtin_amdgcn_global_load_lds((const unsigned*)((const char*)(gbase) + (o0)), (LAS unsigned*)(lds + (bufoff) + ldsw), 16, 0, 0); \
;         __builtin_amdgcn_global_load_lds((const unsigned*)((const char*)(gbase) + (h64) + (o0)), (LAS unsigned*)(lds + (bufoff) + ldsw + 8192), 16, 0, 0); } while (0)
; #define G_LDA(dst, b, h) do { _Pragma("unroll") for (int m = 0; m < 4; ++m) _Pragma("unroll") for (int k = 0; k < 2; ++k) dst[m][k] = *(const LAS bf16x8*)(lds + G_SA(b, h) + aoff + m * 2048 + k * 1024); } while (0)
; #define G_LDB(dst, b, h) do { _Pragma("unroll") for (int n = 0; n < 2; ++n) _Pragma("unroll") for (int k = 0; k < 2; ++k) dst[n][k] = *(const LAS bf16x8*)(lds + G_SB(b, h) + boff + n * 2048 + k * 1024); } while (0)
; #define G_WAIT_V(n) asm volatile("s_waitcnt vmcnt(" #n ")" ::: "memory")
; #define G_WAIT_L(n) asm volatile("s_waitcnt lgkmcnt(" #n ")" ::: "memory")
; #define G_BAR __builtin_amdgcn_s_barrier()
; #define G_SCHED __builtin_amdgcn_sched_barrier(0)
;     ...
;             G_LDA(At, 0, 1); G_STAGE(G_SA(0, 0), a2, cA0, qA);
;             G_BAR; G_WAIT_L(0); G_MMA(1, 0, At, B0); G_BAR; G_SCHED;
;             G_STAGE(G_SB(0, 1), b2 + chB, cB0, qB);
;             G_WAIT_V(6); G_BAR; G_MMA(1, 1, At, B1); G_BAR;
;             G_LDB(B0, 1, 0); G_SCHED; G_LDA(At, 1, 0); G_STAGE(G_SA(0, 1), a2 + chA, cA0, qA);
;             G_WAIT_L(8); G_BAR; G_WAIT_L(0); G_MMA(0, 0, At, B0); G_BAR; G_SCHED;
	s_mov_b32 m0, s27
	ds_read_b128 v[160:163], v146 offset:16384
	ds_read_b128 v[164:167], v146 offset:17408
	ds_read_b128 v[172:175], v146 offset:18432
	ds_read_b128 v[176:179], v146 offset:19456
	ds_read_b128 v[180:183], v146 offset:20480
	ds_read_b128 v[196:199], v146 offset:21504
	ds_read_b128 v[200:203], v146 offset:22528
	ds_read_b128 v[204:207], v146 offset:23552
	global_load_lds_dwordx4 v2, s[22:23]
	s_mov_b32 m0, s28
	s_nop 0
	s_add_u32 vcc_lo, s22, s52
	s_addc_u32 vcc_hi, s23, s53
	global_load_lds_dwordx4 v2, vcc
	s_barrier
	s_waitcnt lgkmcnt(0)
	v_mfma_f32_16x16x32_bf16 v[68:71], v[140:143], v[160:163], v[68:71]
	v_mfma_f32_16x16x32_bf16 v[64:67], v[152:155], v[160:163], v[64:67]
	v_mfma_f32_16x16x32_bf16 v[52:55], v[140:143], v[172:175], v[52:55]
	v_mfma_f32_16x16x32_bf16 v[48:51], v[152:155], v[172:175], v[48:51]
	v_mfma_f32_16x16x32_bf16 v[36:39], v[140:143], v[180:183], v[36:39]
	v_mfma_f32_16x16x32_bf16 v[32:35], v[152:155], v[180:183], v[32:35]
	v_mfma_f32_16x16x32_bf16 v[20:23], v[140:143], v[200:203], v[20:23]
	v_mfma_f32_16x16x32_bf16 v[16:19], v[152:155], v[200:203], v[16:19]
	v_mfma_f32_16x16x32_bf16 v[68:71], v[148:151], v[164:167], v[68:71]
	v_mfma_f32_16x16x32_bf16 v[64:67], v[156:159], v[164:167], v[64:67]
	v_mfma_f32_16x16x32_bf16 v[52:55], v[148:151], v[176:179], v[52:55]
	v_mfma_f32_16x16x32_bf16 v[48:51], v[156:159], v[176:179], v[48:51]
	v_mfma_f32_16x16x32_bf16 v[36:39], v[148:151], v[196:199], v[36:39]
	v_mfma_f32_16x16x32_bf16 v[32:35], v[156:159], v[196:199], v[32:35]
	v_mfma_f32_16x16x32_bf16 v[20:23], v[148:151], v[204:207], v[20:23]
	v_mfma_f32_16x16x32_bf16 v[16:19], v[156:159], v[204:207], v[16:19]
	s_barrier
	s_add_i32 s4, s4, s26
	s_mov_b32 m0, s4
	s_nop 0
	s_add_u32 vcc_lo, s42, s0
	s_addc_u32 vcc_hi, s43, s1
	global_load_lds_dwordx4 v136, vcc
	s_add_i32 m0, s4, 0x2000
	s_nop 0
	s_add_u32 vcc_lo, s42, s54
	s_addc_u32 vcc_hi, s43, s55
	global_load_lds_dwordx4 v136, vcc
	s_waitcnt vmcnt(6)
	s_barrier
	v_mfma_f32_16x16x32_bf16 v[60:63], v[208:211], v[160:163], v[60:63]
	v_mfma_f32_16x16x32_bf16 v[56:59], v[216:219], v[160:163], v[56:59]
	v_mfma_f32_16x16x32_bf16 v[44:47], v[208:211], v[172:175], v[44:47]
	v_mfma_f32_16x16x32_bf16 v[40:43], v[216:219], v[172:175], v[40:43]
	v_mfma_f32_16x16x32_bf16 v[28:31], v[208:211], v[180:183], v[28:31]
	v_mfma_f32_16x16x32_bf16 v[24:27], v[216:219], v[180:183], v[24:27]
	v_mfma_f32_16x16x32_bf16 v[12:15], v[208:211], v[200:203], v[12:15]
	v_mfma_f32_16x16x32_bf16 v[8:11], v[216:219], v[200:203], v[8:11]
	v_mfma_f32_16x16x32_bf16 v[60:63], v[212:215], v[164:167], v[60:63]
	v_mfma_f32_16x16x32_bf16 v[56:59], v[220:223], v[164:167], v[56:59]
	v_mfma_f32_16x16x32_bf16 v[44:47], v[212:215], v[176:179], v[44:47]
	v_mfma_f32_16x16x32_bf16 v[40:43], v[220:223], v[176:179], v[40:43]
	v_mfma_f32_16x16x32_bf16 v[28:31], v[212:215], v[196:199], v[28:31]
	v_mfma_f32_16x16x32_bf16 v[24:27], v[220:223], v[196:199], v[24:27]
	v_mfma_f32_16x16x32_bf16 v[12:15], v[212:215], v[204:207], v[12:15]
	v_mfma_f32_16x16x32_bf16 v[8:11], v[220:223], v[204:207], v[8:11]
	s_barrier
	s_add_i32 s4, 0, 0x18000
	ds_read_b128 v[140:143], v255 offset:32768
	ds_read_b128 v[148:151], v255 offset:33792
	ds_read_b128 v[152:155], v255 offset:34816
	ds_read_b128 v[156:159], v255 offset:35840
	s_mov_b32 m0, s29
	ds_read_b128 v[160:163], v146 offset:32768
	ds_read_b128 v[164:167], v146 offset:33792
	ds_read_b128 v[172:175], v146 offset:34816
	ds_read_b128 v[176:179], v146 offset:35840
	ds_read_b128 v[180:183], v146 offset:36864
	ds_read_b128 v[196:199], v146 offset:37888
	ds_read_b128 v[200:203], v146 offset:38912
	ds_read_b128 v[204:207], v146 offset:39936
	s_add_u32 vcc_lo, s22, s0
	s_addc_u32 vcc_hi, s23, s1
	global_load_lds_dwordx4 v2, vcc
	s_mov_b32 m0, s30
	s_nop 0
	s_add_u32 vcc_lo, s22, s54
	s_addc_u32 vcc_hi, s23, s55
	global_load_lds_dwordx4 v2, vcc
	s_waitcnt lgkmcnt(8)
	s_barrier
	s_waitcnt lgkmcnt(0)
	v_mfma_f32_16x16x32_bf16 v[132:135], v[140:143], v[160:163], v[132:135]
	v_mfma_f32_16x16x32_bf16 v[128:131], v[152:155], v[160:163], v[128:131]
	v_mfma_f32_16x16x32_bf16 v[116:119], v[140:143], v[172:175], v[116:119]
	v_mfma_f32_16x16x32_bf16 v[112:115], v[152:155], v[172:175], v[112:115]
	v_mfma_f32_16x16x32_bf16 v[100:103], v[140:143], v[180:183], v[100:103]
	v_mfma_f32_16x16x32_bf16 v[96:99], v[152:155], v[180:183], v[96:99]
	v_mfma_f32_16x16x32_bf16 v[84:87], v[140:143], v[200:203], v[84:87]
	v_mfma_f32_16x16x32_bf16 v[80:83], v[152:155], v[200:203], v[80:83]
	v_mfma_f32_16x16x32_bf16 v[132:135], v[148:151], v[164:167], v[132:135]
	v_mfma_f32_16x16x32_bf16 v[128:131], v[156:159], v[164:167], v[128:131]
	v_mfma_f32_16x16x32_bf16 v[116:119], v[148:151], v[176:179], v[116:119]
	v_mfma_f32_16x16x32_bf16 v[112:115], v[156:159], v[176:179], v[112:115]
	v_mfma_f32_16x16x32_bf16 v[100:103], v[148:151], v[196:199], v[100:103]
	v_mfma_f32_16x16x32_bf16 v[96:99], v[156:159], v[196:199], v[96:99]
	v_mfma_f32_16x16x32_bf16 v[84:87], v[148:151], v[204:207], v[84:87]
	v_mfma_f32_16x16x32_bf16 v[80:83], v[156:159], v[204:207], v[80:83]
	s_barrier
; #define G_STAGE(bufoff, gbase, o0, h64) do { \
;         __builtin_amdgcn_global_load_lds((const unsigned*)((const char*)(gbase) + (o0)), (LAS unsigned*)(lds + (bufoff) + ldsw), 16, 0, 0); \
;         __builtin_amdgcn_global_load_lds((const unsigned*)((const char*)(gbase) + (h64) + (o0)), (LAS unsigned*)(lds + (bufoff) + ldsw + 8192), 16, 0, 0); } while (0)
; #define G_LDA(dst, b, h) do { _Pragma("unroll") for (int m = 0; m < 4; ++m) _Pragma("unroll") for (int k = 0; k < 2; ++k) dst[m][k] = *(const LAS bf16x8*)(lds + G_SA(b, h) + aoff + m * 2048 + k * 1024); } while (0)
; #define G_LDB(dst, b, h) do { _Pragma("unroll") for (int n = 0; n < 2; ++n) _Pragma("unroll") for (int k = 0; k < 2; ++k) dst[n][k] = *(const LAS bf16x8*)(lds + G_SB(b, h) + boff + n * 2048 + k * 1024); } while (0)
; #define G_WAIT_V(n) asm volatile("s_waitcnt vmcnt(" #n ")" ::: "memory")
; #define G_WAIT_L(n) asm volatile("s_waitcnt lgkmcnt(" #n ")" ::: "memory")
; #define G_BAR __builtin_amdgcn_s_barrier()
; #define G_SCHED __builtin_amdgcn_sched_barrier(0)
;     ...
;             G_LDB(B1, 1, 1); G_STAGE(G_SB(1, 0), b3, cB0, qB);
;             G_BAR; G_WAIT_L(0); G_MMA(0, 1, At, B1); G_BAR;
;             G_LDA(At, 1, 1); G_STAGE(G_SA(1, 0), a3, cA0, qA);
;             G_BAR; G_WAIT_L(0); G_MMA(1, 0, At, B0); G_BAR; G_SCHED;
;             G_STAGE(G_SB(1, 1), b3 + chB, cB0, qB);
;             G_WAIT_V(6); G_BAR; G_MMA(1, 1, At, B1); G_BAR;
	s_add_i32 s5, 0, 0x1c000
	s_add_i32 s4, s4, s26
	s_mov_b32 m0, s4
	ds_read_b128 v[208:211], v255 offset:49152
	ds_read_b128 v[212:215], v255 offset:50176
	ds_read_b128 v[216:219], v255 offset:51200
	ds_read_b128 v[220:223], v255 offset:52224
	s_add_u32 vcc_lo, s42, s46
	s_addc_u32 vcc_hi, s43, s47
	global_load_lds_dwordx4 v136, vcc
	s_add_i32 m0, s4, 0x2000
	s_nop 0
	s_add_u32 vcc_lo, s42, s58
	s_addc_u32 vcc_hi, s43, s59
	global_load_lds_dwordx4 v136, vcc
	s_barrier
	s_waitcnt lgkmcnt(0)
	v_mfma_f32_16x16x32_bf16 v[124:127], v[208:211], v[160:163], v[124:127]
	v_mfma_f32_16x16x32_bf16 v[120:123], v[216:219], v[160:163], v[120:123]
	v_mfma_f32_16x16x32_bf16 v[108:111], v[208:211], v[172:175], v[108:111]
	v_mfma_f32_16x16x32_bf16 v[104:107], v[216:219], v[172:175], v[104:107]
	v_mfma_f32_16x16x32_bf16 v[92:95], v[208:211], v[180:183], v[92:95]
	v_mfma_f32_16x16x32_bf16 v[88:91], v[216:219], v[180:183], v[88:91]
	v_mfma_f32_16x16x32_bf16 v[76:79], v[208:211], v[200:203], v[76:79]
	v_mfma_f32_16x16x32_bf16 v[72:75], v[216:219], v[200:203], v[72:75]
	v_mfma_f32_16x16x32_bf16 v[124:127], v[212:215], v[164:167], v[124:127]
	v_mfma_f32_16x16x32_bf16 v[120:123], v[220:223], v[164:167], v[120:123]
	v_mfma_f32_16x16x32_bf16 v[108:111], v[212:215], v[176:179], v[108:111]
	v_mfma_f32_16x16x32_bf16 v[104:107], v[220:223], v[176:179], v[104:107]
	v_mfma_f32_16x16x32_bf16 v[92:95], v[212:215], v[196:199], v[92:95]
	v_mfma_f32_16x16x32_bf16 v[88:91], v[220:223], v[196:199], v[88:91]
	v_mfma_f32_16x16x32_bf16 v[76:79], v[212:215], v[204:207], v[76:79]
	v_mfma_f32_16x16x32_bf16 v[72:75], v[220:223], v[204:207], v[72:75]
	s_barrier
	s_mov_b32 m0, s31
	ds_read_b128 v[160:163], v146 offset:49152
	ds_read_b128 v[164:167], v146 offset:50176
	ds_read_b128 v[172:175], v146 offset:51200
	ds_read_b128 v[176:179], v146 offset:52224
	ds_read_b128 v[180:183], v146 offset:53248
	ds_read_b128 v[196:199], v146 offset:54272
	ds_read_b128 v[200:203], v146 offset:55296
	ds_read_b128 v[204:207], v146 offset:56320
	s_add_u32 vcc_lo, s22, s46
	s_addc_u32 vcc_hi, s23, s47
	global_load_lds_dwordx4 v2, vcc
	s_mov_b32 m0, s33
	s_nop 0
	s_add_u32 vcc_lo, s22, s58
	s_addc_u32 vcc_hi, s23, s59
	global_load_lds_dwordx4 v2, vcc
	s_barrier
	s_waitcnt lgkmcnt(0)
	v_mfma_f32_16x16x32_bf16 v[68:71], v[140:143], v[160:163], v[68:71]
	v_mfma_f32_16x16x32_bf16 v[64:67], v[152:155], v[160:163], v[64:67]
	v_mfma_f32_16x16x32_bf16 v[52:55], v[140:143], v[172:175], v[52:55]
	v_mfma_f32_16x16x32_bf16 v[48:51], v[152:155], v[172:175], v[48:51]
	v_mfma_f32_16x16x32_bf16 v[36:39], v[140:143], v[180:183], v[36:39]
	v_mfma_f32_16x16x32_bf16 v[32:35], v[152:155], v[180:183], v[32:35]
	v_mfma_f32_16x16x32_bf16 v[20:23], v[140:143], v[200:203], v[20:23]
	v_mfma_f32_16x16x32_bf16 v[16:19], v[152:155], v[200:203], v[16:19]
	v_mfma_f32_16x16x32_bf16 v[68:71], v[148:151], v[164:167], v[68:71]
	v_mfma_f32_16x16x32_bf16 v[64:67], v[156:159], v[164:167], v[64:67]
	v_mfma_f32_16x16x32_bf16 v[52:55], v[148:151], v[176:179], v[52:55]
	v_mfma_f32_16x16x32_bf16 v[48:51], v[156:159], v[176:179], v[48:51]
	v_mfma_f32_16x16x32_bf16 v[36:39], v[148:151], v[196:199], v[36:39]
	v_mfma_f32_16x16x32_bf16 v[32:35], v[156:159], v[196:199], v[32:35]
	v_mfma_f32_16x16x32_bf16 v[20:23], v[148:151], v[204:207], v[20:23]
	v_mfma_f32_16x16x32_bf16 v[16:19], v[156:159], v[204:207], v[16:19]
	s_barrier
	s_add_i32 s4, s5, s26
	s_mov_b32 m0, s4
	s_nop 0
	s_add_u32 vcc_lo, s42, s50
	s_addc_u32 vcc_hi, s43, s51
	global_load_lds_dwordx4 v136, vcc
	s_add_i32 m0, s4, 0x2000
	s_nop 0
	s_add_u32 vcc_lo, s42, s62
	s_addc_u32 vcc_hi, s43, s63
	global_load_lds_dwordx4 v136, vcc
	s_add_i32 s21, s21, 2
	s_add_u32 s6, s6, 0x100
	s_addc_u32 s7, s7, 0
	s_add_u32 s19, s19, 0x100
	s_addc_u32 s20, s20, 0
	s_cmp_gt_u32 s21, 5
	s_waitcnt vmcnt(6)
	s_barrier
	v_mfma_f32_16x16x32_bf16 v[60:63], v[208:211], v[160:163], v[60:63]
	v_mfma_f32_16x16x32_bf16 v[56:59], v[216:219], v[160:163], v[56:59]
	v_mfma_f32_16x16x32_bf16 v[44:47], v[208:211], v[172:175], v[44:47]
	v_mfma_f32_16x16x32_bf16 v[40:43], v[216:219], v[172:175], v[40:43]
	v_mfma_f32_16x16x32_bf16 v[28:31], v[208:211], v[180:183], v[28:31]
	v_mfma_f32_16x16x32_bf16 v[24:27], v[216:219], v[180:183], v[24:27]
	v_mfma_f32_16x16x32_bf16 v[12:15], v[208:211], v[200:203], v[12:15]
	v_mfma_f32_16x16x32_bf16 v[8:11], v[216:219], v[200:203], v[8:11]
	v_mfma_f32_16x16x32_bf16 v[60:63], v[212:215], v[164:167], v[60:63]
	v_mfma_f32_16x16x32_bf16 v[56:59], v[220:223], v[164:167], v[56:59]
	v_mfma_f32_16x16x32_bf16 v[44:47], v[212:215], v[176:179], v[44:47]
	v_mfma_f32_16x16x32_bf16 v[40:43], v[220:223], v[176:179], v[40:43]
	v_mfma_f32_16x16x32_bf16 v[28:31], v[212:215], v[196:199], v[28:31]
	v_mfma_f32_16x16x32_bf16 v[24:27], v[220:223], v[196:199], v[24:27]
	v_mfma_f32_16x16x32_bf16 v[12:15], v[212:215], v[204:207], v[12:15]
	v_mfma_f32_16x16x32_bf16 v[8:11], v[220:223], v[204:207], v[8:11]
	s_cbranch_scc0 .Ldb_SSM1_cont
	v_readfirstlane_b32 s101, v186
	s_cmpk_gt_u32 s101, 0xff
	s_cbranch_scc1 .Ldb_SSM1_young
	s_barrier
	s_mov_b32 s101, 1
	s_branch .Ldb_SSM1_exit

; #define G_STAGE(bufoff, gbase, o0, h64) do { \
;         __builtin_amdgcn_global_load_lds((const unsigned*)((const char*)(gbase) + (o0)), (LAS unsigned*)(lds + (bufoff) + ldsw), 16, 0, 0); \
;         __builtin_amdgcn_global_load_lds((const unsigned*)((const char*)(gbase) + (h64) + (o0)), (LAS unsigned*)(lds + (bufoff) + ldsw + 8192), 16, 0, 0); } while (0)
; #define G_LDA(dst, b, h) do { _Pragma("unroll") for (int m = 0; m < 4; ++m) _Pragma("unroll") for (int k = 0; k < 2; ++k) dst[m][k] = *(const LAS bf16x8*)(lds + G_SA(b, h) + aoff + m * 2048 + k * 1024); } while (0)
; #define G_LDB(dst, b, h) do { _Pragma("unroll") for (int n = 0; n < 2; ++n) _Pragma("unroll") for (int k = 0; k < 2; ++k) dst[n][k] = *(const LAS bf16x8*)(lds + G_SB(b, h) + boff + n * 2048 + k * 1024); } while (0)
; #define G_WAIT_L(n) asm volatile("s_waitcnt lgkmcnt(" #n ")" ::: "memory")
; #define G_BAR __builtin_amdgcn_s_barrier()
; #define G_SCHED __builtin_amdgcn_sched_barrier(0)
;     ...
;         for (int t = 0; t < nt; t += 2) {
;             const bool last = (t == nt - 2);
;             const char* a1 = cA + (size_t)(t + 1) * ckA;
;             const char* a2 = last ? nA : cA + (size_t)(t + 2) * ckA; const char* b2 = last ? nB : cB + (size_t)(t + 2) * kB;
;             const char* a3 = a2 + ckA; const char* b3 = b2 + kB;
;             G_LDB(B0, 0, 0); G_SCHED; G_LDA(At, 0, 0); G_STAGE(G_SA(1, 1), a1 + chA, cA0, qA);
;             G_WAIT_L(8); G_BAR; G_WAIT_L(0); G_MMA(0, 0, At, B0); G_BAR; G_SCHED;
;             G_LDB(B1, 0, 1); G_STAGE(G_SB(0, 0), b2, cB0, qB);
;     ...
;         for (int a = 0; a < 2; ++a)
; #pragma unroll
;             for (int b = 0; b < 2; ++b)
; #pragma unroll
;                 for (int m = 0; m < 4; ++m)
; #pragma unroll
;                     for (int n = 0; n < 2; ++n) acc[a][b][m][n] = (f32x4){0.f, 0.f, 0.f, 0.f};
.LBB0_741:
	v_mov_b64_e32 v[8:9], 0
	s_mov_b64 s[30:31], 0
	s_mov_b64 s[24:25], -1
	s_mov_b64 s[26:27], 0
	v_mov_b64_e32 v[10:11], 0
	v_mov_b64_e32 v[12:13], 0
	v_mov_b64_e32 v[14:15], 0
	v_mov_b64_e32 v[24:25], 0
	v_mov_b64_e32 v[26:27], 0
	v_mov_b64_e32 v[28:29], 0
	v_mov_b64_e32 v[30:31], 0
	v_mov_b64_e32 v[40:41], 0
	v_mov_b64_e32 v[42:43], 0
	v_mov_b64_e32 v[44:45], 0
	v_mov_b64_e32 v[46:47], 0
	v_mov_b64_e32 v[64:65], 0
	v_mov_b64_e32 v[66:67], 0
	v_mov_b64_e32 v[68:69], 0
	v_mov_b64_e32 v[70:71], 0
	v_mov_b64_e32 v[16:17], 0
	v_mov_b64_e32 v[18:19], 0
	v_mov_b64_e32 v[20:21], 0
	v_mov_b64_e32 v[22:23], 0
	v_mov_b64_e32 v[32:33], 0
	v_mov_b64_e32 v[34:35], 0
	v_mov_b64_e32 v[36:37], 0
	v_mov_b64_e32 v[38:39], 0
	v_mov_b64_e32 v[48:49], 0
	v_mov_b64_e32 v[50:51], 0
	v_mov_b64_e32 v[52:53], 0
	v_mov_b64_e32 v[54:55], 0
	v_mov_b64_e32 v[72:73], 0
	v_mov_b64_e32 v[74:75], 0
	v_mov_b64_e32 v[76:77], 0
	v_mov_b64_e32 v[78:79], 0
	v_mov_b64_e32 v[80:81], 0
	v_mov_b64_e32 v[82:83], 0
	v_mov_b64_e32 v[84:85], 0
	v_mov_b64_e32 v[86:87], 0
	v_mov_b64_e32 v[96:97], 0
	v_mov_b64_e32 v[98:99], 0
	v_mov_b64_e32 v[100:101], 0
	v_mov_b64_e32 v[102:103], 0
	v_mov_b64_e32 v[112:113], 0
	v_mov_b64_e32 v[114:115], 0
	v_mov_b64_e32 v[116:117], 0
	v_mov_b64_e32 v[118:119], 0
	v_mov_b64_e32 v[128:129], 0
	v_mov_b64_e32 v[130:131], 0
	v_mov_b64_e32 v[132:133], 0
	v_mov_b64_e32 v[134:135], 0
	v_mov_b64_e32 v[88:89], 0
	v_mov_b64_e32 v[90:91], 0
	v_mov_b64_e32 v[92:93], 0
	v_mov_b64_e32 v[94:95], 0
	v_mov_b64_e32 v[104:105], 0
	v_mov_b64_e32 v[106:107], 0
	v_mov_b64_e32 v[108:109], 0
	v_mov_b64_e32 v[110:111], 0
	v_mov_b64_e32 v[120:121], 0
	v_mov_b64_e32 v[122:123], 0
	v_mov_b64_e32 v[124:125], 0
	v_mov_b64_e32 v[126:127], 0
	v_mov_b64_e32 v[136:137], 0
	v_mov_b64_e32 v[138:139], 0
	v_mov_b64_e32 v[140:141], 0
	v_mov_b64_e32 v[142:143], 0
	s_mov_b64 s[82:83], 0x10000
	s_mov_b64 s[84:85], 0x10080
	s_mov_b64 s[86:87], 0x200000
	s_mov_b64 s[88:89], 0x100000
	s_mov_b64 s[92:93], 0x8000
	s_mov_b64 s[94:95], 0x18000
	s_mov_b64 s[96:97], 0x300000
	s_mov_b64 s[70:71], 0x8080
	s_mov_b64 s[68:69], 0x100080
	s_mov_b64 s[28:29], 0x18080
	s_cmp_eq_u32 s101, 2
	s_cselect_b32 s101, 0, s101
	v_add_u32_e32 v255, 0x10000, v183
.LBB0_742:
	s_add_u32 s36, s2, s30
	s_addc_u32 s37, s3, s31
	s_add_u32 s19, s36, 0x100
	s_addc_u32 s35, s37, 0
	s_and_b64 s[4:5], s[26:27], exec
	s_cselect_b32 s34, s12, s19
	s_cselect_b32 s35, s13, s35
	s_add_u32 s4, s20, s30
	s_addc_u32 s5, s21, s31
	s_add_u32 s19, s4, 0x100
	s_addc_u32 s30, s5, 0
	s_add_i32 s44, 0, 0x10000
	ds_read_b128 v[56:59], v255 offset:0
	ds_read_b128 v[60:63], v255 offset:1024
	ds_read_b128 v[144:147], v255 offset:2048
	ds_read_b128 v[148:151], v255 offset:3072
	s_and_b64 s[4:5], s[26:27], exec
	s_cselect_b32 s26, s16, s19
	s_cselect_b32 s27, s17, s30
	s_add_i32 s48, 0, 0x14000
	s_add_i32 s31, 0, 0x18000
	s_add_i32 s19, 0, 0x1c000
	s_add_i32 s49, s44, s38
	s_add_i32 s63, s48, s38
	s_add_i32 s30, s31, s38
	s_add_i32 s65, s19, s38
	s_add_i32 m0, s43, 0xc000
	s_add_i32 s45, s43, 0xe000
	s_add_i32 s66, s49, 0x2000
	s_add_i32 s62, s63, 0x2000
	s_add_i32 s67, s30, 0x2000
	s_add_i32 s64, s65, 0x2000
	s_mov_b64 s[4:5], 0x200080
	s_add_u32 vcc_lo, s36, s4
	s_addc_u32 vcc_hi, s37, s5
	s_mov_b64 s[4:5], 0x300080
	ds_read_b128 v[152:155], v184
	ds_read_b128 v[156:159], v184 offset:1024
	ds_read_b128 v[162:165], v184 offset:2048
	ds_read_b128 v[172:175], v184 offset:3072
	ds_read_b128 v[176:179], v184 offset:4096
	ds_read_b128 v[196:199], v184 offset:5120
	ds_read_b128 v[200:203], v184 offset:6144
	ds_read_b128 v[204:207], v184 offset:7168
	global_load_lds_dwordx4 v160, vcc
	s_mov_b32 m0, s45
	s_nop 0
	s_add_u32 vcc_lo, s36, s4
	s_addc_u32 vcc_hi, s37, s5
	global_load_lds_dwordx4 v160, vcc
	s_waitcnt lgkmcnt(8)
	s_cmp_eq_u32 s101, 1
	s_cbranch_scc1 .Ldb_SSM2_sk
	s_barrier
.Ldb_SSM2_sk:
	s_mov_b32 s101, 0
	s_waitcnt lgkmcnt(0)
	v_mfma_f32_16x16x32_bf16 v[140:143], v[56:59], v[152:155], v[140:143]
	v_mfma_f32_16x16x32_bf16 v[136:139], v[144:147], v[152:155], v[136:139]
	v_mfma_f32_16x16x32_bf16 v[124:127], v[56:59], v[162:165], v[124:127]
	v_mfma_f32_16x16x32_bf16 v[120:123], v[144:147], v[162:165], v[120:123]
	v_mfma_f32_16x16x32_bf16 v[108:111], v[56:59], v[176:179], v[108:111]
	v_mfma_f32_16x16x32_bf16 v[104:107], v[144:147], v[176:179], v[104:107]
	v_mfma_f32_16x16x32_bf16 v[92:95], v[56:59], v[200:203], v[92:95]
	v_mfma_f32_16x16x32_bf16 v[88:91], v[144:147], v[200:203], v[88:91]
	v_mfma_f32_16x16x32_bf16 v[140:143], v[60:63], v[156:159], v[140:143]
	v_mfma_f32_16x16x32_bf16 v[136:139], v[148:151], v[156:159], v[136:139]
	v_mfma_f32_16x16x32_bf16 v[124:127], v[60:63], v[172:175], v[124:127]
	v_mfma_f32_16x16x32_bf16 v[120:123], v[148:151], v[172:175], v[120:123]
	v_mfma_f32_16x16x32_bf16 v[108:111], v[60:63], v[196:199], v[108:111]
	v_mfma_f32_16x16x32_bf16 v[104:107], v[148:151], v[196:199], v[104:107]
	v_mfma_f32_16x16x32_bf16 v[92:95], v[60:63], v[204:207], v[92:95]
	v_mfma_f32_16x16x32_bf16 v[88:91], v[148:151], v[204:207], v[88:91]
	s_barrier
	s_mov_b32 m0, s49
	ds_read_b128 v[208:211], v255 offset:16384
	ds_read_b128 v[212:215], v255 offset:17408
	ds_read_b128 v[216:219], v255 offset:18432
	ds_read_b128 v[220:223], v255 offset:19456
	global_load_lds_dwordx4 v2, s[26:27]
	s_mov_b32 m0, s66
	s_nop 0
	s_add_u32 vcc_lo, s26, s92
	s_addc_u32 vcc_hi, s27, s93
	global_load_lds_dwordx4 v2, vcc
	s_barrier
; #define G_STAGE(bufoff, gbase, o0, h64) do { \
;         __builtin_amdgcn_global_load_lds((const unsigned*)((const char*)(gbase) + (o0)), (LAS unsigned*)(lds + (bufoff) + ldsw), 16, 0, 0); \
;         __builtin_amdgcn_global_load_lds((const unsigned*)((const char*)(gbase) + (h64) + (o0)), (LAS unsigned*)(lds + (bufoff) + ldsw + 8192), 16, 0, 0); } while (0)
; #define G_LDA(dst, b, h) do { _Pragma("unroll") for (int m = 0; m < 4; ++m) _Pragma("unroll") for (int k = 0; k < 2; ++k) dst[m][k] = *(const LAS bf16x8*)(lds + G_SA(b, h) + aoff + m * 2048 + k * 1024); } while (0)
; #define G_LDB(dst, b, h) do { _Pragma("unroll") for (int n = 0; n < 2; ++n) _Pragma("unroll") for (int k = 0; k < 2; ++k) dst[n][k] = *(const LAS bf16x8*)(lds + G_SB(b, h) + boff + n * 2048 + k * 1024); } while (0)
; #define G_WAIT_V(n) asm volatile("s_waitcnt vmcnt(" #n ")" ::: "memory")
; #define G_WAIT_L(n) asm volatile("s_waitcnt lgkmcnt(" #n ")" ::: "memory")
; #define G_BAR __builtin_amdgcn_s_barrier()
; #define G_SCHED __builtin_amdgcn_sched_barrier(0)
;     ...
;             G_BAR; G_WAIT_L(0); G_MMA(0, 1, At, B1); G_BAR;
;             G_LDA(At, 0, 1); G_STAGE(G_SA(0, 0), a2, cA0, qA);
;             G_BAR; G_WAIT_L(0); G_MMA(1, 0, At, B0); G_BAR; G_SCHED;
;             G_STAGE(G_SB(0, 1), b2 + chB, cB0, qB);
;             G_WAIT_V(6); G_BAR; G_MMA(1, 1, At, B1); G_BAR;
;             G_LDB(B0, 1, 0); G_SCHED; G_LDA(At, 1, 0); G_STAGE(G_SA(0, 1), a2 + chA, cA0, qA);
	s_waitcnt lgkmcnt(0)
	v_mfma_f32_16x16x32_bf16 v[132:135], v[208:211], v[152:155], v[132:135]
	v_mfma_f32_16x16x32_bf16 v[128:131], v[216:219], v[152:155], v[128:131]
	v_mfma_f32_16x16x32_bf16 v[116:119], v[208:211], v[162:165], v[116:119]
	v_mfma_f32_16x16x32_bf16 v[112:115], v[216:219], v[162:165], v[112:115]
	v_mfma_f32_16x16x32_bf16 v[100:103], v[208:211], v[176:179], v[100:103]
	v_mfma_f32_16x16x32_bf16 v[96:99], v[216:219], v[176:179], v[96:99]
	v_mfma_f32_16x16x32_bf16 v[84:87], v[208:211], v[200:203], v[84:87]
	v_mfma_f32_16x16x32_bf16 v[80:83], v[216:219], v[200:203], v[80:83]
	v_mfma_f32_16x16x32_bf16 v[132:135], v[212:215], v[156:159], v[132:135]
	v_mfma_f32_16x16x32_bf16 v[128:131], v[220:223], v[156:159], v[128:131]
	v_mfma_f32_16x16x32_bf16 v[116:119], v[212:215], v[172:175], v[116:119]
	v_mfma_f32_16x16x32_bf16 v[112:115], v[220:223], v[172:175], v[112:115]
	v_mfma_f32_16x16x32_bf16 v[100:103], v[212:215], v[196:199], v[100:103]
	v_mfma_f32_16x16x32_bf16 v[96:99], v[220:223], v[196:199], v[96:99]
	v_mfma_f32_16x16x32_bf16 v[84:87], v[212:215], v[204:207], v[84:87]
	v_mfma_f32_16x16x32_bf16 v[80:83], v[220:223], v[204:207], v[80:83]
	s_barrier
	s_mov_b32 m0, s43
	ds_read_b128 v[152:155], v184 offset:16384
	ds_read_b128 v[156:159], v184 offset:17408
	ds_read_b128 v[162:165], v184 offset:18432
	ds_read_b128 v[172:175], v184 offset:19456
	ds_read_b128 v[176:179], v184 offset:20480
	ds_read_b128 v[196:199], v184 offset:21504
	ds_read_b128 v[200:203], v184 offset:22528
	ds_read_b128 v[204:207], v184 offset:23552
	global_load_lds_dwordx4 v160, s[34:35]
	s_mov_b32 m0, s50
	s_nop 0
	s_add_u32 vcc_lo, s34, s88
	s_addc_u32 vcc_hi, s35, s89
	global_load_lds_dwordx4 v160, vcc
	s_barrier
	s_waitcnt lgkmcnt(0)
	v_mfma_f32_16x16x32_bf16 v[76:79], v[56:59], v[152:155], v[76:79]
	v_mfma_f32_16x16x32_bf16 v[72:75], v[144:147], v[152:155], v[72:75]
	v_mfma_f32_16x16x32_bf16 v[52:55], v[56:59], v[162:165], v[52:55]
	v_mfma_f32_16x16x32_bf16 v[48:51], v[144:147], v[162:165], v[48:51]
	v_mfma_f32_16x16x32_bf16 v[36:39], v[56:59], v[176:179], v[36:39]
	v_mfma_f32_16x16x32_bf16 v[32:35], v[144:147], v[176:179], v[32:35]
	v_mfma_f32_16x16x32_bf16 v[20:23], v[56:59], v[200:203], v[20:23]
	v_mfma_f32_16x16x32_bf16 v[16:19], v[144:147], v[200:203], v[16:19]
	v_mfma_f32_16x16x32_bf16 v[76:79], v[60:63], v[156:159], v[76:79]
	v_mfma_f32_16x16x32_bf16 v[72:75], v[148:151], v[156:159], v[72:75]
	v_mfma_f32_16x16x32_bf16 v[52:55], v[60:63], v[172:175], v[52:55]
	v_mfma_f32_16x16x32_bf16 v[48:51], v[148:151], v[172:175], v[48:51]
	v_mfma_f32_16x16x32_bf16 v[36:39], v[60:63], v[196:199], v[36:39]
	v_mfma_f32_16x16x32_bf16 v[32:35], v[148:151], v[196:199], v[32:35]
	v_mfma_f32_16x16x32_bf16 v[20:23], v[60:63], v[204:207], v[20:23]
	v_mfma_f32_16x16x32_bf16 v[16:19], v[148:151], v[204:207], v[16:19]
	s_barrier
	s_mov_b32 m0, s63
	s_add_u32 vcc_lo, s26, s82
	s_addc_u32 vcc_hi, s27, s83
	global_load_lds_dwordx4 v2, vcc
	s_mov_b32 m0, s62
	s_nop 0
	s_add_u32 vcc_lo, s26, s94
	s_addc_u32 vcc_hi, s27, s95
	global_load_lds_dwordx4 v2, vcc
	s_waitcnt vmcnt(6)
	s_barrier
	v_mfma_f32_16x16x32_bf16 v[44:47], v[208:211], v[162:165], v[44:47]
	v_mfma_f32_16x16x32_bf16 v[40:43], v[216:219], v[162:165], v[40:43]
	v_mfma_f32_16x16x32_bf16 v[28:31], v[208:211], v[176:179], v[28:31]
	v_mfma_f32_16x16x32_bf16 v[24:27], v[216:219], v[176:179], v[24:27]
	v_mfma_f32_16x16x32_bf16 v[12:15], v[208:211], v[200:203], v[12:15]
	v_mfma_f32_16x16x32_bf16 v[8:11], v[216:219], v[200:203], v[8:11]
	v_mfma_f32_16x16x32_bf16 v[56:59], v[208:211], v[152:155], v[68:71]
	v_mfma_f32_16x16x32_bf16 v[60:63], v[216:219], v[152:155], v[64:67]
	v_mfma_f32_16x16x32_bf16 v[44:47], v[212:215], v[172:175], v[44:47]
	v_mfma_f32_16x16x32_bf16 v[40:43], v[220:223], v[172:175], v[40:43]
	v_mfma_f32_16x16x32_bf16 v[28:31], v[212:215], v[196:199], v[28:31]
	v_mfma_f32_16x16x32_bf16 v[24:27], v[220:223], v[196:199], v[24:27]
	v_mfma_f32_16x16x32_bf16 v[12:15], v[212:215], v[204:207], v[12:15]
	v_mfma_f32_16x16x32_bf16 v[8:11], v[220:223], v[204:207], v[8:11]
	v_mfma_f32_16x16x32_bf16 v[56:59], v[212:215], v[156:159], v[56:59]
	v_mfma_f32_16x16x32_bf16 v[60:63], v[220:223], v[156:159], v[60:63]
	s_barrier
	ds_read_b128 v[64:67], v255 offset:32768
	ds_read_b128 v[68:71], v255 offset:33792
	ds_read_b128 v[144:147], v255 offset:34816
	ds_read_b128 v[148:151], v255 offset:35840
	s_mov_b32 m0, s51
	ds_read_b128 v[152:155], v184 offset:32768
	ds_read_b128 v[156:159], v184 offset:33792
	ds_read_b128 v[162:165], v184 offset:34816
	ds_read_b128 v[172:175], v184 offset:35840
	ds_read_b128 v[176:179], v184 offset:36864
	ds_read_b128 v[196:199], v184 offset:37888
	ds_read_b128 v[200:203], v184 offset:38912
	ds_read_b128 v[204:207], v184 offset:39936
	s_add_u32 vcc_lo, s34, s86
	s_addc_u32 vcc_hi, s35, s87
	global_load_lds_dwordx4 v160, vcc
	s_mov_b32 m0, s52
	s_nop 0
	s_add_u32 vcc_lo, s34, s96
	s_addc_u32 vcc_hi, s35, s97
	global_load_lds_dwordx4 v160, vcc
	s_waitcnt lgkmcnt(8)
	s_barrier
; #define G_STAGE(bufoff, gbase, o0, h64) do { \
;         __builtin_amdgcn_global_load_lds((const unsigned*)((const char*)(gbase) + (o0)), (LAS unsigned*)(lds + (bufoff) + ldsw), 16, 0, 0); \
;         __builtin_amdgcn_global_load_lds((const unsigned*)((const char*)(gbase) + (h64) + (o0)), (LAS unsigned*)(lds + (bufoff) + ldsw + 8192), 16, 0, 0); } while (0)
; #define G_LDA(dst, b, h) do { _Pragma("unroll") for (int m = 0; m < 4; ++m) _Pragma("unroll") for (int k = 0; k < 2; ++k) dst[m][k] = *(const LAS bf16x8*)(lds + G_SA(b, h) + aoff + m * 2048 + k * 1024); } while (0)
; #define G_LDB(dst, b, h) do { _Pragma("unroll") for (int n = 0; n < 2; ++n) _Pragma("unroll") for (int k = 0; k < 2; ++k) dst[n][k] = *(const LAS bf16x8*)(lds + G_SB(b, h) + boff + n * 2048 + k * 1024); } while (0)
; #define G_WAIT_V(n) asm volatile("s_waitcnt vmcnt(" #n ")" ::: "memory")
; #define G_WAIT_L(n) asm volatile("s_waitcnt lgkmcnt(" #n ")" ::: "memory")
; #define G_BAR __builtin_amdgcn_s_barrier()
; #define G_SCHED __builtin_amdgcn_sched_barrier(0)
;     ...
;             G_WAIT_L(8); G_BAR; G_WAIT_L(0); G_MMA(0, 0, At, B0); G_BAR; G_SCHED;
;             G_LDB(B1, 1, 1); G_STAGE(G_SB(1, 0), b3, cB0, qB);
;             G_BAR; G_WAIT_L(0); G_MMA(0, 1, At, B1); G_BAR;
;             G_LDA(At, 1, 1); G_STAGE(G_SA(1, 0), a3, cA0, qA);
;             G_BAR; G_WAIT_L(0); G_MMA(1, 0, At, B0); G_BAR; G_SCHED;
;             G_STAGE(G_SB(1, 1), b3 + chB, cB0, qB);
;             G_WAIT_V(6); G_BAR; G_MMA(1, 1, At, B1); G_BAR;
	s_waitcnt lgkmcnt(0)
	v_mfma_f32_16x16x32_bf16 v[140:143], v[64:67], v[152:155], v[140:143]
	v_mfma_f32_16x16x32_bf16 v[136:139], v[144:147], v[152:155], v[136:139]
	v_mfma_f32_16x16x32_bf16 v[124:127], v[64:67], v[162:165], v[124:127]
	v_mfma_f32_16x16x32_bf16 v[120:123], v[144:147], v[162:165], v[120:123]
	v_mfma_f32_16x16x32_bf16 v[108:111], v[64:67], v[176:179], v[108:111]
	v_mfma_f32_16x16x32_bf16 v[104:107], v[144:147], v[176:179], v[104:107]
	v_mfma_f32_16x16x32_bf16 v[92:95], v[64:67], v[200:203], v[92:95]
	v_mfma_f32_16x16x32_bf16 v[88:91], v[144:147], v[200:203], v[88:91]
	v_mfma_f32_16x16x32_bf16 v[140:143], v[68:71], v[156:159], v[140:143]
	v_mfma_f32_16x16x32_bf16 v[136:139], v[148:151], v[156:159], v[136:139]
	v_mfma_f32_16x16x32_bf16 v[124:127], v[68:71], v[172:175], v[124:127]
	v_mfma_f32_16x16x32_bf16 v[120:123], v[148:151], v[172:175], v[120:123]
	v_mfma_f32_16x16x32_bf16 v[108:111], v[68:71], v[196:199], v[108:111]
	v_mfma_f32_16x16x32_bf16 v[104:107], v[148:151], v[196:199], v[104:107]
	v_mfma_f32_16x16x32_bf16 v[92:95], v[68:71], v[204:207], v[92:95]
	v_mfma_f32_16x16x32_bf16 v[88:91], v[148:151], v[204:207], v[88:91]
	s_barrier
	s_mov_b32 m0, s30
	ds_read_b128 v[208:211], v255 offset:49152
	ds_read_b128 v[212:215], v255 offset:50176
	ds_read_b128 v[216:219], v255 offset:51200
	ds_read_b128 v[220:223], v255 offset:52224
	s_add_u32 vcc_lo, s26, s46
	s_addc_u32 vcc_hi, s27, s47
	global_load_lds_dwordx4 v2, vcc
	s_mov_b32 m0, s67
	s_nop 0
	s_add_u32 vcc_lo, s26, s70
	s_addc_u32 vcc_hi, s27, s71
	global_load_lds_dwordx4 v2, vcc
	s_barrier
	s_waitcnt lgkmcnt(0)
	v_mfma_f32_16x16x32_bf16 v[132:135], v[208:211], v[152:155], v[132:135]
	v_mfma_f32_16x16x32_bf16 v[128:131], v[216:219], v[152:155], v[128:131]
	v_mfma_f32_16x16x32_bf16 v[116:119], v[208:211], v[162:165], v[116:119]
	v_mfma_f32_16x16x32_bf16 v[112:115], v[216:219], v[162:165], v[112:115]
	v_mfma_f32_16x16x32_bf16 v[100:103], v[208:211], v[176:179], v[100:103]
	v_mfma_f32_16x16x32_bf16 v[96:99], v[216:219], v[176:179], v[96:99]
	v_mfma_f32_16x16x32_bf16 v[84:87], v[208:211], v[200:203], v[84:87]
	v_mfma_f32_16x16x32_bf16 v[80:83], v[216:219], v[200:203], v[80:83]
	v_mfma_f32_16x16x32_bf16 v[132:135], v[212:215], v[156:159], v[132:135]
	v_mfma_f32_16x16x32_bf16 v[128:131], v[220:223], v[156:159], v[128:131]
	v_mfma_f32_16x16x32_bf16 v[116:119], v[212:215], v[172:175], v[116:119]
	v_mfma_f32_16x16x32_bf16 v[112:115], v[220:223], v[172:175], v[112:115]
	v_mfma_f32_16x16x32_bf16 v[100:103], v[212:215], v[196:199], v[100:103]
	v_mfma_f32_16x16x32_bf16 v[96:99], v[220:223], v[196:199], v[96:99]
	v_mfma_f32_16x16x32_bf16 v[84:87], v[212:215], v[204:207], v[84:87]
	v_mfma_f32_16x16x32_bf16 v[80:83], v[220:223], v[204:207], v[80:83]
	s_barrier
	s_mov_b32 m0, s53
	ds_read_b128 v[152:155], v184 offset:49152
	ds_read_b128 v[156:159], v184 offset:50176
	ds_read_b128 v[162:165], v184 offset:51200
	ds_read_b128 v[172:175], v184 offset:52224
	ds_read_b128 v[176:179], v184 offset:53248
	ds_read_b128 v[196:199], v184 offset:54272
	ds_read_b128 v[200:203], v184 offset:55296
	ds_read_b128 v[204:207], v184 offset:56320
	s_add_u32 vcc_lo, s34, s46
	s_addc_u32 vcc_hi, s35, s47
	global_load_lds_dwordx4 v160, vcc
	s_mov_b32 m0, s54
	s_nop 0
	s_add_u32 vcc_lo, s34, s68
	s_addc_u32 vcc_hi, s35, s69
	global_load_lds_dwordx4 v160, vcc
	s_barrier
	s_waitcnt lgkmcnt(0)
	v_mfma_f32_16x16x32_bf16 v[76:79], v[64:67], v[152:155], v[76:79]
	v_mfma_f32_16x16x32_bf16 v[72:75], v[144:147], v[152:155], v[72:75]
	v_mfma_f32_16x16x32_bf16 v[52:55], v[64:67], v[162:165], v[52:55]
	v_mfma_f32_16x16x32_bf16 v[48:51], v[144:147], v[162:165], v[48:51]
	v_mfma_f32_16x16x32_bf16 v[36:39], v[64:67], v[176:179], v[36:39]
	v_mfma_f32_16x16x32_bf16 v[32:35], v[144:147], v[176:179], v[32:35]
	v_mfma_f32_16x16x32_bf16 v[20:23], v[64:67], v[200:203], v[20:23]
	v_mfma_f32_16x16x32_bf16 v[16:19], v[144:147], v[200:203], v[16:19]
	v_mfma_f32_16x16x32_bf16 v[76:79], v[68:71], v[156:159], v[76:79]
	v_mfma_f32_16x16x32_bf16 v[72:75], v[148:151], v[156:159], v[72:75]
	v_mfma_f32_16x16x32_bf16 v[52:55], v[68:71], v[172:175], v[52:55]
	v_mfma_f32_16x16x32_bf16 v[48:51], v[148:151], v[172:175], v[48:51]
	v_mfma_f32_16x16x32_bf16 v[36:39], v[68:71], v[196:199], v[36:39]
	v_mfma_f32_16x16x32_bf16 v[32:35], v[148:151], v[196:199], v[32:35]
	v_mfma_f32_16x16x32_bf16 v[20:23], v[68:71], v[204:207], v[20:23]
	v_mfma_f32_16x16x32_bf16 v[16:19], v[148:151], v[204:207], v[16:19]
	s_barrier
	s_mov_b32 m0, s65
	s_add_u32 vcc_lo, s26, s84
	s_addc_u32 vcc_hi, s27, s85
	global_load_lds_dwordx4 v2, vcc
	s_mov_b32 m0, s64
	s_nop 0
	s_add_u32 vcc_lo, s26, s28
	s_addc_u32 vcc_hi, s27, s29
	global_load_lds_dwordx4 v2, vcc
	s_waitcnt vmcnt(6)
	s_barrier
	v_mfma_f32_16x16x32_bf16 v[56:59], v[208:211], v[152:155], v[56:59]
	v_mfma_f32_16x16x32_bf16 v[68:71], v[212:215], v[156:159], v[56:59]
	v_mfma_f32_16x16x32_bf16 v[56:59], v[216:219], v[152:155], v[60:63]
	v_mfma_f32_16x16x32_bf16 v[44:47], v[208:211], v[162:165], v[44:47]
	v_mfma_f32_16x16x32_bf16 v[40:43], v[216:219], v[162:165], v[40:43]
	v_mfma_f32_16x16x32_bf16 v[28:31], v[208:211], v[176:179], v[28:31]
	v_mfma_f32_16x16x32_bf16 v[24:27], v[216:219], v[176:179], v[24:27]
	v_mfma_f32_16x16x32_bf16 v[12:15], v[208:211], v[200:203], v[12:15]
	v_mfma_f32_16x16x32_bf16 v[8:11], v[216:219], v[200:203], v[8:11]
	v_mfma_f32_16x16x32_bf16 v[64:67], v[220:223], v[156:159], v[56:59]
	v_mfma_f32_16x16x32_bf16 v[44:47], v[212:215], v[172:175], v[44:47]
	v_mfma_f32_16x16x32_bf16 v[40:43], v[220:223], v[172:175], v[40:43]
	v_mfma_f32_16x16x32_bf16 v[28:31], v[212:215], v[196:199], v[28:31]
	v_mfma_f32_16x16x32_bf16 v[24:27], v[220:223], v[196:199], v[24:27]
	v_mfma_f32_16x16x32_bf16 v[12:15], v[212:215], v[204:207], v[12:15]
	v_mfma_f32_16x16x32_bf16 v[8:11], v[220:223], v[204:207], v[8:11]
	s_andn2_b64 vcc, exec, s[24:25]
	s_mov_b64 s[26:27], -1
	s_mov_b64 s[24:25], 0
	s_mov_b64 s[30:31], 0x100
	s_cbranch_vccz .Ldb_SSM2_cont
	v_readfirstlane_b32 s101, v186
	s_cmpk_gt_u32 s101, 0xff
	s_cbranch_scc1 .Ldb_SSM2_young
	s_barrier
	s_mov_b32 s101, 1
	s_branch .Ldb_SSM2_exit

; #define G_STAGE(bufoff, gbase, o0, h64) do { \
;         __builtin_amdgcn_global_load_lds((const unsigned*)((const char*)(gbase) + (o0)), (LAS unsigned*)(lds + (bufoff) + ldsw), 16, 0, 0); \
;         __builtin_amdgcn_global_load_lds((const unsigned*)((const char*)(gbase) + (h64) + (o0)), (LAS unsigned*)(lds + (bufoff) + ldsw + 8192), 16, 0, 0); } while (0)
; #define G_LDA(dst, b, h) do { _Pragma("unroll") for (int m = 0; m < 4; ++m) _Pragma("unroll") for (int k = 0; k < 2; ++k) dst[m][k] = *(const LAS bf16x8*)(lds + G_SA(b, h) + aoff + m * 2048 + k * 1024); } while (0)
; #define G_LDB(dst, b, h) do { _Pragma("unroll") for (int n = 0; n < 2; ++n) _Pragma("unroll") for (int k = 0; k < 2; ++k) dst[n][k] = *(const LAS bf16x8*)(lds + G_SB(b, h) + boff + n * 2048 + k * 1024); } while (0)
; #define G_WAIT_L(n) asm volatile("s_waitcnt lgkmcnt(" #n ")" ::: "memory")
; #define G_BAR __builtin_amdgcn_s_barrier()
; #define G_SCHED __builtin_amdgcn_sched_barrier(0)
;     ...
;         for (int t = 0; t < nt; t += 2) {
;             const bool last = (t == nt - 2);
;             const char* a1 = cA + (size_t)(t + 1) * ckA;
;             const char* a2 = last ? nA : cA + (size_t)(t + 2) * ckA; const char* b2 = last ? nB : cB + (size_t)(t + 2) * kB;
;             const char* a3 = a2 + ckA; const char* b3 = b2 + kB;
;             G_LDB(B0, 0, 0); G_SCHED; G_LDA(At, 0, 0); G_STAGE(G_SA(1, 1), a1 + chA, cA0, qA);
;             G_WAIT_L(8); G_BAR; G_WAIT_L(0); G_MMA(0, 0, At, B0); G_BAR; G_SCHED;
;             G_LDB(B1, 0, 1); G_STAGE(G_SB(0, 0), b2, cB0, qB);
;             G_BAR; G_WAIT_L(0); G_MMA(0, 1, At, B1); G_BAR;
;     ...
;         for (int a = 0; a < 2; ++a)
; #pragma unroll
;             for (int b = 0; b < 2; ++b)
; #pragma unroll
;                 for (int m = 0; m < 4; ++m)
; #pragma unroll
;                     for (int n = 0; n < 2; ++n) acc[a][b][m][n] = (f32x4){0.f, 0.f, 0.f, 0.f};
.LBB0_803:
	s_add_u32 s13, s18, 0x100
	s_addc_u32 s18, s19, 0
	s_add_u32 s2, s2, 0x800000
	v_mov_b64_e32 v[8:9], 0
	s_addc_u32 s3, s3, 0
	s_mov_b32 s19, -2
	v_mov_b64_e32 v[10:11], 0
	v_mov_b64_e32 v[12:13], 0
	v_mov_b64_e32 v[14:15], 0
	v_mov_b64_e32 v[24:25], 0
	v_mov_b64_e32 v[26:27], 0
	v_mov_b64_e32 v[28:29], 0
	v_mov_b64_e32 v[30:31], 0
	v_mov_b64_e32 v[40:41], 0
	v_mov_b64_e32 v[42:43], 0
	v_mov_b64_e32 v[44:45], 0
	v_mov_b64_e32 v[46:47], 0
	v_mov_b64_e32 v[56:57], 0
	v_mov_b64_e32 v[58:59], 0
	v_mov_b64_e32 v[60:61], 0
	v_mov_b64_e32 v[62:63], 0
	v_mov_b64_e32 v[16:17], 0
	v_mov_b64_e32 v[18:19], 0
	v_mov_b64_e32 v[20:21], 0
	v_mov_b64_e32 v[22:23], 0
	v_mov_b64_e32 v[32:33], 0
	v_mov_b64_e32 v[34:35], 0
	v_mov_b64_e32 v[36:37], 0
	v_mov_b64_e32 v[38:39], 0
	v_mov_b64_e32 v[48:49], 0
	v_mov_b64_e32 v[50:51], 0
	v_mov_b64_e32 v[52:53], 0
	v_mov_b64_e32 v[54:55], 0
	v_mov_b64_e32 v[64:65], 0
	v_mov_b64_e32 v[66:67], 0
	v_mov_b64_e32 v[68:69], 0
	v_mov_b64_e32 v[70:71], 0
	v_mov_b64_e32 v[72:73], 0
	v_mov_b64_e32 v[74:75], 0
	v_mov_b64_e32 v[76:77], 0
	v_mov_b64_e32 v[78:79], 0
	v_mov_b64_e32 v[88:89], 0
	v_mov_b64_e32 v[90:91], 0
	v_mov_b64_e32 v[92:93], 0
	v_mov_b64_e32 v[94:95], 0
	v_mov_b64_e32 v[104:105], 0
	v_mov_b64_e32 v[106:107], 0
	v_mov_b64_e32 v[108:109], 0
	v_mov_b64_e32 v[110:111], 0
	v_mov_b64_e32 v[128:129], 0
	v_mov_b64_e32 v[130:131], 0
	v_mov_b64_e32 v[132:133], 0
	v_mov_b64_e32 v[134:135], 0
	v_mov_b64_e32 v[80:81], 0
	v_mov_b64_e32 v[82:83], 0
	v_mov_b64_e32 v[84:85], 0
	v_mov_b64_e32 v[86:87], 0
	v_mov_b64_e32 v[96:97], 0
	v_mov_b64_e32 v[98:99], 0
	v_mov_b64_e32 v[100:101], 0
	v_mov_b64_e32 v[102:103], 0
	v_mov_b64_e32 v[116:117], 0
	v_mov_b64_e32 v[118:119], 0
	v_mov_b64_e32 v[120:121], 0
	v_mov_b64_e32 v[122:123], 0
	v_mov_b64_e32 v[140:141], 0
	v_mov_b64_e32 v[142:143], 0
	v_mov_b64_e32 v[144:145], 0
	v_mov_b64_e32 v[146:147], 0
	s_mov_b64 s[42:43], 0x20080
	s_mov_b64 s[50:51], 0x10000
	s_mov_b64 s[52:53], 0x30000
	s_mov_b64 s[54:55], 0x10080
	s_mov_b64 s[58:59], 0x30080
	s_mov_b64 s[62:63], 0x400000
	s_cmp_eq_u32 s101, 2
	s_cselect_b32 s101, 0, s101
	v_add_u32_e32 v255, 0x10000, v196
.LBB0_804:
	s_add_i32 s40, 0, 0x10000
	ds_read_b128 v[112:115], v255 offset:0
	ds_read_b128 v[124:127], v255 offset:1024
	ds_read_b128 v[136:139], v255 offset:2048
	ds_read_b128 v[148:151], v255 offset:3072
	s_cmp_eq_u32 s19, 4
	s_cselect_b32 s5, s15, s3
	s_cselect_b32 s4, s14, s2
	s_cselect_b32 s37, s17, s18
	s_cselect_b32 s36, s16, s13
	s_mov_b32 s38, 0xffc01000
	s_mov_b32 s39, -1
	s_add_u32 vcc_lo, s2, s38
	s_addc_u32 vcc_hi, s3, s39
	s_mov_b32 s38, 0xffc01800
	s_add_i32 m0, s24, 0xc000
	s_mov_b32 s39, -1
	ds_read_b128 v[152:155], v197
	ds_read_b128 v[156:159], v197 offset:1024
	ds_read_b128 v[160:163], v197 offset:2048
	ds_read_b128 v[172:175], v197 offset:3072
	ds_read_b128 v[176:179], v197 offset:4096
	ds_read_b128 v[180:183], v197 offset:5120
	ds_read_b128 v[198:201], v197 offset:6144
	ds_read_b128 v[202:205], v197 offset:7168
	global_load_lds_dwordx4 v166, vcc
	s_add_i32 m0, s24, 0xe000
	s_nop 0
	s_add_u32 vcc_lo, s2, s38
	s_addc_u32 vcc_hi, s3, s39
	global_load_lds_dwordx4 v166, vcc
	s_waitcnt lgkmcnt(8)
	s_cmp_eq_u32 s101, 1
	s_cbranch_scc1 .Ldb_GLU_sk
	s_barrier
.Ldb_GLU_sk:
	s_mov_b32 s101, 0
	s_waitcnt lgkmcnt(0)
	v_mfma_f32_16x16x32_bf16 v[144:147], v[112:115], v[152:155], v[144:147]
	v_mfma_f32_16x16x32_bf16 v[140:143], v[136:139], v[152:155], v[140:143]
	v_mfma_f32_16x16x32_bf16 v[120:123], v[112:115], v[160:163], v[120:123]
	v_mfma_f32_16x16x32_bf16 v[116:119], v[136:139], v[160:163], v[116:119]
	v_mfma_f32_16x16x32_bf16 v[100:103], v[112:115], v[176:179], v[100:103]
	v_mfma_f32_16x16x32_bf16 v[96:99], v[136:139], v[176:179], v[96:99]
	v_mfma_f32_16x16x32_bf16 v[84:87], v[112:115], v[198:201], v[84:87]
	v_mfma_f32_16x16x32_bf16 v[80:83], v[136:139], v[198:201], v[80:83]
	v_mfma_f32_16x16x32_bf16 v[144:147], v[124:127], v[156:159], v[144:147]
	v_mfma_f32_16x16x32_bf16 v[140:143], v[148:151], v[156:159], v[140:143]
	v_mfma_f32_16x16x32_bf16 v[120:123], v[124:127], v[172:175], v[120:123]
	v_mfma_f32_16x16x32_bf16 v[116:119], v[148:151], v[172:175], v[116:119]
	v_mfma_f32_16x16x32_bf16 v[100:103], v[124:127], v[180:183], v[100:103]
	v_mfma_f32_16x16x32_bf16 v[96:99], v[148:151], v[180:183], v[96:99]
	v_mfma_f32_16x16x32_bf16 v[84:87], v[124:127], v[202:205], v[84:87]
	v_mfma_f32_16x16x32_bf16 v[80:83], v[148:151], v[202:205], v[80:83]
	s_barrier
	s_add_i32 s38, 0, 0x14000
	s_add_i32 s100, s40, s21
	s_mov_b32 m0, s100
	ds_read_b128 v[206:209], v255 offset:16384
	ds_read_b128 v[210:213], v255 offset:17408
	ds_read_b128 v[214:217], v255 offset:18432
	ds_read_b128 v[218:221], v255 offset:19456
	global_load_lds_dwordx4 v2, s[36:37]
	s_add_i32 m0, s100, 0x2000
	s_nop 0
	s_add_u32 vcc_lo, s36, s50
	s_addc_u32 vcc_hi, s37, s51
	global_load_lds_dwordx4 v2, vcc
	s_barrier
	s_waitcnt lgkmcnt(0)
	v_mfma_f32_16x16x32_bf16 v[132:135], v[206:209], v[152:155], v[132:135]
	v_mfma_f32_16x16x32_bf16 v[128:131], v[214:217], v[152:155], v[128:131]
	v_mfma_f32_16x16x32_bf16 v[108:111], v[206:209], v[160:163], v[108:111]
	v_mfma_f32_16x16x32_bf16 v[104:107], v[214:217], v[160:163], v[104:107]
	v_mfma_f32_16x16x32_bf16 v[92:95], v[206:209], v[176:179], v[92:95]
	v_mfma_f32_16x16x32_bf16 v[88:91], v[214:217], v[176:179], v[88:91]
	v_mfma_f32_16x16x32_bf16 v[76:79], v[206:209], v[198:201], v[76:79]
	v_mfma_f32_16x16x32_bf16 v[72:75], v[214:217], v[198:201], v[72:75]
	v_mfma_f32_16x16x32_bf16 v[132:135], v[210:213], v[156:159], v[132:135]
	v_mfma_f32_16x16x32_bf16 v[128:131], v[218:221], v[156:159], v[128:131]
	v_mfma_f32_16x16x32_bf16 v[108:111], v[210:213], v[172:175], v[108:111]
	v_mfma_f32_16x16x32_bf16 v[104:107], v[218:221], v[172:175], v[104:107]
	v_mfma_f32_16x16x32_bf16 v[92:95], v[210:213], v[180:183], v[92:95]
	v_mfma_f32_16x16x32_bf16 v[88:91], v[218:221], v[180:183], v[88:91]
	v_mfma_f32_16x16x32_bf16 v[76:79], v[210:213], v[202:205], v[76:79]
	v_mfma_f32_16x16x32_bf16 v[72:75], v[218:221], v[202:205], v[72:75]
	s_barrier
; #define G_STAGE(bufoff, gbase, o0, h64) do { \
;         __builtin_amdgcn_global_load_lds((const unsigned*)((const char*)(gbase) + (o0)), (LAS unsigned*)(lds + (bufoff) + ldsw), 16, 0, 0); \
;         __builtin_amdgcn_global_load_lds((const unsigned*)((const char*)(gbase) + (h64) + (o0)), (LAS unsigned*)(lds + (bufoff) + ldsw + 8192), 16, 0, 0); } while (0)
; #define G_LDA(dst, b, h) do { _Pragma("unroll") for (int m = 0; m < 4; ++m) _Pragma("unroll") for (int k = 0; k < 2; ++k) dst[m][k] = *(const LAS bf16x8*)(lds + G_SA(b, h) + aoff + m * 2048 + k * 1024); } while (0)
; #define G_LDB(dst, b, h) do { _Pragma("unroll") for (int n = 0; n < 2; ++n) _Pragma("unroll") for (int k = 0; k < 2; ++k) dst[n][k] = *(const LAS bf16x8*)(lds + G_SB(b, h) + boff + n * 2048 + k * 1024); } while (0)
; #define G_WAIT_V(n) asm volatile("s_waitcnt vmcnt(" #n ")" ::: "memory")
; #define G_WAIT_L(n) asm volatile("s_waitcnt lgkmcnt(" #n ")" ::: "memory")
; #define G_BAR __builtin_amdgcn_s_barrier()
; #define G_SCHED __builtin_amdgcn_sched_barrier(0)
;     ...
;             G_LDA(At, 0, 1); G_STAGE(G_SA(0, 0), a2, cA0, qA);
;             G_BAR; G_WAIT_L(0); G_MMA(1, 0, At, B0); G_BAR; G_SCHED;
;             G_STAGE(G_SB(0, 1), b2 + chB, cB0, qB);
;             G_WAIT_V(6); G_BAR; G_MMA(1, 1, At, B1); G_BAR;
;             G_LDB(B0, 1, 0); G_SCHED; G_LDA(At, 1, 0); G_STAGE(G_SA(0, 1), a2 + chA, cA0, qA);
;             G_WAIT_L(8); G_BAR; G_WAIT_L(0); G_MMA(0, 0, At, B0); G_BAR; G_SCHED;
	s_mov_b32 m0, s24
	v_lshl_add_u64 v[222:223], s[4:5], 0, v[164:165]
	ds_read_b128 v[152:155], v197 offset:16384
	ds_read_b128 v[156:159], v197 offset:17408
	ds_read_b128 v[160:163], v197 offset:18432
	ds_read_b128 v[172:175], v197 offset:19456
	ds_read_b128 v[176:179], v197 offset:20480
	ds_read_b128 v[180:183], v197 offset:21504
	ds_read_b128 v[198:201], v197 offset:22528
	ds_read_b128 v[202:205], v197 offset:23552
	global_load_lds_dwordx4 v164, s[4:5]
	s_mov_b32 m0, s25
	s_nop 0
	s_add_u32 vcc_lo, s4, s70
	s_addc_u32 vcc_hi, s5, s71
	global_load_lds_dwordx4 v164, vcc
	s_barrier
	s_waitcnt lgkmcnt(0)
	v_mfma_f32_16x16x32_bf16 v[68:71], v[112:115], v[152:155], v[68:71]
	v_mfma_f32_16x16x32_bf16 v[64:67], v[136:139], v[152:155], v[64:67]
	v_mfma_f32_16x16x32_bf16 v[52:55], v[112:115], v[160:163], v[52:55]
	v_mfma_f32_16x16x32_bf16 v[48:51], v[136:139], v[160:163], v[48:51]
	v_mfma_f32_16x16x32_bf16 v[36:39], v[112:115], v[176:179], v[36:39]
	v_mfma_f32_16x16x32_bf16 v[32:35], v[136:139], v[176:179], v[32:35]
	v_mfma_f32_16x16x32_bf16 v[20:23], v[112:115], v[198:201], v[20:23]
	v_mfma_f32_16x16x32_bf16 v[16:19], v[136:139], v[198:201], v[16:19]
	v_mfma_f32_16x16x32_bf16 v[68:71], v[124:127], v[156:159], v[68:71]
	v_mfma_f32_16x16x32_bf16 v[64:67], v[148:151], v[156:159], v[64:67]
	v_mfma_f32_16x16x32_bf16 v[52:55], v[124:127], v[172:175], v[52:55]
	v_mfma_f32_16x16x32_bf16 v[48:51], v[148:151], v[172:175], v[48:51]
	v_mfma_f32_16x16x32_bf16 v[36:39], v[124:127], v[180:183], v[36:39]
	v_mfma_f32_16x16x32_bf16 v[32:35], v[148:151], v[180:183], v[32:35]
	v_mfma_f32_16x16x32_bf16 v[20:23], v[124:127], v[202:205], v[20:23]
	v_mfma_f32_16x16x32_bf16 v[16:19], v[148:151], v[202:205], v[16:19]
	s_barrier
	s_add_i32 s100, s38, s21
	s_mov_b32 m0, s100
	s_nop 0
	s_add_u32 vcc_lo, s36, s0
	s_addc_u32 vcc_hi, s37, s1
	global_load_lds_dwordx4 v2, vcc
	s_add_i32 m0, s100, 0x2000
	s_nop 0
	s_add_u32 vcc_lo, s36, s52
	s_addc_u32 vcc_hi, s37, s53
	global_load_lds_dwordx4 v2, vcc
	s_waitcnt vmcnt(6)
	s_barrier
	v_mfma_f32_16x16x32_bf16 v[60:63], v[206:209], v[152:155], v[60:63]
	v_mfma_f32_16x16x32_bf16 v[56:59], v[214:217], v[152:155], v[56:59]
	v_mfma_f32_16x16x32_bf16 v[44:47], v[206:209], v[160:163], v[44:47]
	v_mfma_f32_16x16x32_bf16 v[40:43], v[214:217], v[160:163], v[40:43]
	v_mfma_f32_16x16x32_bf16 v[28:31], v[206:209], v[176:179], v[28:31]
	v_mfma_f32_16x16x32_bf16 v[24:27], v[214:217], v[176:179], v[24:27]
	v_mfma_f32_16x16x32_bf16 v[12:15], v[206:209], v[198:201], v[12:15]
	v_mfma_f32_16x16x32_bf16 v[8:11], v[214:217], v[198:201], v[8:11]
	v_mfma_f32_16x16x32_bf16 v[60:63], v[210:213], v[156:159], v[60:63]
	v_mfma_f32_16x16x32_bf16 v[56:59], v[218:221], v[156:159], v[56:59]
	v_mfma_f32_16x16x32_bf16 v[44:47], v[210:213], v[172:175], v[44:47]
	v_mfma_f32_16x16x32_bf16 v[40:43], v[218:221], v[172:175], v[40:43]
	v_mfma_f32_16x16x32_bf16 v[28:31], v[210:213], v[180:183], v[28:31]
	v_mfma_f32_16x16x32_bf16 v[24:27], v[218:221], v[180:183], v[24:27]
	v_mfma_f32_16x16x32_bf16 v[12:15], v[210:213], v[202:205], v[12:15]
	v_mfma_f32_16x16x32_bf16 v[8:11], v[218:221], v[202:205], v[8:11]
	s_barrier
	s_add_i32 s100, 0, 0x18000
	ds_read_b128 v[112:115], v255 offset:32768
	ds_read_b128 v[124:127], v255 offset:33792
	ds_read_b128 v[136:139], v255 offset:34816
	ds_read_b128 v[148:151], v255 offset:35840
	s_mov_b32 m0, s26
	ds_read_b128 v[152:155], v197 offset:32768
	ds_read_b128 v[156:159], v197 offset:33792
	ds_read_b128 v[160:163], v197 offset:34816
	ds_read_b128 v[172:175], v197 offset:35840
	ds_read_b128 v[176:179], v197 offset:36864
	ds_read_b128 v[180:183], v197 offset:37888
	ds_read_b128 v[198:201], v197 offset:38912
	ds_read_b128 v[202:205], v197 offset:39936
	s_add_u32 vcc_lo, s4, s80
	s_addc_u32 vcc_hi, s5, s81
	global_load_lds_dwordx4 v164, vcc
	s_mov_b32 m0, s27
	s_nop 0
	s_add_u32 vcc_lo, s4, s82
	s_addc_u32 vcc_hi, s5, s83
	global_load_lds_dwordx4 v164, vcc
	s_waitcnt lgkmcnt(8)
	s_barrier
	s_waitcnt lgkmcnt(0)
	v_mfma_f32_16x16x32_bf16 v[144:147], v[112:115], v[152:155], v[144:147]
	v_mfma_f32_16x16x32_bf16 v[140:143], v[136:139], v[152:155], v[140:143]
	v_mfma_f32_16x16x32_bf16 v[120:123], v[112:115], v[160:163], v[120:123]
	v_mfma_f32_16x16x32_bf16 v[116:119], v[136:139], v[160:163], v[116:119]
	v_mfma_f32_16x16x32_bf16 v[100:103], v[112:115], v[176:179], v[100:103]
	v_mfma_f32_16x16x32_bf16 v[96:99], v[136:139], v[176:179], v[96:99]
	v_mfma_f32_16x16x32_bf16 v[84:87], v[112:115], v[198:201], v[84:87]
	v_mfma_f32_16x16x32_bf16 v[80:83], v[136:139], v[198:201], v[80:83]
	v_mfma_f32_16x16x32_bf16 v[144:147], v[124:127], v[156:159], v[144:147]
	v_mfma_f32_16x16x32_bf16 v[140:143], v[148:151], v[156:159], v[140:143]
	v_mfma_f32_16x16x32_bf16 v[120:123], v[124:127], v[172:175], v[120:123]
	v_mfma_f32_16x16x32_bf16 v[116:119], v[148:151], v[172:175], v[116:119]
	v_mfma_f32_16x16x32_bf16 v[100:103], v[124:127], v[180:183], v[100:103]
	v_mfma_f32_16x16x32_bf16 v[96:99], v[148:151], v[180:183], v[96:99]
	v_mfma_f32_16x16x32_bf16 v[84:87], v[124:127], v[202:205], v[84:87]
	v_mfma_f32_16x16x32_bf16 v[80:83], v[148:151], v[202:205], v[80:83]
	s_barrier
; #define G_STAGE(bufoff, gbase, o0, h64) do { \
;         __builtin_amdgcn_global_load_lds((const unsigned*)((const char*)(gbase) + (o0)), (LAS unsigned*)(lds + (bufoff) + ldsw), 16, 0, 0); \
;         __builtin_amdgcn_global_load_lds((const unsigned*)((const char*)(gbase) + (h64) + (o0)), (LAS unsigned*)(lds + (bufoff) + ldsw + 8192), 16, 0, 0); } while (0)
; #define G_LDA(dst, b, h) do { _Pragma("unroll") for (int m = 0; m < 4; ++m) _Pragma("unroll") for (int k = 0; k < 2; ++k) dst[m][k] = *(const LAS bf16x8*)(lds + G_SA(b, h) + aoff + m * 2048 + k * 1024); } while (0)
; #define G_WAIT_V(n) asm volatile("s_waitcnt vmcnt(" #n ")" ::: "memory")
; #define G_WAIT_L(n) asm volatile("s_waitcnt lgkmcnt(" #n ")" ::: "memory")
; #define G_BAR __builtin_amdgcn_s_barrier()
; #define G_SCHED __builtin_amdgcn_sched_barrier(0)
;     ...
;             G_LDA(At, 1, 1); G_STAGE(G_SA(1, 0), a3, cA0, qA);
;             G_BAR; G_WAIT_L(0); G_MMA(1, 0, At, B0); G_BAR; G_SCHED;
;             G_STAGE(G_SB(1, 1), b3 + chB, cB0, qB);
;             G_WAIT_V(6); G_BAR; G_MMA(1, 1, At, B1); G_BAR;
;         }
	s_add_i32 s5, 0, 0x1c000
	s_add_i32 s4, s100, s21
	s_mov_b32 m0, s4
	ds_read_b128 v[206:209], v255 offset:49152
	ds_read_b128 v[210:213], v255 offset:50176
	ds_read_b128 v[214:217], v255 offset:51200
	ds_read_b128 v[218:221], v255 offset:52224
	s_add_u32 vcc_lo, s36, s46
	s_addc_u32 vcc_hi, s37, s47
	global_load_lds_dwordx4 v2, vcc
	s_add_i32 m0, s4, 0x2000
	s_nop 0
	s_add_u32 vcc_lo, s36, s54
	s_addc_u32 vcc_hi, s37, s55
	global_load_lds_dwordx4 v2, vcc
	s_barrier
	s_waitcnt lgkmcnt(0)
	v_mfma_f32_16x16x32_bf16 v[132:135], v[206:209], v[152:155], v[132:135]
	v_mfma_f32_16x16x32_bf16 v[128:131], v[214:217], v[152:155], v[128:131]
	v_mfma_f32_16x16x32_bf16 v[108:111], v[206:209], v[160:163], v[108:111]
	v_mfma_f32_16x16x32_bf16 v[104:107], v[214:217], v[160:163], v[104:107]
	v_mfma_f32_16x16x32_bf16 v[92:95], v[206:209], v[176:179], v[92:95]
	v_mfma_f32_16x16x32_bf16 v[88:91], v[214:217], v[176:179], v[88:91]
	v_mfma_f32_16x16x32_bf16 v[76:79], v[206:209], v[198:201], v[76:79]
	v_mfma_f32_16x16x32_bf16 v[72:75], v[214:217], v[198:201], v[72:75]
	v_mfma_f32_16x16x32_bf16 v[132:135], v[210:213], v[156:159], v[132:135]
	v_mfma_f32_16x16x32_bf16 v[128:131], v[218:221], v[156:159], v[128:131]
	v_mfma_f32_16x16x32_bf16 v[108:111], v[210:213], v[172:175], v[108:111]
	v_mfma_f32_16x16x32_bf16 v[104:107], v[218:221], v[172:175], v[104:107]
	v_mfma_f32_16x16x32_bf16 v[92:95], v[210:213], v[180:183], v[92:95]
	v_mfma_f32_16x16x32_bf16 v[88:91], v[218:221], v[180:183], v[88:91]
	v_mfma_f32_16x16x32_bf16 v[76:79], v[210:213], v[202:205], v[76:79]
	v_mfma_f32_16x16x32_bf16 v[72:75], v[218:221], v[202:205], v[72:75]
	s_barrier
	s_mov_b32 m0, s29
	v_lshl_add_u64 v[224:225], v[222:223], 0, s[62:63]
	ds_read_b128 v[152:155], v197 offset:49152
	ds_read_b128 v[156:159], v197 offset:50176
	ds_read_b128 v[160:163], v197 offset:51200
	ds_read_b128 v[172:175], v197 offset:52224
	ds_read_b128 v[176:179], v197 offset:53248
	ds_read_b128 v[180:183], v197 offset:54272
	ds_read_b128 v[198:201], v197 offset:55296
	ds_read_b128 v[202:205], v197 offset:56320
	global_load_lds_dwordx4 v[224:225], off
	v_lshl_add_u64 v[222:223], v[222:223], 0, s[84:85]
	s_mov_b32 m0, s30
	s_nop 0
	global_load_lds_dwordx4 v[222:223], off
	s_barrier
	s_waitcnt lgkmcnt(0)
	v_mfma_f32_16x16x32_bf16 v[68:71], v[112:115], v[152:155], v[68:71]
	v_mfma_f32_16x16x32_bf16 v[64:67], v[136:139], v[152:155], v[64:67]
	v_mfma_f32_16x16x32_bf16 v[52:55], v[112:115], v[160:163], v[52:55]
	v_mfma_f32_16x16x32_bf16 v[48:51], v[136:139], v[160:163], v[48:51]
	v_mfma_f32_16x16x32_bf16 v[36:39], v[112:115], v[176:179], v[36:39]
	v_mfma_f32_16x16x32_bf16 v[32:35], v[136:139], v[176:179], v[32:35]
	v_mfma_f32_16x16x32_bf16 v[20:23], v[112:115], v[198:201], v[20:23]
	v_mfma_f32_16x16x32_bf16 v[16:19], v[136:139], v[198:201], v[16:19]
	v_mfma_f32_16x16x32_bf16 v[68:71], v[124:127], v[156:159], v[68:71]
	v_mfma_f32_16x16x32_bf16 v[64:67], v[148:151], v[156:159], v[64:67]
	v_mfma_f32_16x16x32_bf16 v[52:55], v[124:127], v[172:175], v[52:55]
	v_mfma_f32_16x16x32_bf16 v[48:51], v[148:151], v[172:175], v[48:51]
	v_mfma_f32_16x16x32_bf16 v[36:39], v[124:127], v[180:183], v[36:39]
	v_mfma_f32_16x16x32_bf16 v[32:35], v[148:151], v[180:183], v[32:35]
	v_mfma_f32_16x16x32_bf16 v[20:23], v[124:127], v[202:205], v[20:23]
	v_mfma_f32_16x16x32_bf16 v[16:19], v[148:151], v[202:205], v[16:19]
	s_barrier
	s_add_i32 s4, s5, s21
	s_mov_b32 m0, s4
	s_nop 0
	s_add_u32 vcc_lo, s36, s42
	s_addc_u32 vcc_hi, s37, s43
	global_load_lds_dwordx4 v2, vcc
	s_add_i32 m0, s4, 0x2000
	s_nop 0
	s_add_u32 vcc_lo, s36, s58
	s_addc_u32 vcc_hi, s37, s59
	global_load_lds_dwordx4 v2, vcc
	s_add_i32 s19, s19, 2
	s_add_u32 s13, s13, 0x100
	s_addc_u32 s18, s18, 0
	s_add_u32 s2, s2, 0x800000
	s_addc_u32 s3, s3, 0
	s_cmp_gt_u32 s19, 5
	s_waitcnt vmcnt(6)
	s_barrier
	v_mfma_f32_16x16x32_bf16 v[60:63], v[206:209], v[152:155], v[60:63]
	v_mfma_f32_16x16x32_bf16 v[56:59], v[214:217], v[152:155], v[56:59]
	v_mfma_f32_16x16x32_bf16 v[44:47], v[206:209], v[160:163], v[44:47]
	v_mfma_f32_16x16x32_bf16 v[40:43], v[214:217], v[160:163], v[40:43]
	v_mfma_f32_16x16x32_bf16 v[28:31], v[206:209], v[176:179], v[28:31]
	v_mfma_f32_16x16x32_bf16 v[24:27], v[214:217], v[176:179], v[24:27]
	v_mfma_f32_16x16x32_bf16 v[12:15], v[206:209], v[198:201], v[12:15]
	v_mfma_f32_16x16x32_bf16 v[8:11], v[214:217], v[198:201], v[8:11]
	v_mfma_f32_16x16x32_bf16 v[60:63], v[210:213], v[156:159], v[60:63]
	v_mfma_f32_16x16x32_bf16 v[56:59], v[218:221], v[156:159], v[56:59]
	v_mfma_f32_16x16x32_bf16 v[44:47], v[210:213], v[172:175], v[44:47]
	v_mfma_f32_16x16x32_bf16 v[40:43], v[218:221], v[172:175], v[40:43]
	v_mfma_f32_16x16x32_bf16 v[28:31], v[210:213], v[180:183], v[28:31]
	v_mfma_f32_16x16x32_bf16 v[24:27], v[218:221], v[180:183], v[24:27]
	v_mfma_f32_16x16x32_bf16 v[12:15], v[210:213], v[202:205], v[12:15]
	v_mfma_f32_16x16x32_bf16 v[8:11], v[218:221], v[202:205], v[8:11]
	s_cbranch_scc0 .Ldb_GLU_cont
	v_readfirstlane_b32 s101, v186
	s_cmpk_gt_u32 s101, 0xff
	s_cbranch_scc1 .Ldb_GLU_young
	s_barrier
	s_mov_b32 s101, 1
	s_branch .Ldb_GLU_exit

; #define G_STAGE(bufoff, gbase, o0, h64) do { \
;         __builtin_amdgcn_global_load_lds((const unsigned*)((const char*)(gbase) + (o0)), (LAS unsigned*)(lds + (bufoff) + ldsw), 16, 0, 0); \
;         __builtin_amdgcn_global_load_lds((const unsigned*)((const char*)(gbase) + (h64) + (o0)), (LAS unsigned*)(lds + (bufoff) + ldsw + 8192), 16, 0, 0); } while (0)
; #define G_LDA(dst, b, h) do { _Pragma("unroll") for (int m = 0; m < 4; ++m) _Pragma("unroll") for (int k = 0; k < 2; ++k) dst[m][k] = *(const LAS bf16x8*)(lds + G_SA(b, h) + aoff + m * 2048 + k * 1024); } while (0)
; #define G_WAIT_V(n) asm volatile("s_waitcnt vmcnt(" #n ")" ::: "memory")
; #define G_WAIT_L(n) asm volatile("s_waitcnt lgkmcnt(" #n ")" ::: "memory")
;     ...
;     for (;;) {
;         const bool has_next = sched_next<PH, SUB>(E.ws, E.layer, ui + 1, nxt, E.x);
;         if (!has_next) nxt = cur;
;         const char* nA = nxt.A; const char* nB = nxt.B;
; #pragma unroll 1
;         for (int t = 0; t < nt; t += 2) {
;             const bool last = (t == nt - 2);
;             const char* a1 = cA + (size_t)(t + 1) * ckA;
;             const char* a2 = last ? nA : cA + (size_t)(t + 2) * ckA; const char* b2 = last ? nB : cB + (size_t)(t + 2) * kB;
;             const char* a3 = a2 + ckA; const char* b3 = b2 + kB;
;             G_LDB(B0, 0, 0); G_SCHED; G_LDA(At, 0, 0); G_STAGE(G_SA(1, 1), a1 + chA, cA0, qA);
;             G_WAIT_L(8); G_BAR; G_WAIT_L(0); G_MMA(0, 0, At, B0); G_BAR; G_SCHED;
;             G_LDB(B1, 0, 1); G_STAGE(G_SB(0, 0), b2, cB0, qB);
;             G_BAR; G_WAIT_L(0); G_MMA(0, 1, At, B1); G_BAR;
;             G_LDA(At, 0, 1); G_STAGE(G_SA(0, 0), a2, cA0, qA);
;             G_BAR; G_WAIT_L(0); G_MMA(1, 0, At, B0); G_BAR; G_SCHED;
;             G_STAGE(G_SB(0, 1), b2 + chB, cB0, qB);
;             G_WAIT_V(6); G_BAR; G_MMA(1, 1, At, B1); G_BAR;
;             G_LDB(B0, 1, 0); G_SCHED; G_LDA(At, 1, 0); G_STAGE(G_SA(0, 1), a2 + chA, cA0, qA);
;             G_WAIT_L(8); G_BAR; G_WAIT_L(0); G_MMA(0, 0, At, B0); G_BAR; G_SCHED;
;     ...
; #pragma unroll
;         for (int a = 0; a < 2; ++a)
; #pragma unroll
;             for (int b = 0; b < 2; ++b)
; #pragma unroll
;                 for (int m = 0; m < 4; ++m)
; #pragma unroll
;                     for (int n = 0; n < 2; ++n) acc[a][b][m][n] = (f32x4){0.f, 0.f, 0.f, 0.f};
;         cur = nxt; cA = nA; cB = nB; ++ui;
.LBB0_871:
	s_add_u32 s2, s2, 0xb0080
	s_addc_u32 s3, s3, 0
	s_add_u32 s37, s12, 0x100
	v_mov_b64_e32 v[8:9], 0
	s_addc_u32 s38, s13, 0
	s_mov_b32 s39, -2
	v_mov_b64_e32 v[10:11], 0
	v_mov_b64_e32 v[12:13], 0
	v_mov_b64_e32 v[14:15], 0
	v_mov_b64_e32 v[24:25], 0
	v_mov_b64_e32 v[26:27], 0
	v_mov_b64_e32 v[28:29], 0
	v_mov_b64_e32 v[30:31], 0
	v_mov_b64_e32 v[40:41], 0
	v_mov_b64_e32 v[42:43], 0
	v_mov_b64_e32 v[44:45], 0
	v_mov_b64_e32 v[46:47], 0
	v_mov_b64_e32 v[56:57], 0
	v_mov_b64_e32 v[58:59], 0
	v_mov_b64_e32 v[60:61], 0
	v_mov_b64_e32 v[62:63], 0
	v_mov_b64_e32 v[16:17], 0
	v_mov_b64_e32 v[18:19], 0
	v_mov_b64_e32 v[20:21], 0
	v_mov_b64_e32 v[22:23], 0
	v_mov_b64_e32 v[36:37], 0
	v_mov_b64_e32 v[38:39], 0
	v_mov_b64_e32 v[32:33], 0
	v_mov_b64_e32 v[34:35], 0
	v_mov_b64_e32 v[52:53], 0
	v_mov_b64_e32 v[54:55], 0
	v_mov_b64_e32 v[48:49], 0
	v_mov_b64_e32 v[50:51], 0
	v_mov_b64_e32 v[68:69], 0
	v_mov_b64_e32 v[70:71], 0
	v_mov_b64_e32 v[64:65], 0
	v_mov_b64_e32 v[66:67], 0
	v_mov_b64_e32 v[72:73], 0
	v_mov_b64_e32 v[74:75], 0
	v_mov_b64_e32 v[76:77], 0
	v_mov_b64_e32 v[78:79], 0
	v_mov_b64_e32 v[88:89], 0
	v_mov_b64_e32 v[90:91], 0
	v_mov_b64_e32 v[92:93], 0
	v_mov_b64_e32 v[94:95], 0
	v_mov_b64_e32 v[104:105], 0
	v_mov_b64_e32 v[106:107], 0
	v_mov_b64_e32 v[108:109], 0
	v_mov_b64_e32 v[110:111], 0
	v_mov_b64_e32 v[120:121], 0
	v_mov_b64_e32 v[122:123], 0
	v_mov_b64_e32 v[124:125], 0
	v_mov_b64_e32 v[126:127], 0
	v_mov_b64_e32 v[84:85], 0
	v_mov_b64_e32 v[86:87], 0
	v_mov_b64_e32 v[80:81], 0
	v_mov_b64_e32 v[82:83], 0
	v_mov_b64_e32 v[100:101], 0
	v_mov_b64_e32 v[102:103], 0
	v_mov_b64_e32 v[96:97], 0
	v_mov_b64_e32 v[98:99], 0
	v_mov_b64_e32 v[116:117], 0
	v_mov_b64_e32 v[118:119], 0
	v_mov_b64_e32 v[112:113], 0
	v_mov_b64_e32 v[114:115], 0
	v_mov_b64_e32 v[132:133], 0
	v_mov_b64_e32 v[134:135], 0
	v_mov_b64_e32 v[128:129], 0
	v_mov_b64_e32 v[130:131], 0
	s_mov_b64 s[42:43], 0x20080
	s_mov_b64 s[50:51], 0x10000
	s_mov_b64 s[52:53], 0x30000
	s_mov_b64 s[54:55], 0x10080
	s_mov_b64 s[58:59], 0x30080
	s_cmp_eq_u32 s101, 2
	s_cselect_b32 s101, 0, s101
	v_add_u32_e32 v239, 0x10000, v159
.LBB0_872:
	s_add_u32 s4, s2, 0xfff50080
	s_addc_u32 s5, s3, -1
	s_add_i32 s40, 0, 0x10000
	ds_read_b128 v[144:147], v239 offset:0
	ds_read_b128 v[148:151], v239 offset:1024
	ds_read_b128 v[136:139], v239 offset:2048
	ds_read_b128 v[140:143], v239 offset:3072
	s_cmp_eq_u32 s39, 4
	s_cselect_b32 s13, s9, s5
	s_cselect_b32 s12, s8, s4
	s_cselect_b32 s15, s11, s38
	s_cselect_b32 s14, s10, s37
	s_add_i32 m0, s22, 0xc000
	ds_read_b128 v[160:163], v236
	ds_read_b128 v[164:167], v236 offset:1024
	ds_read_b128 v[176:179], v236 offset:2048
	ds_read_b128 v[180:183], v236 offset:3072
	ds_read_b128 v[196:199], v236 offset:4096
	ds_read_b128 v[200:203], v236 offset:5120
	ds_read_b128 v[204:207], v236 offset:6144
	ds_read_b128 v[208:211], v236 offset:7168
	global_load_lds_dwordx4 v152, s[2:3]
	s_add_i32 m0, s22, 0xe000
	s_nop 0
	s_add_u32 vcc_lo, s2, s86
	s_addc_u32 vcc_hi, s3, s87
	global_load_lds_dwordx4 v152, vcc
	s_waitcnt lgkmcnt(8)
	s_cmp_eq_u32 s101, 1
	s_cbranch_scc1 .Ldb_MG0_sk
	s_barrier
.Ldb_MG0_sk:
	s_mov_b32 s101, 0
	s_waitcnt lgkmcnt(0)
	v_mfma_f32_16x16x128_f8f6f4 v[128:131], v[144:151], v[160:167], v[128:131]
	v_mfma_f32_16x16x128_f8f6f4 v[132:135], v[136:143], v[160:167], v[132:135]
	v_mfma_f32_16x16x128_f8f6f4 v[112:115], v[144:151], v[176:183], v[112:115]
	v_mfma_f32_16x16x128_f8f6f4 v[116:119], v[136:143], v[176:183], v[116:119]
	v_mfma_f32_16x16x128_f8f6f4 v[96:99], v[144:151], v[196:203], v[96:99]
	v_mfma_f32_16x16x128_f8f6f4 v[100:103], v[136:143], v[196:203], v[100:103]
	v_mfma_f32_16x16x128_f8f6f4 v[80:83], v[144:151], v[204:211], v[80:83]
	v_mfma_f32_16x16x128_f8f6f4 v[84:87], v[136:143], v[204:211], v[84:87]
	s_barrier
	s_add_i32 s4, 0, 0x14000
	s_add_i32 s5, s40, s17
	ds_read_b128 v[212:215], v239 offset:16384
	ds_read_b128 v[216:219], v239 offset:17408
	ds_read_b128 v[220:223], v239 offset:18432
	ds_read_b128 v[224:227], v239 offset:19456
	s_mov_b32 m0, s5
	global_load_lds_dwordx4 v0, s[14:15]
	s_add_i32 m0, s5, 0x2000
	s_nop 0
	s_add_u32 vcc_lo, s14, s50
	s_addc_u32 vcc_hi, s15, s51
	global_load_lds_dwordx4 v0, vcc
	s_barrier
	s_waitcnt lgkmcnt(0)
	v_mfma_f32_16x16x128_f8f6f4 v[124:127], v[212:219], v[160:167], v[124:127]
	v_mfma_f32_16x16x128_f8f6f4 v[120:123], v[220:227], v[160:167], v[120:123]
	v_mfma_f32_16x16x128_f8f6f4 v[108:111], v[212:219], v[176:183], v[108:111]
	v_mfma_f32_16x16x128_f8f6f4 v[104:107], v[220:227], v[176:183], v[104:107]
	v_mfma_f32_16x16x128_f8f6f4 v[92:95], v[212:219], v[196:203], v[92:95]
	v_mfma_f32_16x16x128_f8f6f4 v[88:91], v[220:227], v[196:203], v[88:91]
	v_mfma_f32_16x16x128_f8f6f4 v[76:79], v[212:219], v[204:211], v[76:79]
	v_mfma_f32_16x16x128_f8f6f4 v[72:75], v[220:227], v[204:211], v[72:75]
	s_barrier
	s_mov_b32 m0, s22
	ds_read_b128 v[160:163], v236 offset:16384
	ds_read_b128 v[164:167], v236 offset:17408
	ds_read_b128 v[176:179], v236 offset:18432
	ds_read_b128 v[180:183], v236 offset:19456
	ds_read_b128 v[196:199], v236 offset:20480
	ds_read_b128 v[200:203], v236 offset:21504
	ds_read_b128 v[204:207], v236 offset:22528
	ds_read_b128 v[208:211], v236 offset:23552
	global_load_lds_dwordx4 v2, s[12:13]
	s_mov_b32 m0, s23
	s_nop 0
	s_add_u32 vcc_lo, s12, s86
	s_addc_u32 vcc_hi, s13, s87
	global_load_lds_dwordx4 v2, vcc
	s_barrier
; #define G_STAGE(bufoff, gbase, o0, h64) do { \
;         __builtin_amdgcn_global_load_lds((const unsigned*)((const char*)(gbase) + (o0)), (LAS unsigned*)(lds + (bufoff) + ldsw), 16, 0, 0); \
;         __builtin_amdgcn_global_load_lds((const unsigned*)((const char*)(gbase) + (h64) + (o0)), (LAS unsigned*)(lds + (bufoff) + ldsw + 8192), 16, 0, 0); } while (0)
; #define G_LDA(dst, b, h) do { _Pragma("unroll") for (int m = 0; m < 4; ++m) _Pragma("unroll") for (int k = 0; k < 2; ++k) dst[m][k] = *(const LAS bf16x8*)(lds + G_SA(b, h) + aoff + m * 2048 + k * 1024); } while (0)
; #define G_LDB(dst, b, h) do { _Pragma("unroll") for (int n = 0; n < 2; ++n) _Pragma("unroll") for (int k = 0; k < 2; ++k) dst[n][k] = *(const LAS bf16x8*)(lds + G_SB(b, h) + boff + n * 2048 + k * 1024); } while (0)
; #define G_WAIT_V(n) asm volatile("s_waitcnt vmcnt(" #n ")" ::: "memory")
; #define G_WAIT_L(n) asm volatile("s_waitcnt lgkmcnt(" #n ")" ::: "memory")
; #define G_BAR __builtin_amdgcn_s_barrier()
; #define G_SCHED __builtin_amdgcn_sched_barrier(0)
;     ...
;             G_WAIT_V(6); G_BAR; G_MMA(1, 1, At, B1); G_BAR;
;             G_LDB(B0, 1, 0); G_SCHED; G_LDA(At, 1, 0); G_STAGE(G_SA(0, 1), a2 + chA, cA0, qA);
;             G_WAIT_L(8); G_BAR; G_WAIT_L(0); G_MMA(0, 0, At, B0); G_BAR; G_SCHED;
;             G_LDB(B1, 1, 1); G_STAGE(G_SB(1, 0), b3, cB0, qB);
;             G_BAR; G_WAIT_L(0); G_MMA(0, 1, At, B1); G_BAR;
;             G_LDA(At, 1, 1); G_STAGE(G_SA(1, 0), a3, cA0, qA);
;             G_BAR; G_WAIT_L(0); G_MMA(1, 0, At, B0); G_BAR; G_SCHED;
;             G_STAGE(G_SB(1, 1), b3 + chB, cB0, qB);
;             G_WAIT_V(6); G_BAR; G_MMA(1, 1, At, B1); G_BAR;
;         }
	s_waitcnt lgkmcnt(0)
	v_mfma_f32_16x16x128_f8f6f4 v[64:67], v[144:151], v[160:167], v[64:67]
	v_mfma_f32_16x16x128_f8f6f4 v[68:71], v[136:143], v[160:167], v[68:71]
	v_mfma_f32_16x16x128_f8f6f4 v[48:51], v[144:151], v[176:183], v[48:51]
	v_mfma_f32_16x16x128_f8f6f4 v[52:55], v[136:143], v[176:183], v[52:55]
	v_mfma_f32_16x16x128_f8f6f4 v[32:35], v[144:151], v[196:203], v[32:35]
	v_mfma_f32_16x16x128_f8f6f4 v[36:39], v[136:143], v[196:203], v[36:39]
	v_mfma_f32_16x16x128_f8f6f4 v[20:23], v[144:151], v[204:211], v[20:23]
	v_mfma_f32_16x16x128_f8f6f4 v[16:19], v[136:143], v[204:211], v[16:19]
	s_barrier
	s_add_i32 s4, s4, s17
	s_mov_b32 m0, s4
	s_nop 0
	s_add_u32 vcc_lo, s14, s0
	s_addc_u32 vcc_hi, s15, s1
	global_load_lds_dwordx4 v0, vcc
	s_add_i32 m0, s4, 0x2000
	s_nop 0
	s_add_u32 vcc_lo, s14, s52
	s_addc_u32 vcc_hi, s15, s53
	global_load_lds_dwordx4 v0, vcc
	s_waitcnt vmcnt(6)
	s_barrier
	v_mfma_f32_16x16x128_f8f6f4 v[60:63], v[212:219], v[160:167], v[60:63]
	v_mfma_f32_16x16x128_f8f6f4 v[56:59], v[220:227], v[160:167], v[56:59]
	v_mfma_f32_16x16x128_f8f6f4 v[44:47], v[212:219], v[176:183], v[44:47]
	v_mfma_f32_16x16x128_f8f6f4 v[40:43], v[220:227], v[176:183], v[40:43]
	v_mfma_f32_16x16x128_f8f6f4 v[28:31], v[212:219], v[196:203], v[28:31]
	v_mfma_f32_16x16x128_f8f6f4 v[24:27], v[220:227], v[196:203], v[24:27]
	v_mfma_f32_16x16x128_f8f6f4 v[12:15], v[212:219], v[204:211], v[12:15]
	v_mfma_f32_16x16x128_f8f6f4 v[8:11], v[220:227], v[204:211], v[8:11]
	s_barrier
	s_add_i32 s4, 0, 0x18000
	ds_read_b128 v[144:147], v239 offset:32768
	ds_read_b128 v[148:151], v239 offset:33792
	ds_read_b128 v[136:139], v239 offset:34816
	ds_read_b128 v[140:143], v239 offset:35840
	s_mov_b32 m0, s24
	ds_read_b128 v[160:163], v236 offset:32768
	ds_read_b128 v[164:167], v236 offset:33792
	ds_read_b128 v[176:179], v236 offset:34816
	ds_read_b128 v[180:183], v236 offset:35840
	ds_read_b128 v[196:199], v236 offset:36864
	ds_read_b128 v[200:203], v236 offset:37888
	ds_read_b128 v[204:207], v236 offset:38912
	ds_read_b128 v[208:211], v236 offset:39936
	s_add_u32 vcc_lo, s12, s88
	s_addc_u32 vcc_hi, s13, s89
	global_load_lds_dwordx4 v2, vcc
	s_mov_b32 m0, s25
	s_nop 0
	s_add_u32 vcc_lo, s12, s64
	s_addc_u32 vcc_hi, s13, s65
	global_load_lds_dwordx4 v2, vcc
	s_waitcnt lgkmcnt(8)
	s_barrier
	s_waitcnt lgkmcnt(0)
	v_mfma_f32_16x16x128_f8f6f4 v[128:131], v[144:151], v[160:167], v[128:131]
	v_mfma_f32_16x16x128_f8f6f4 v[132:135], v[136:143], v[160:167], v[132:135]
	v_mfma_f32_16x16x128_f8f6f4 v[112:115], v[144:151], v[176:183], v[112:115]
	v_mfma_f32_16x16x128_f8f6f4 v[116:119], v[136:143], v[176:183], v[116:119]
	v_mfma_f32_16x16x128_f8f6f4 v[96:99], v[144:151], v[196:203], v[96:99]
	v_mfma_f32_16x16x128_f8f6f4 v[100:103], v[136:143], v[196:203], v[100:103]
	v_mfma_f32_16x16x128_f8f6f4 v[80:83], v[144:151], v[204:211], v[80:83]
	v_mfma_f32_16x16x128_f8f6f4 v[84:87], v[136:143], v[204:211], v[84:87]
	s_barrier
	s_add_i32 s5, 0, 0x1c000
	s_add_i32 s4, s4, s17
	s_mov_b32 m0, s4
	ds_read_b128 v[212:215], v239 offset:49152
	ds_read_b128 v[216:219], v239 offset:50176
	ds_read_b128 v[220:223], v239 offset:51200
	ds_read_b128 v[224:227], v239 offset:52224
	s_add_u32 vcc_lo, s14, s46
	s_addc_u32 vcc_hi, s15, s47
	global_load_lds_dwordx4 v0, vcc
	s_add_i32 m0, s4, 0x2000
	s_nop 0
	s_add_u32 vcc_lo, s14, s54
	s_addc_u32 vcc_hi, s15, s55
	global_load_lds_dwordx4 v0, vcc
	s_barrier
	s_waitcnt lgkmcnt(0)
	v_mfma_f32_16x16x128_f8f6f4 v[124:127], v[212:219], v[160:167], v[124:127]
	v_mfma_f32_16x16x128_f8f6f4 v[120:123], v[220:227], v[160:167], v[120:123]
	v_mfma_f32_16x16x128_f8f6f4 v[108:111], v[212:219], v[176:183], v[108:111]
	v_mfma_f32_16x16x128_f8f6f4 v[104:107], v[220:227], v[176:183], v[104:107]
	v_mfma_f32_16x16x128_f8f6f4 v[92:95], v[212:219], v[196:203], v[92:95]
	v_mfma_f32_16x16x128_f8f6f4 v[88:91], v[220:227], v[196:203], v[88:91]
	v_mfma_f32_16x16x128_f8f6f4 v[76:79], v[212:219], v[204:211], v[76:79]
	v_mfma_f32_16x16x128_f8f6f4 v[72:75], v[220:227], v[204:211], v[72:75]
	s_barrier
	s_mov_b32 m0, s26
	ds_read_b128 v[160:163], v236 offset:49152
	ds_read_b128 v[164:167], v236 offset:50176
	ds_read_b128 v[176:179], v236 offset:51200
	ds_read_b128 v[180:183], v236 offset:52224
	ds_read_b128 v[196:199], v236 offset:53248
	ds_read_b128 v[200:203], v236 offset:54272
	ds_read_b128 v[204:207], v236 offset:55296
	ds_read_b128 v[208:211], v236 offset:56320
	s_add_u32 vcc_lo, s12, s46
	s_addc_u32 vcc_hi, s13, s47
	global_load_lds_dwordx4 v2, vcc
	s_mov_b32 m0, s27
	s_nop 0
	s_add_u32 vcc_lo, s12, s66
	s_addc_u32 vcc_hi, s13, s67
	global_load_lds_dwordx4 v2, vcc
	s_barrier
	s_waitcnt lgkmcnt(0)
	v_mfma_f32_16x16x128_f8f6f4 v[64:67], v[144:151], v[160:167], v[64:67]
	v_mfma_f32_16x16x128_f8f6f4 v[68:71], v[136:143], v[160:167], v[68:71]
	v_mfma_f32_16x16x128_f8f6f4 v[48:51], v[144:151], v[176:183], v[48:51]
	v_mfma_f32_16x16x128_f8f6f4 v[52:55], v[136:143], v[176:183], v[52:55]
	v_mfma_f32_16x16x128_f8f6f4 v[32:35], v[144:151], v[196:203], v[32:35]
	v_mfma_f32_16x16x128_f8f6f4 v[36:39], v[136:143], v[196:203], v[36:39]
	v_mfma_f32_16x16x128_f8f6f4 v[20:23], v[144:151], v[204:211], v[20:23]
	v_mfma_f32_16x16x128_f8f6f4 v[16:19], v[136:143], v[204:211], v[16:19]
	s_barrier
	s_add_i32 s4, s5, s17
	s_mov_b32 m0, s4
	s_nop 0
	s_add_u32 vcc_lo, s14, s42
	s_addc_u32 vcc_hi, s15, s43
	global_load_lds_dwordx4 v0, vcc
	s_add_i32 m0, s4, 0x2000
	s_nop 0
	s_add_u32 vcc_lo, s14, s58
	s_addc_u32 vcc_hi, s15, s59
	global_load_lds_dwordx4 v0, vcc
	s_add_i32 s39, s39, 2
	s_add_u32 s2, s2, 0x100
	s_addc_u32 s3, s3, 0
	s_add_u32 s37, s37, 0x100
	s_addc_u32 s38, s38, 0
	s_cmp_gt_u32 s39, 5
	s_waitcnt vmcnt(6)
	s_barrier
	v_mfma_f32_16x16x128_f8f6f4 v[60:63], v[212:219], v[160:167], v[60:63]
	v_mfma_f32_16x16x128_f8f6f4 v[56:59], v[220:227], v[160:167], v[56:59]
	v_mfma_f32_16x16x128_f8f6f4 v[44:47], v[212:219], v[176:183], v[44:47]
	v_mfma_f32_16x16x128_f8f6f4 v[40:43], v[220:227], v[176:183], v[40:43]
	v_mfma_f32_16x16x128_f8f6f4 v[28:31], v[212:219], v[196:203], v[28:31]
	v_mfma_f32_16x16x128_f8f6f4 v[24:27], v[220:227], v[196:203], v[24:27]
	v_mfma_f32_16x16x128_f8f6f4 v[12:15], v[212:219], v[204:211], v[12:15]
	v_mfma_f32_16x16x128_f8f6f4 v[8:11], v[220:227], v[204:211], v[8:11]
	s_cbranch_scc0 .Ldb_MG0_cont
	v_readfirstlane_b32 s101, v186
	s_cmpk_gt_u32 s101, 0xff
	s_cbranch_scc1 .Ldb_MG0_young
	s_barrier
	s_mov_b32 s101, 1
	s_branch .Ldb_MG0_exit

; #define G_STAGE(bufoff, gbase, o0, h64) do { \
;         __builtin_amdgcn_global_load_lds((const unsigned*)((const char*)(gbase) + (o0)), (LAS unsigned*)(lds + (bufoff) + ldsw), 16, 0, 0); \
;         __builtin_amdgcn_global_load_lds((const unsigned*)((const char*)(gbase) + (h64) + (o0)), (LAS unsigned*)(lds + (bufoff) + ldsw + 8192), 16, 0, 0); } while (0)
; #define G_LDA(dst, b, h) do { _Pragma("unroll") for (int m = 0; m < 4; ++m) _Pragma("unroll") for (int k = 0; k < 2; ++k) dst[m][k] = *(const LAS bf16x8*)(lds + G_SA(b, h) + aoff + m * 2048 + k * 1024); } while (0)
; #define G_LDB(dst, b, h) do { _Pragma("unroll") for (int n = 0; n < 2; ++n) _Pragma("unroll") for (int k = 0; k < 2; ++k) dst[n][k] = *(const LAS bf16x8*)(lds + G_SB(b, h) + boff + n * 2048 + k * 1024); } while (0)
; #define G_WAIT_L(n) asm volatile("s_waitcnt lgkmcnt(" #n ")" ::: "memory")
; #define G_BAR __builtin_amdgcn_s_barrier()
; #define G_SCHED __builtin_amdgcn_sched_barrier(0)
;     ...
;     for (;;) {
;         const bool has_next = sched_next<PH, SUB>(E.ws, E.layer, ui + 1, nxt, E.x);
;         if (!has_next) nxt = cur;
;         const char* nA = nxt.A; const char* nB = nxt.B;
; #pragma unroll 1
;         for (int t = 0; t < nt; t += 2) {
;             const bool last = (t == nt - 2);
;             const char* a1 = cA + (size_t)(t + 1) * ckA;
;             const char* a2 = last ? nA : cA + (size_t)(t + 2) * ckA; const char* b2 = last ? nB : cB + (size_t)(t + 2) * kB;
;             const char* a3 = a2 + ckA; const char* b3 = b2 + kB;
;             G_LDB(B0, 0, 0); G_SCHED; G_LDA(At, 0, 0); G_STAGE(G_SA(1, 1), a1 + chA, cA0, qA);
;             G_WAIT_L(8); G_BAR; G_WAIT_L(0); G_MMA(0, 0, At, B0); G_BAR; G_SCHED;
;             G_LDB(B1, 0, 1); G_STAGE(G_SB(0, 0), b2, cB0, qB);
;             G_BAR; G_WAIT_L(0); G_MMA(0, 1, At, B1); G_BAR;
;             G_LDA(At, 0, 1); G_STAGE(G_SA(0, 0), a2, cA0, qA);
;             G_BAR; G_WAIT_L(0); G_MMA(1, 0, At, B0); G_BAR; G_SCHED;
.LBB0_889:
	s_add_u32 s6, s6, 0xb0080
	s_addc_u32 s7, s7, 0
	s_add_u32 s8, s18, 0x100
	s_addc_u32 s9, s19, 0
	s_mov_b32 s18, -2
	s_mov_b64 s[50:51], 0x20080
	s_mov_b64 s[52:53], 0x30000
	s_mov_b64 s[54:55], 0x10080
	s_mov_b64 s[58:59], 0x30080
	s_cmp_eq_u32 s101, 2
	s_cselect_b32 s101, 0, s101
	v_add_u32_e32 v239, 0x10000, v175
.LBB0_890:
	s_add_u32 s4, s6, 0xfff50080
	s_addc_u32 s5, s7, -1
	s_add_i32 s19, 0, 0x10000
	ds_read_b128 v[136:139], v239 offset:0
	ds_read_b128 v[140:143], v239 offset:1024
	ds_read_b128 v[144:147], v239 offset:2048
	ds_read_b128 v[148:151], v239 offset:3072
	s_cmp_eq_u32 s18, 4
	s_cselect_b32 s45, s15, s9
	s_cselect_b32 s44, s14, s8
	s_cselect_b32 s5, s13, s5
	s_cselect_b32 s4, s12, s4
	s_add_i32 m0, s22, 0xc000
	ds_read_b128 v[158:161], v176
	ds_read_b128 v[162:165], v176 offset:1024
	ds_read_b128 v[178:181], v176 offset:2048
	ds_read_b128 v[182:185], v176 offset:3072
	ds_read_b128 v[196:199], v176 offset:4096
	ds_read_b128 v[200:203], v176 offset:5120
	ds_read_b128 v[204:207], v176 offset:6144
	ds_read_b128 v[208:211], v176 offset:7168
	global_load_lds_dwordx4 v156, s[6:7]
	s_add_i32 m0, s22, 0xe000
	s_nop 0
	s_add_u32 vcc_lo, s6, s86
	s_addc_u32 vcc_hi, s7, s87
	global_load_lds_dwordx4 v156, vcc
	s_waitcnt lgkmcnt(8)
	s_cmp_eq_u32 s101, 1
	s_cbranch_scc1 .Ldb_MG1_sk
	s_barrier
.Ldb_MG1_sk:
	s_mov_b32 s101, 0
	s_waitcnt lgkmcnt(0)
	v_mfma_f32_16x16x32_bf16 v[104:107], v[136:139], v[158:161], v[104:107]
	v_mfma_f32_16x16x32_bf16 v[108:111], v[144:147], v[158:161], v[108:111]
	v_mfma_f32_16x16x32_bf16 v[132:135], v[136:139], v[178:181], v[132:135]
	v_mfma_f32_16x16x32_bf16 v[128:131], v[144:147], v[178:181], v[128:131]
	v_mfma_f32_16x16x32_bf16 v[124:127], v[136:139], v[196:199], v[124:127]
	v_mfma_f32_16x16x32_bf16 v[120:123], v[144:147], v[196:199], v[120:123]
	v_mfma_f32_16x16x32_bf16 v[116:119], v[136:139], v[204:207], v[116:119]
	v_mfma_f32_16x16x32_bf16 v[112:115], v[144:147], v[204:207], v[112:115]
	v_mfma_f32_16x16x32_bf16 v[104:107], v[140:143], v[162:165], v[104:107]
	v_mfma_f32_16x16x32_bf16 v[108:111], v[148:151], v[162:165], v[108:111]
	v_mfma_f32_16x16x32_bf16 v[132:135], v[140:143], v[182:185], v[132:135]
	v_mfma_f32_16x16x32_bf16 v[128:131], v[148:151], v[182:185], v[128:131]
	v_mfma_f32_16x16x32_bf16 v[124:127], v[140:143], v[200:203], v[124:127]
	v_mfma_f32_16x16x32_bf16 v[120:123], v[148:151], v[200:203], v[120:123]
	v_mfma_f32_16x16x32_bf16 v[116:119], v[140:143], v[208:211], v[116:119]
	v_mfma_f32_16x16x32_bf16 v[112:115], v[148:151], v[208:211], v[112:115]
	s_barrier
	s_add_i32 s43, 0, 0x14000
	s_add_i32 s19, s19, s21
	v_lshl_add_u64 v[2:3], s[44:45], 0, v[154:155]
	s_mov_b64 vcc, s[44:45]
	s_mov_b64 s[44:45], 0x10000
	s_mov_b32 m0, s19
	ds_read_b128 v[212:215], v239 offset:16384
	ds_read_b128 v[216:219], v239 offset:17408
	ds_read_b128 v[220:223], v239 offset:18432
	ds_read_b128 v[224:227], v239 offset:19456
	global_load_lds_dwordx4 v154, vcc
	v_lshl_add_u64 v[166:167], v[2:3], 0, s[44:45]
	s_add_i32 m0, s19, 0x2000
	s_nop 0
	global_load_lds_dwordx4 v[166:167], off
	s_barrier
	s_waitcnt lgkmcnt(0)
	v_mfma_f32_16x16x32_bf16 v[100:103], v[212:215], v[158:161], v[100:103]
	v_mfma_f32_16x16x32_bf16 v[96:99], v[220:223], v[158:161], v[96:99]
	v_mfma_f32_16x16x32_bf16 v[92:95], v[212:215], v[178:181], v[92:95]
	v_mfma_f32_16x16x32_bf16 v[88:91], v[220:223], v[178:181], v[88:91]
	v_mfma_f32_16x16x32_bf16 v[84:87], v[212:215], v[196:199], v[84:87]
	v_mfma_f32_16x16x32_bf16 v[80:83], v[220:223], v[196:199], v[80:83]
	v_mfma_f32_16x16x32_bf16 v[76:79], v[212:215], v[204:207], v[76:79]
	v_mfma_f32_16x16x32_bf16 v[72:75], v[220:223], v[204:207], v[72:75]
	v_mfma_f32_16x16x32_bf16 v[100:103], v[216:219], v[162:165], v[100:103]
	v_mfma_f32_16x16x32_bf16 v[96:99], v[224:227], v[162:165], v[96:99]
	v_mfma_f32_16x16x32_bf16 v[92:95], v[216:219], v[182:185], v[92:95]
	v_mfma_f32_16x16x32_bf16 v[88:91], v[224:227], v[182:185], v[88:91]
	v_mfma_f32_16x16x32_bf16 v[84:87], v[216:219], v[200:203], v[84:87]
	v_mfma_f32_16x16x32_bf16 v[80:83], v[224:227], v[200:203], v[80:83]
	v_mfma_f32_16x16x32_bf16 v[76:79], v[216:219], v[208:211], v[76:79]
	v_mfma_f32_16x16x32_bf16 v[72:75], v[224:227], v[208:211], v[72:75]
	s_barrier
	s_mov_b32 m0, s22
	v_lshl_add_u64 v[166:167], s[4:5], 0, v[152:153]
	ds_read_b128 v[158:161], v176 offset:16384
	ds_read_b128 v[162:165], v176 offset:17408
	ds_read_b128 v[178:181], v176 offset:18432
	ds_read_b128 v[182:185], v176 offset:19456
	ds_read_b128 v[196:199], v176 offset:20480
	ds_read_b128 v[200:203], v176 offset:21504
	ds_read_b128 v[204:207], v176 offset:22528
	ds_read_b128 v[208:211], v176 offset:23552
	global_load_lds_dwordx4 v152, s[4:5]
	s_mov_b32 m0, s23
	s_nop 0
	s_add_u32 vcc_lo, s4, s86
	s_addc_u32 vcc_hi, s5, s87
	global_load_lds_dwordx4 v152, vcc
	s_barrier
	s_waitcnt lgkmcnt(0)
	v_mfma_f32_16x16x32_bf16 v[68:71], v[136:139], v[158:161], v[68:71]
	v_mfma_f32_16x16x32_bf16 v[64:67], v[144:147], v[158:161], v[64:67]
	v_mfma_f32_16x16x32_bf16 v[60:63], v[136:139], v[178:181], v[60:63]
	v_mfma_f32_16x16x32_bf16 v[56:59], v[144:147], v[178:181], v[56:59]
	v_mfma_f32_16x16x32_bf16 v[52:55], v[136:139], v[196:199], v[52:55]
	v_mfma_f32_16x16x32_bf16 v[48:51], v[144:147], v[196:199], v[48:51]
	v_mfma_f32_16x16x32_bf16 v[44:47], v[136:139], v[204:207], v[44:47]
	v_mfma_f32_16x16x32_bf16 v[40:43], v[144:147], v[204:207], v[40:43]
	v_mfma_f32_16x16x32_bf16 v[68:71], v[140:143], v[162:165], v[68:71]
	v_mfma_f32_16x16x32_bf16 v[64:67], v[148:151], v[162:165], v[64:67]
	v_mfma_f32_16x16x32_bf16 v[60:63], v[140:143], v[182:185], v[60:63]
	v_mfma_f32_16x16x32_bf16 v[56:59], v[148:151], v[182:185], v[56:59]
	v_mfma_f32_16x16x32_bf16 v[52:55], v[140:143], v[200:203], v[52:55]
	v_mfma_f32_16x16x32_bf16 v[48:51], v[148:151], v[200:203], v[48:51]
	v_mfma_f32_16x16x32_bf16 v[44:47], v[140:143], v[208:211], v[44:47]
	v_mfma_f32_16x16x32_bf16 v[40:43], v[148:151], v[208:211], v[40:43]
	s_barrier
; #define G_STAGE(bufoff, gbase, o0, h64) do { \
;         __builtin_amdgcn_global_load_lds((const unsigned*)((const char*)(gbase) + (o0)), (LAS unsigned*)(lds + (bufoff) + ldsw), 16, 0, 0); \
;         __builtin_amdgcn_global_load_lds((const unsigned*)((const char*)(gbase) + (h64) + (o0)), (LAS unsigned*)(lds + (bufoff) + ldsw + 8192), 16, 0, 0); } while (0)
; #define G_LDA(dst, b, h) do { _Pragma("unroll") for (int m = 0; m < 4; ++m) _Pragma("unroll") for (int k = 0; k < 2; ++k) dst[m][k] = *(const LAS bf16x8*)(lds + G_SA(b, h) + aoff + m * 2048 + k * 1024); } while (0)
; #define G_LDB(dst, b, h) do { _Pragma("unroll") for (int n = 0; n < 2; ++n) _Pragma("unroll") for (int k = 0; k < 2; ++k) dst[n][k] = *(const LAS bf16x8*)(lds + G_SB(b, h) + boff + n * 2048 + k * 1024); } while (0)
; #define G_WAIT_V(n) asm volatile("s_waitcnt vmcnt(" #n ")" ::: "memory")
; #define G_WAIT_L(n) asm volatile("s_waitcnt lgkmcnt(" #n ")" ::: "memory")
; #define G_BAR __builtin_amdgcn_s_barrier()
; #define G_SCHED __builtin_amdgcn_sched_barrier(0)
;     ...
;             G_BAR; G_WAIT_L(0); G_MMA(1, 0, At, B0); G_BAR; G_SCHED;
;             G_STAGE(G_SB(0, 1), b2 + chB, cB0, qB);
;             G_WAIT_V(6); G_BAR; G_MMA(1, 1, At, B1); G_BAR;
;             G_LDB(B0, 1, 0); G_SCHED; G_LDA(At, 1, 0); G_STAGE(G_SA(0, 1), a2 + chA, cA0, qA);
;             G_WAIT_L(8); G_BAR; G_WAIT_L(0); G_MMA(0, 0, At, B0); G_BAR; G_SCHED;
;             G_LDB(B1, 1, 1); G_STAGE(G_SB(1, 0), b3, cB0, qB);
;             G_BAR; G_WAIT_L(0); G_MMA(0, 1, At, B1); G_BAR;
;             G_LDA(At, 1, 1); G_STAGE(G_SA(1, 0), a3, cA0, qA);
;             G_BAR; G_WAIT_L(0); G_MMA(1, 0, At, B0); G_BAR; G_SCHED;
	s_add_i32 s4, s43, s21
	v_lshl_add_u64 v[136:137], v[2:3], 0, s[0:1]
	s_mov_b32 m0, s4
	s_nop 0
	global_load_lds_dwordx4 v[136:137], off
	v_lshl_add_u64 v[136:137], v[2:3], 0, s[52:53]
	s_add_i32 m0, s4, 0x2000
	s_nop 0
	global_load_lds_dwordx4 v[136:137], off
	s_waitcnt vmcnt(6)
	s_barrier
	v_mfma_f32_16x16x32_bf16 v[36:39], v[212:215], v[158:161], v[36:39]
	v_mfma_f32_16x16x32_bf16 v[32:35], v[220:223], v[158:161], v[32:35]
	v_mfma_f32_16x16x32_bf16 v[28:31], v[212:215], v[178:181], v[28:31]
	v_mfma_f32_16x16x32_bf16 v[24:27], v[220:223], v[178:181], v[24:27]
	v_mfma_f32_16x16x32_bf16 v[20:23], v[212:215], v[196:199], v[20:23]
	v_mfma_f32_16x16x32_bf16 v[16:19], v[220:223], v[196:199], v[16:19]
	v_mfma_f32_16x16x32_bf16 v[12:15], v[212:215], v[204:207], v[12:15]
	v_mfma_f32_16x16x32_bf16 v[8:11], v[220:223], v[204:207], v[8:11]
	v_mfma_f32_16x16x32_bf16 v[36:39], v[216:219], v[162:165], v[36:39]
	v_mfma_f32_16x16x32_bf16 v[32:35], v[224:227], v[162:165], v[32:35]
	v_mfma_f32_16x16x32_bf16 v[28:31], v[216:219], v[182:185], v[28:31]
	v_mfma_f32_16x16x32_bf16 v[24:27], v[224:227], v[182:185], v[24:27]
	v_mfma_f32_16x16x32_bf16 v[20:23], v[216:219], v[200:203], v[20:23]
	v_mfma_f32_16x16x32_bf16 v[16:19], v[224:227], v[200:203], v[16:19]
	v_mfma_f32_16x16x32_bf16 v[12:15], v[216:219], v[208:211], v[12:15]
	v_mfma_f32_16x16x32_bf16 v[8:11], v[224:227], v[208:211], v[8:11]
	s_barrier
	s_add_i32 s4, 0, 0x18000
	ds_read_b128 v[136:139], v239 offset:32768
	ds_read_b128 v[140:143], v239 offset:33792
	ds_read_b128 v[144:147], v239 offset:34816
	ds_read_b128 v[148:151], v239 offset:35840
	s_mov_b32 m0, s24
	v_lshl_add_u64 v[172:173], v[166:167], 0, s[88:89]
	ds_read_b128 v[158:161], v176 offset:32768
	ds_read_b128 v[162:165], v176 offset:33792
	ds_read_b128 v[178:181], v176 offset:34816
	ds_read_b128 v[182:185], v176 offset:35840
	ds_read_b128 v[196:199], v176 offset:36864
	ds_read_b128 v[200:203], v176 offset:37888
	ds_read_b128 v[204:207], v176 offset:38912
	ds_read_b128 v[208:211], v176 offset:39936
	global_load_lds_dwordx4 v[172:173], off
	v_lshl_add_u64 v[172:173], v[166:167], 0, s[64:65]
	s_mov_b32 m0, s25
	s_nop 0
	global_load_lds_dwordx4 v[172:173], off
	s_waitcnt lgkmcnt(8)
	s_barrier
	s_waitcnt lgkmcnt(0)
	v_mfma_f32_16x16x32_bf16 v[104:107], v[136:139], v[158:161], v[104:107]
	v_mfma_f32_16x16x32_bf16 v[108:111], v[144:147], v[158:161], v[108:111]
	v_mfma_f32_16x16x32_bf16 v[132:135], v[136:139], v[178:181], v[132:135]
	v_mfma_f32_16x16x32_bf16 v[128:131], v[144:147], v[178:181], v[128:131]
	v_mfma_f32_16x16x32_bf16 v[124:127], v[136:139], v[196:199], v[124:127]
	v_mfma_f32_16x16x32_bf16 v[120:123], v[144:147], v[196:199], v[120:123]
	v_mfma_f32_16x16x32_bf16 v[116:119], v[136:139], v[204:207], v[116:119]
	v_mfma_f32_16x16x32_bf16 v[112:115], v[144:147], v[204:207], v[112:115]
	v_mfma_f32_16x16x32_bf16 v[104:107], v[140:143], v[162:165], v[104:107]
	v_mfma_f32_16x16x32_bf16 v[108:111], v[148:151], v[162:165], v[108:111]
	v_mfma_f32_16x16x32_bf16 v[132:135], v[140:143], v[182:185], v[132:135]
	v_mfma_f32_16x16x32_bf16 v[128:131], v[148:151], v[182:185], v[128:131]
	v_mfma_f32_16x16x32_bf16 v[124:127], v[140:143], v[200:203], v[124:127]
	v_mfma_f32_16x16x32_bf16 v[120:123], v[148:151], v[200:203], v[120:123]
	v_mfma_f32_16x16x32_bf16 v[116:119], v[140:143], v[208:211], v[116:119]
	v_mfma_f32_16x16x32_bf16 v[112:115], v[148:151], v[208:211], v[112:115]
	s_barrier
	s_add_i32 s5, 0, 0x1c000
	s_add_i32 s4, s4, s21
	v_lshl_add_u64 v[172:173], v[2:3], 0, s[46:47]
	s_mov_b32 m0, s4
	ds_read_b128 v[212:215], v239 offset:49152
	ds_read_b128 v[216:219], v239 offset:50176
	ds_read_b128 v[220:223], v239 offset:51200
	ds_read_b128 v[224:227], v239 offset:52224
	global_load_lds_dwordx4 v[172:173], off
	v_lshl_add_u64 v[172:173], v[2:3], 0, s[54:55]
	s_add_i32 m0, s4, 0x2000
	s_nop 0
	global_load_lds_dwordx4 v[172:173], off
	s_barrier
; #define G_STAGE(bufoff, gbase, o0, h64) do { \
;         __builtin_amdgcn_global_load_lds((const unsigned*)((const char*)(gbase) + (o0)), (LAS unsigned*)(lds + (bufoff) + ldsw), 16, 0, 0); \
;         __builtin_amdgcn_global_load_lds((const unsigned*)((const char*)(gbase) + (h64) + (o0)), (LAS unsigned*)(lds + (bufoff) + ldsw + 8192), 16, 0, 0); } while (0)
; #define G_LDA(dst, b, h) do { _Pragma("unroll") for (int m = 0; m < 4; ++m) _Pragma("unroll") for (int k = 0; k < 2; ++k) dst[m][k] = *(const LAS bf16x8*)(lds + G_SA(b, h) + aoff + m * 2048 + k * 1024); } while (0)
; #define G_WAIT_V(n) asm volatile("s_waitcnt vmcnt(" #n ")" ::: "memory")
; #define G_WAIT_L(n) asm volatile("s_waitcnt lgkmcnt(" #n ")" ::: "memory")
; #define G_BAR __builtin_amdgcn_s_barrier()
; #define G_SCHED __builtin_amdgcn_sched_barrier(0)
;     ...
;             G_BAR; G_WAIT_L(0); G_MMA(0, 1, At, B1); G_BAR;
;             G_LDA(At, 1, 1); G_STAGE(G_SA(1, 0), a3, cA0, qA);
;             G_BAR; G_WAIT_L(0); G_MMA(1, 0, At, B0); G_BAR; G_SCHED;
;             G_STAGE(G_SB(1, 1), b3 + chB, cB0, qB);
;             G_WAIT_V(6); G_BAR; G_MMA(1, 1, At, B1); G_BAR;
;         }
	s_waitcnt lgkmcnt(0)
	v_mfma_f32_16x16x32_bf16 v[100:103], v[212:215], v[158:161], v[100:103]
	v_mfma_f32_16x16x32_bf16 v[96:99], v[220:223], v[158:161], v[96:99]
	v_mfma_f32_16x16x32_bf16 v[92:95], v[212:215], v[178:181], v[92:95]
	v_mfma_f32_16x16x32_bf16 v[88:91], v[220:223], v[178:181], v[88:91]
	v_mfma_f32_16x16x32_bf16 v[84:87], v[212:215], v[196:199], v[84:87]
	v_mfma_f32_16x16x32_bf16 v[80:83], v[220:223], v[196:199], v[80:83]
	v_mfma_f32_16x16x32_bf16 v[76:79], v[212:215], v[204:207], v[76:79]
	v_mfma_f32_16x16x32_bf16 v[72:75], v[220:223], v[204:207], v[72:75]
	v_mfma_f32_16x16x32_bf16 v[100:103], v[216:219], v[162:165], v[100:103]
	v_mfma_f32_16x16x32_bf16 v[96:99], v[224:227], v[162:165], v[96:99]
	v_mfma_f32_16x16x32_bf16 v[92:95], v[216:219], v[182:185], v[92:95]
	v_mfma_f32_16x16x32_bf16 v[88:91], v[224:227], v[182:185], v[88:91]
	v_mfma_f32_16x16x32_bf16 v[84:87], v[216:219], v[200:203], v[84:87]
	v_mfma_f32_16x16x32_bf16 v[80:83], v[224:227], v[200:203], v[80:83]
	v_mfma_f32_16x16x32_bf16 v[76:79], v[216:219], v[208:211], v[76:79]
	v_mfma_f32_16x16x32_bf16 v[72:75], v[224:227], v[208:211], v[72:75]
	s_barrier
	s_mov_b32 m0, s26
	v_lshl_add_u64 v[172:173], v[166:167], 0, s[46:47]
	ds_read_b128 v[158:161], v176 offset:49152
	ds_read_b128 v[162:165], v176 offset:50176
	ds_read_b128 v[178:181], v176 offset:51200
	ds_read_b128 v[182:185], v176 offset:52224
	ds_read_b128 v[196:199], v176 offset:53248
	ds_read_b128 v[200:203], v176 offset:54272
	ds_read_b128 v[204:207], v176 offset:55296
	ds_read_b128 v[208:211], v176 offset:56320
	global_load_lds_dwordx4 v[172:173], off
	v_lshl_add_u64 v[166:167], v[166:167], 0, s[66:67]
	s_mov_b32 m0, s27
	s_nop 0
	global_load_lds_dwordx4 v[166:167], off
	s_barrier
	s_waitcnt lgkmcnt(0)
	v_mfma_f32_16x16x32_bf16 v[68:71], v[136:139], v[158:161], v[68:71]
	v_mfma_f32_16x16x32_bf16 v[64:67], v[144:147], v[158:161], v[64:67]
	v_mfma_f32_16x16x32_bf16 v[60:63], v[136:139], v[178:181], v[60:63]
	v_mfma_f32_16x16x32_bf16 v[56:59], v[144:147], v[178:181], v[56:59]
	v_mfma_f32_16x16x32_bf16 v[52:55], v[136:139], v[196:199], v[52:55]
	v_mfma_f32_16x16x32_bf16 v[48:51], v[144:147], v[196:199], v[48:51]
	v_mfma_f32_16x16x32_bf16 v[44:47], v[136:139], v[204:207], v[44:47]
	v_mfma_f32_16x16x32_bf16 v[40:43], v[144:147], v[204:207], v[40:43]
	v_mfma_f32_16x16x32_bf16 v[68:71], v[140:143], v[162:165], v[68:71]
	v_mfma_f32_16x16x32_bf16 v[64:67], v[148:151], v[162:165], v[64:67]
	v_mfma_f32_16x16x32_bf16 v[60:63], v[140:143], v[182:185], v[60:63]
	v_mfma_f32_16x16x32_bf16 v[56:59], v[148:151], v[182:185], v[56:59]
	v_mfma_f32_16x16x32_bf16 v[52:55], v[140:143], v[200:203], v[52:55]
	v_mfma_f32_16x16x32_bf16 v[48:51], v[148:151], v[200:203], v[48:51]
	v_mfma_f32_16x16x32_bf16 v[44:47], v[140:143], v[208:211], v[44:47]
	v_mfma_f32_16x16x32_bf16 v[40:43], v[148:151], v[208:211], v[40:43]
	s_barrier
	s_add_i32 s4, s5, s21
	v_lshl_add_u64 v[136:137], v[2:3], 0, s[50:51]
	s_mov_b32 m0, s4
	v_lshl_add_u64 v[2:3], v[2:3], 0, s[58:59]
	global_load_lds_dwordx4 v[136:137], off
	s_add_i32 m0, s4, 0x2000
	s_nop 0
	global_load_lds_dwordx4 v[2:3], off
	s_add_i32 s18, s18, 2
	s_add_u32 s6, s6, 0x100
	s_addc_u32 s7, s7, 0
	s_add_u32 s8, s8, 0x100
	s_addc_u32 s9, s9, 0
	s_cmp_gt_u32 s18, 5
	s_waitcnt vmcnt(6)
	s_barrier
	v_mfma_f32_16x16x32_bf16 v[36:39], v[212:215], v[158:161], v[36:39]
	v_mfma_f32_16x16x32_bf16 v[32:35], v[220:223], v[158:161], v[32:35]
	v_mfma_f32_16x16x32_bf16 v[28:31], v[212:215], v[178:181], v[28:31]
	v_mfma_f32_16x16x32_bf16 v[24:27], v[220:223], v[178:181], v[24:27]
	v_mfma_f32_16x16x32_bf16 v[20:23], v[212:215], v[196:199], v[20:23]
	v_mfma_f32_16x16x32_bf16 v[16:19], v[220:223], v[196:199], v[16:19]
	v_mfma_f32_16x16x32_bf16 v[12:15], v[212:215], v[204:207], v[12:15]
	v_mfma_f32_16x16x32_bf16 v[8:11], v[220:223], v[204:207], v[8:11]
	v_mfma_f32_16x16x32_bf16 v[36:39], v[216:219], v[162:165], v[36:39]
	v_mfma_f32_16x16x32_bf16 v[32:35], v[224:227], v[162:165], v[32:35]
	v_mfma_f32_16x16x32_bf16 v[28:31], v[216:219], v[182:185], v[28:31]
	v_mfma_f32_16x16x32_bf16 v[24:27], v[224:227], v[182:185], v[24:27]
	v_mfma_f32_16x16x32_bf16 v[20:23], v[216:219], v[200:203], v[20:23]
	v_mfma_f32_16x16x32_bf16 v[16:19], v[224:227], v[200:203], v[16:19]
	v_mfma_f32_16x16x32_bf16 v[12:15], v[216:219], v[208:211], v[12:15]
	v_mfma_f32_16x16x32_bf16 v[8:11], v[224:227], v[208:211], v[8:11]
	s_cbranch_scc0 .Ldb_MG1_cont
	v_readfirstlane_b32 s101, v186
	s_cmpk_gt_u32 s101, 0xff
	s_cbranch_scc1 .Ldb_MG1_young
	s_barrier
	s_mov_b32 s101, 1
	s_branch .Ldb_MG1_exit

; #define G_STAGE(bufoff, gbase, o0, h64) do { \
;         __builtin_amdgcn_global_load_lds((const unsigned*)((const char*)(gbase) + (o0)), (LAS unsigned*)(lds + (bufoff) + ldsw), 16, 0, 0); \
;         __builtin_amdgcn_global_load_lds((const unsigned*)((const char*)(gbase) + (h64) + (o0)), (LAS unsigned*)(lds + (bufoff) + ldsw + 8192), 16, 0, 0); } while (0)
; #define G_LDA(dst, b, h) do { _Pragma("unroll") for (int m = 0; m < 4; ++m) _Pragma("unroll") for (int k = 0; k < 2; ++k) dst[m][k] = *(const LAS bf16x8*)(lds + G_SA(b, h) + aoff + m * 2048 + k * 1024); } while (0)
; #define G_LDB(dst, b, h) do { _Pragma("unroll") for (int n = 0; n < 2; ++n) _Pragma("unroll") for (int k = 0; k < 2; ++k) dst[n][k] = *(const LAS bf16x8*)(lds + G_SB(b, h) + boff + n * 2048 + k * 1024); } while (0)
; #define G_WAIT_L(n) asm volatile("s_waitcnt lgkmcnt(" #n ")" ::: "memory")
; #define G_BAR __builtin_amdgcn_s_barrier()
; #define G_SCHED __builtin_amdgcn_sched_barrier(0)
;     ...
;     for (;;) {
;         const bool has_next = sched_next<PH, SUB>(E.ws, E.layer, ui + 1, nxt, E.x);
;         if (!has_next) nxt = cur;
;         const char* nA = nxt.A; const char* nB = nxt.B;
; #pragma unroll 1
;         for (int t = 0; t < nt; t += 2) {
;             const bool last = (t == nt - 2);
;             const char* a1 = cA + (size_t)(t + 1) * ckA;
;             const char* a2 = last ? nA : cA + (size_t)(t + 2) * ckA; const char* b2 = last ? nB : cB + (size_t)(t + 2) * kB;
;             const char* a3 = a2 + ckA; const char* b3 = b2 + kB;
;             G_LDB(B0, 0, 0); G_SCHED; G_LDA(At, 0, 0); G_STAGE(G_SA(1, 1), a1 + chA, cA0, qA);
;             G_WAIT_L(8); G_BAR; G_WAIT_L(0); G_MMA(0, 0, At, B0); G_BAR; G_SCHED;
;             G_LDB(B1, 0, 1); G_STAGE(G_SB(0, 0), b2, cB0, qB);
;             G_BAR; G_WAIT_L(0); G_MMA(0, 1, At, B1); G_BAR;
;     ...
; #pragma unroll
;         for (int a = 0; a < 2; ++a)
; #pragma unroll
;             for (int b = 0; b < 2; ++b)
; #pragma unroll
;                 for (int m = 0; m < 4; ++m)
; #pragma unroll
;                     for (int n = 0; n < 2; ++n) acc[a][b][m][n] = (f32x4){0.f, 0.f, 0.f, 0.f};
;         cur = nxt; cA = nA; cB = nB; ++ui;
.LBB0_1036:
	s_add_u32 s2, s2, 0x40080
	s_addc_u32 s3, s3, 0
	s_add_u32 s6, s6, 0x100
	s_waitcnt lgkmcnt(0)
	v_mov_b64_e32 v[8:9], 0
	s_addc_u32 s7, s7, 0
	s_mov_b32 s15, -2
	v_mov_b64_e32 v[10:11], 0
	v_mov_b64_e32 v[12:13], 0
	v_mov_b64_e32 v[14:15], 0
	v_mov_b64_e32 v[24:25], 0
	v_mov_b64_e32 v[26:27], 0
	v_mov_b64_e32 v[28:29], 0
	v_mov_b64_e32 v[30:31], 0
	v_mov_b64_e32 v[40:41], 0
	v_mov_b64_e32 v[42:43], 0
	v_mov_b64_e32 v[44:45], 0
	v_mov_b64_e32 v[46:47], 0
	v_mov_b64_e32 v[56:57], 0
	v_mov_b64_e32 v[58:59], 0
	v_mov_b64_e32 v[60:61], 0
	v_mov_b64_e32 v[62:63], 0
	v_mov_b64_e32 v[16:17], 0
	v_mov_b64_e32 v[18:19], 0
	v_mov_b64_e32 v[20:21], 0
	v_mov_b64_e32 v[22:23], 0
	v_mov_b64_e32 v[32:33], 0
	v_mov_b64_e32 v[34:35], 0
	v_mov_b64_e32 v[36:37], 0
	v_mov_b64_e32 v[38:39], 0
	v_mov_b64_e32 v[48:49], 0
	v_mov_b64_e32 v[50:51], 0
	v_mov_b64_e32 v[52:53], 0
	v_mov_b64_e32 v[54:55], 0
	v_mov_b64_e32 v[64:65], 0
	v_mov_b64_e32 v[66:67], 0
	v_mov_b64_e32 v[68:69], 0
	v_mov_b64_e32 v[70:71], 0
	v_mov_b64_e32 v[72:73], 0
	v_mov_b64_e32 v[74:75], 0
	v_mov_b64_e32 v[76:77], 0
	v_mov_b64_e32 v[78:79], 0
	v_mov_b64_e32 v[88:89], 0
	v_mov_b64_e32 v[90:91], 0
	v_mov_b64_e32 v[92:93], 0
	v_mov_b64_e32 v[94:95], 0
	v_mov_b64_e32 v[104:105], 0
	v_mov_b64_e32 v[106:107], 0
	v_mov_b64_e32 v[108:109], 0
	v_mov_b64_e32 v[110:111], 0
	v_mov_b64_e32 v[120:121], 0
	v_mov_b64_e32 v[122:123], 0
	v_mov_b64_e32 v[124:125], 0
	v_mov_b64_e32 v[126:127], 0
	v_mov_b64_e32 v[80:81], 0
	v_mov_b64_e32 v[82:83], 0
	v_mov_b64_e32 v[84:85], 0
	v_mov_b64_e32 v[86:87], 0
	v_mov_b64_e32 v[96:97], 0
	v_mov_b64_e32 v[98:99], 0
	v_mov_b64_e32 v[100:101], 0
	v_mov_b64_e32 v[102:103], 0
	v_mov_b64_e32 v[112:113], 0
	v_mov_b64_e32 v[114:115], 0
	v_mov_b64_e32 v[116:117], 0
	v_mov_b64_e32 v[118:119], 0
	v_mov_b64_e32 v[128:129], 0
	v_mov_b64_e32 v[130:131], 0
	v_mov_b64_e32 v[132:133], 0
	v_mov_b64_e32 v[134:135], 0
	s_mov_b64 s[42:43], 0x40000
	s_mov_b64 s[50:51], 0x60000
	s_mov_b64 s[52:53], 0x20080
	s_mov_b64 s[54:55], 0x40080
	s_mov_b64 s[58:59], 0x60080
	s_cmp_eq_u32 s101, 2
	s_cselect_b32 s101, 0, s101
	v_add_u32_e32 v255, 0x10000, v181
.LBB0_1037:
	s_add_u32 s4, s2, 0xfffc0080
	s_addc_u32 s5, s3, -1
	s_add_i32 s33, 0, 0x10000
	ds_read_b128 v[136:139], v255 offset:0
	ds_read_b128 v[140:143], v255 offset:1024
	ds_read_b128 v[144:147], v255 offset:2048
	ds_read_b128 v[148:151], v255 offset:3072
	s_cmp_eq_u32 s15, 12
	s_cselect_b32 s5, s17, s5
	s_cselect_b32 s4, s16, s4
	s_cselect_b32 s21, s19, s7
	s_cselect_b32 s20, s18, s6
	s_add_i32 m0, s24, 0xc000
	ds_read_b128 v[152:155], v182
	ds_read_b128 v[156:159], v182 offset:1024
	ds_read_b128 v[160:163], v182 offset:2048
	ds_read_b128 v[172:175], v182 offset:3072
	ds_read_b128 v[176:179], v182 offset:4096
	ds_read_b128 v[196:199], v182 offset:5120
	ds_read_b128 v[200:203], v182 offset:6144
	ds_read_b128 v[204:207], v182 offset:7168
	global_load_lds_dwordx4 v166, s[2:3]
	s_add_i32 m0, s24, 0xe000
	s_nop 0
	s_add_u32 vcc_lo, s2, s0
	s_addc_u32 vcc_hi, s3, s1
	global_load_lds_dwordx4 v166, vcc
	s_waitcnt lgkmcnt(8)
	s_cmp_eq_u32 s101, 1
	s_cbranch_scc1 .Ldb_WOUT_sk
	s_barrier
.Ldb_WOUT_sk:
	s_mov_b32 s101, 0
	s_waitcnt lgkmcnt(0)
	v_mfma_f32_16x16x32_bf16 v[132:135], v[136:139], v[152:155], v[132:135]
	v_mfma_f32_16x16x32_bf16 v[128:131], v[144:147], v[152:155], v[128:131]
	v_mfma_f32_16x16x32_bf16 v[116:119], v[136:139], v[160:163], v[116:119]
	v_mfma_f32_16x16x32_bf16 v[112:115], v[144:147], v[160:163], v[112:115]
	v_mfma_f32_16x16x32_bf16 v[100:103], v[136:139], v[176:179], v[100:103]
	v_mfma_f32_16x16x32_bf16 v[96:99], v[144:147], v[176:179], v[96:99]
	v_mfma_f32_16x16x32_bf16 v[84:87], v[136:139], v[200:203], v[84:87]
	v_mfma_f32_16x16x32_bf16 v[80:83], v[144:147], v[200:203], v[80:83]
	v_mfma_f32_16x16x32_bf16 v[132:135], v[140:143], v[156:159], v[132:135]
	v_mfma_f32_16x16x32_bf16 v[128:131], v[148:151], v[156:159], v[128:131]
	v_mfma_f32_16x16x32_bf16 v[116:119], v[140:143], v[172:175], v[116:119]
	v_mfma_f32_16x16x32_bf16 v[112:115], v[148:151], v[172:175], v[112:115]
	v_mfma_f32_16x16x32_bf16 v[100:103], v[140:143], v[196:199], v[100:103]
	v_mfma_f32_16x16x32_bf16 v[96:99], v[148:151], v[196:199], v[96:99]
	v_mfma_f32_16x16x32_bf16 v[84:87], v[140:143], v[204:207], v[84:87]
	v_mfma_f32_16x16x32_bf16 v[80:83], v[148:151], v[204:207], v[80:83]
	s_barrier
	s_add_i32 s41, 0, 0x14000
	s_add_i32 s100, s33, s23
	s_mov_b32 m0, s100
	ds_read_b128 v[208:211], v255 offset:16384
	ds_read_b128 v[212:215], v255 offset:17408
	ds_read_b128 v[216:219], v255 offset:18432
	ds_read_b128 v[220:223], v255 offset:19456
	global_load_lds_dwordx4 v164, s[20:21]
	s_add_i32 m0, s100, 0x2000
	s_nop 0
	s_add_u32 vcc_lo, s20, s0
	s_addc_u32 vcc_hi, s21, s1
	global_load_lds_dwordx4 v164, vcc
	s_barrier
	s_waitcnt lgkmcnt(0)
	v_mfma_f32_16x16x32_bf16 v[124:127], v[208:211], v[152:155], v[124:127]
	v_mfma_f32_16x16x32_bf16 v[120:123], v[216:219], v[152:155], v[120:123]
	v_mfma_f32_16x16x32_bf16 v[108:111], v[208:211], v[160:163], v[108:111]
	v_mfma_f32_16x16x32_bf16 v[104:107], v[216:219], v[160:163], v[104:107]
	v_mfma_f32_16x16x32_bf16 v[92:95], v[208:211], v[176:179], v[92:95]
	v_mfma_f32_16x16x32_bf16 v[88:91], v[216:219], v[176:179], v[88:91]
	v_mfma_f32_16x16x32_bf16 v[76:79], v[208:211], v[200:203], v[76:79]
	v_mfma_f32_16x16x32_bf16 v[72:75], v[216:219], v[200:203], v[72:75]
	v_mfma_f32_16x16x32_bf16 v[124:127], v[212:215], v[156:159], v[124:127]
	v_mfma_f32_16x16x32_bf16 v[120:123], v[220:223], v[156:159], v[120:123]
	v_mfma_f32_16x16x32_bf16 v[108:111], v[212:215], v[172:175], v[108:111]
	v_mfma_f32_16x16x32_bf16 v[104:107], v[220:223], v[172:175], v[104:107]
	v_mfma_f32_16x16x32_bf16 v[92:95], v[212:215], v[196:199], v[92:95]
	v_mfma_f32_16x16x32_bf16 v[88:91], v[220:223], v[196:199], v[88:91]
	v_mfma_f32_16x16x32_bf16 v[76:79], v[212:215], v[204:207], v[76:79]
	v_mfma_f32_16x16x32_bf16 v[72:75], v[220:223], v[204:207], v[72:75]
	s_barrier
; #define G_STAGE(bufoff, gbase, o0, h64) do { \
;         __builtin_amdgcn_global_load_lds((const unsigned*)((const char*)(gbase) + (o0)), (LAS unsigned*)(lds + (bufoff) + ldsw), 16, 0, 0); \
;         __builtin_amdgcn_global_load_lds((const unsigned*)((const char*)(gbase) + (h64) + (o0)), (LAS unsigned*)(lds + (bufoff) + ldsw + 8192), 16, 0, 0); } while (0)
; #define G_LDA(dst, b, h) do { _Pragma("unroll") for (int m = 0; m < 4; ++m) _Pragma("unroll") for (int k = 0; k < 2; ++k) dst[m][k] = *(const LAS bf16x8*)(lds + G_SA(b, h) + aoff + m * 2048 + k * 1024); } while (0)
; #define G_LDB(dst, b, h) do { _Pragma("unroll") for (int n = 0; n < 2; ++n) _Pragma("unroll") for (int k = 0; k < 2; ++k) dst[n][k] = *(const LAS bf16x8*)(lds + G_SB(b, h) + boff + n * 2048 + k * 1024); } while (0)
; #define G_WAIT_V(n) asm volatile("s_waitcnt vmcnt(" #n ")" ::: "memory")
; #define G_WAIT_L(n) asm volatile("s_waitcnt lgkmcnt(" #n ")" ::: "memory")
; #define G_BAR __builtin_amdgcn_s_barrier()
; #define G_SCHED __builtin_amdgcn_sched_barrier(0)
;     ...
;             G_LDB(B1, 0, 1); G_STAGE(G_SB(0, 0), b2, cB0, qB);
;             G_BAR; G_WAIT_L(0); G_MMA(0, 1, At, B1); G_BAR;
;             G_LDA(At, 0, 1); G_STAGE(G_SA(0, 0), a2, cA0, qA);
;             G_BAR; G_WAIT_L(0); G_MMA(1, 0, At, B0); G_BAR; G_SCHED;
;             G_STAGE(G_SB(0, 1), b2 + chB, cB0, qB);
;             G_WAIT_V(6); G_BAR; G_MMA(1, 1, At, B1); G_BAR;
;             G_LDB(B0, 1, 0); G_SCHED; G_LDA(At, 1, 0); G_STAGE(G_SA(0, 1), a2 + chA, cA0, qA);
;             G_WAIT_L(8); G_BAR; G_WAIT_L(0); G_MMA(0, 0, At, B0); G_BAR; G_SCHED;
;             G_LDB(B1, 1, 1); G_STAGE(G_SB(1, 0), b3, cB0, qB);
	s_mov_b32 m0, s24
	v_lshl_add_u64 v[224:225], s[4:5], 0, v[2:3]
	ds_read_b128 v[152:155], v182 offset:16384
	ds_read_b128 v[156:159], v182 offset:17408
	ds_read_b128 v[160:163], v182 offset:18432
	ds_read_b128 v[172:175], v182 offset:19456
	ds_read_b128 v[176:179], v182 offset:20480
	ds_read_b128 v[196:199], v182 offset:21504
	ds_read_b128 v[200:203], v182 offset:22528
	ds_read_b128 v[204:207], v182 offset:23552
	global_load_lds_dwordx4 v2, s[4:5]
	s_mov_b32 m0, s25
	s_nop 0
	s_add_u32 vcc_lo, s4, s0
	s_addc_u32 vcc_hi, s5, s1
	global_load_lds_dwordx4 v2, vcc
	s_barrier
	s_waitcnt lgkmcnt(0)
	v_mfma_f32_16x16x32_bf16 v[68:71], v[136:139], v[152:155], v[68:71]
	v_mfma_f32_16x16x32_bf16 v[64:67], v[144:147], v[152:155], v[64:67]
	v_mfma_f32_16x16x32_bf16 v[52:55], v[136:139], v[160:163], v[52:55]
	v_mfma_f32_16x16x32_bf16 v[48:51], v[144:147], v[160:163], v[48:51]
	v_mfma_f32_16x16x32_bf16 v[36:39], v[136:139], v[176:179], v[36:39]
	v_mfma_f32_16x16x32_bf16 v[32:35], v[144:147], v[176:179], v[32:35]
	v_mfma_f32_16x16x32_bf16 v[20:23], v[136:139], v[200:203], v[20:23]
	v_mfma_f32_16x16x32_bf16 v[16:19], v[144:147], v[200:203], v[16:19]
	v_mfma_f32_16x16x32_bf16 v[68:71], v[140:143], v[156:159], v[68:71]
	v_mfma_f32_16x16x32_bf16 v[64:67], v[148:151], v[156:159], v[64:67]
	v_mfma_f32_16x16x32_bf16 v[52:55], v[140:143], v[172:175], v[52:55]
	v_mfma_f32_16x16x32_bf16 v[48:51], v[148:151], v[172:175], v[48:51]
	v_mfma_f32_16x16x32_bf16 v[36:39], v[140:143], v[196:199], v[36:39]
	v_mfma_f32_16x16x32_bf16 v[32:35], v[148:151], v[196:199], v[32:35]
	v_mfma_f32_16x16x32_bf16 v[20:23], v[140:143], v[204:207], v[20:23]
	v_mfma_f32_16x16x32_bf16 v[16:19], v[148:151], v[204:207], v[16:19]
	s_barrier
	s_add_i32 s100, s41, s23
	s_mov_b32 m0, s100
	s_nop 0
	s_add_u32 vcc_lo, s20, s42
	s_addc_u32 vcc_hi, s21, s43
	global_load_lds_dwordx4 v164, vcc
	s_add_i32 m0, s100, 0x2000
	s_nop 0
	s_add_u32 vcc_lo, s20, s50
	s_addc_u32 vcc_hi, s21, s51
	global_load_lds_dwordx4 v164, vcc
	s_waitcnt vmcnt(6)
	s_barrier
	v_mfma_f32_16x16x32_bf16 v[60:63], v[208:211], v[152:155], v[60:63]
	v_mfma_f32_16x16x32_bf16 v[56:59], v[216:219], v[152:155], v[56:59]
	v_mfma_f32_16x16x32_bf16 v[44:47], v[208:211], v[160:163], v[44:47]
	v_mfma_f32_16x16x32_bf16 v[40:43], v[216:219], v[160:163], v[40:43]
	v_mfma_f32_16x16x32_bf16 v[28:31], v[208:211], v[176:179], v[28:31]
	v_mfma_f32_16x16x32_bf16 v[24:27], v[216:219], v[176:179], v[24:27]
	v_mfma_f32_16x16x32_bf16 v[12:15], v[208:211], v[200:203], v[12:15]
	v_mfma_f32_16x16x32_bf16 v[8:11], v[216:219], v[200:203], v[8:11]
	v_mfma_f32_16x16x32_bf16 v[60:63], v[212:215], v[156:159], v[60:63]
	v_mfma_f32_16x16x32_bf16 v[56:59], v[220:223], v[156:159], v[56:59]
	v_mfma_f32_16x16x32_bf16 v[44:47], v[212:215], v[172:175], v[44:47]
	v_mfma_f32_16x16x32_bf16 v[40:43], v[220:223], v[172:175], v[40:43]
	v_mfma_f32_16x16x32_bf16 v[28:31], v[212:215], v[196:199], v[28:31]
	v_mfma_f32_16x16x32_bf16 v[24:27], v[220:223], v[196:199], v[24:27]
	v_mfma_f32_16x16x32_bf16 v[12:15], v[212:215], v[204:207], v[12:15]
	v_mfma_f32_16x16x32_bf16 v[8:11], v[220:223], v[204:207], v[8:11]
	s_barrier
	s_add_i32 s100, 0, 0x18000
	ds_read_b128 v[136:139], v255 offset:32768
	ds_read_b128 v[140:143], v255 offset:33792
	ds_read_b128 v[144:147], v255 offset:34816
	ds_read_b128 v[148:151], v255 offset:35840
	s_mov_b32 m0, s26
	ds_read_b128 v[152:155], v182 offset:32768
	ds_read_b128 v[156:159], v182 offset:33792
	ds_read_b128 v[160:163], v182 offset:34816
	ds_read_b128 v[172:175], v182 offset:35840
	ds_read_b128 v[176:179], v182 offset:36864
	ds_read_b128 v[196:199], v182 offset:37888
	ds_read_b128 v[200:203], v182 offset:38912
	ds_read_b128 v[204:207], v182 offset:39936
	s_add_u32 vcc_lo, s4, s42
	s_addc_u32 vcc_hi, s5, s43
	global_load_lds_dwordx4 v2, vcc
	s_mov_b32 m0, s27
	s_nop 0
	s_add_u32 vcc_lo, s4, s50
	s_addc_u32 vcc_hi, s5, s51
	global_load_lds_dwordx4 v2, vcc
	s_waitcnt lgkmcnt(8)
	s_barrier
	s_waitcnt lgkmcnt(0)
	v_mfma_f32_16x16x32_bf16 v[132:135], v[136:139], v[152:155], v[132:135]
	v_mfma_f32_16x16x32_bf16 v[128:131], v[144:147], v[152:155], v[128:131]
	v_mfma_f32_16x16x32_bf16 v[116:119], v[136:139], v[160:163], v[116:119]
	v_mfma_f32_16x16x32_bf16 v[112:115], v[144:147], v[160:163], v[112:115]
	v_mfma_f32_16x16x32_bf16 v[100:103], v[136:139], v[176:179], v[100:103]
	v_mfma_f32_16x16x32_bf16 v[96:99], v[144:147], v[176:179], v[96:99]
	v_mfma_f32_16x16x32_bf16 v[84:87], v[136:139], v[200:203], v[84:87]
	v_mfma_f32_16x16x32_bf16 v[80:83], v[144:147], v[200:203], v[80:83]
	v_mfma_f32_16x16x32_bf16 v[132:135], v[140:143], v[156:159], v[132:135]
	v_mfma_f32_16x16x32_bf16 v[128:131], v[148:151], v[156:159], v[128:131]
	v_mfma_f32_16x16x32_bf16 v[116:119], v[140:143], v[172:175], v[116:119]
	v_mfma_f32_16x16x32_bf16 v[112:115], v[148:151], v[172:175], v[112:115]
	v_mfma_f32_16x16x32_bf16 v[100:103], v[140:143], v[196:199], v[100:103]
	v_mfma_f32_16x16x32_bf16 v[96:99], v[148:151], v[196:199], v[96:99]
	v_mfma_f32_16x16x32_bf16 v[84:87], v[140:143], v[204:207], v[84:87]
	v_mfma_f32_16x16x32_bf16 v[80:83], v[148:151], v[204:207], v[80:83]
	s_barrier
; #define G_STAGE(bufoff, gbase, o0, h64) do { \
;         __builtin_amdgcn_global_load_lds((const unsigned*)((const char*)(gbase) + (o0)), (LAS unsigned*)(lds + (bufoff) + ldsw), 16, 0, 0); \
;         __builtin_amdgcn_global_load_lds((const unsigned*)((const char*)(gbase) + (h64) + (o0)), (LAS unsigned*)(lds + (bufoff) + ldsw + 8192), 16, 0, 0); } while (0)
; #define G_LDA(dst, b, h) do { _Pragma("unroll") for (int m = 0; m < 4; ++m) _Pragma("unroll") for (int k = 0; k < 2; ++k) dst[m][k] = *(const LAS bf16x8*)(lds + G_SA(b, h) + aoff + m * 2048 + k * 1024); } while (0)
; #define G_LDB(dst, b, h) do { _Pragma("unroll") for (int n = 0; n < 2; ++n) _Pragma("unroll") for (int k = 0; k < 2; ++k) dst[n][k] = *(const LAS bf16x8*)(lds + G_SB(b, h) + boff + n * 2048 + k * 1024); } while (0)
; #define G_WAIT_V(n) asm volatile("s_waitcnt vmcnt(" #n ")" ::: "memory")
; #define G_WAIT_L(n) asm volatile("s_waitcnt lgkmcnt(" #n ")" ::: "memory")
; #define G_BAR __builtin_amdgcn_s_barrier()
; #define G_SCHED __builtin_amdgcn_sched_barrier(0)
;     ...
;             G_LDB(B1, 1, 1); G_STAGE(G_SB(1, 0), b3, cB0, qB);
;             G_BAR; G_WAIT_L(0); G_MMA(0, 1, At, B1); G_BAR;
;             G_LDA(At, 1, 1); G_STAGE(G_SA(1, 0), a3, cA0, qA);
;             G_BAR; G_WAIT_L(0); G_MMA(1, 0, At, B0); G_BAR; G_SCHED;
;             G_STAGE(G_SB(1, 1), b3 + chB, cB0, qB);
;             G_WAIT_V(6); G_BAR; G_MMA(1, 1, At, B1); G_BAR;
;         }
	s_add_i32 s5, 0, 0x1c000
	s_add_i32 s4, s100, s23
	s_mov_b32 m0, s4
	ds_read_b128 v[208:211], v255 offset:49152
	ds_read_b128 v[212:215], v255 offset:50176
	ds_read_b128 v[216:219], v255 offset:51200
	ds_read_b128 v[220:223], v255 offset:52224
	s_add_u32 vcc_lo, s20, s46
	s_addc_u32 vcc_hi, s21, s47
	global_load_lds_dwordx4 v164, vcc
	s_add_i32 m0, s4, 0x2000
	s_nop 0
	s_add_u32 vcc_lo, s20, s52
	s_addc_u32 vcc_hi, s21, s53
	global_load_lds_dwordx4 v164, vcc
	s_barrier
	s_waitcnt lgkmcnt(0)
	v_mfma_f32_16x16x32_bf16 v[124:127], v[208:211], v[152:155], v[124:127]
	v_mfma_f32_16x16x32_bf16 v[120:123], v[216:219], v[152:155], v[120:123]
	v_mfma_f32_16x16x32_bf16 v[108:111], v[208:211], v[160:163], v[108:111]
	v_mfma_f32_16x16x32_bf16 v[104:107], v[216:219], v[160:163], v[104:107]
	v_mfma_f32_16x16x32_bf16 v[92:95], v[208:211], v[176:179], v[92:95]
	v_mfma_f32_16x16x32_bf16 v[88:91], v[216:219], v[176:179], v[88:91]
	v_mfma_f32_16x16x32_bf16 v[76:79], v[208:211], v[200:203], v[76:79]
	v_mfma_f32_16x16x32_bf16 v[72:75], v[216:219], v[200:203], v[72:75]
	v_mfma_f32_16x16x32_bf16 v[124:127], v[212:215], v[156:159], v[124:127]
	v_mfma_f32_16x16x32_bf16 v[120:123], v[220:223], v[156:159], v[120:123]
	v_mfma_f32_16x16x32_bf16 v[108:111], v[212:215], v[172:175], v[108:111]
	v_mfma_f32_16x16x32_bf16 v[104:107], v[220:223], v[172:175], v[104:107]
	v_mfma_f32_16x16x32_bf16 v[92:95], v[212:215], v[196:199], v[92:95]
	v_mfma_f32_16x16x32_bf16 v[88:91], v[220:223], v[196:199], v[88:91]
	v_mfma_f32_16x16x32_bf16 v[76:79], v[212:215], v[204:207], v[76:79]
	v_mfma_f32_16x16x32_bf16 v[72:75], v[220:223], v[204:207], v[72:75]
	s_barrier
	s_mov_b32 m0, s29
	v_lshl_add_u64 v[226:227], v[224:225], 0, s[46:47]
	ds_read_b128 v[152:155], v182 offset:49152
	ds_read_b128 v[156:159], v182 offset:50176
	ds_read_b128 v[160:163], v182 offset:51200
	ds_read_b128 v[172:175], v182 offset:52224
	ds_read_b128 v[176:179], v182 offset:53248
	ds_read_b128 v[196:199], v182 offset:54272
	ds_read_b128 v[200:203], v182 offset:55296
	ds_read_b128 v[204:207], v182 offset:56320
	global_load_lds_dwordx4 v[226:227], off
	v_lshl_add_u64 v[224:225], v[224:225], 0, s[52:53]
	s_mov_b32 m0, s30
	s_nop 0
	global_load_lds_dwordx4 v[224:225], off
	s_barrier
	s_waitcnt lgkmcnt(0)
	v_mfma_f32_16x16x32_bf16 v[68:71], v[136:139], v[152:155], v[68:71]
	v_mfma_f32_16x16x32_bf16 v[64:67], v[144:147], v[152:155], v[64:67]
	v_mfma_f32_16x16x32_bf16 v[52:55], v[136:139], v[160:163], v[52:55]
	v_mfma_f32_16x16x32_bf16 v[48:51], v[144:147], v[160:163], v[48:51]
	v_mfma_f32_16x16x32_bf16 v[36:39], v[136:139], v[176:179], v[36:39]
	v_mfma_f32_16x16x32_bf16 v[32:35], v[144:147], v[176:179], v[32:35]
	v_mfma_f32_16x16x32_bf16 v[20:23], v[136:139], v[200:203], v[20:23]
	v_mfma_f32_16x16x32_bf16 v[16:19], v[144:147], v[200:203], v[16:19]
	v_mfma_f32_16x16x32_bf16 v[68:71], v[140:143], v[156:159], v[68:71]
	v_mfma_f32_16x16x32_bf16 v[64:67], v[148:151], v[156:159], v[64:67]
	v_mfma_f32_16x16x32_bf16 v[52:55], v[140:143], v[172:175], v[52:55]
	v_mfma_f32_16x16x32_bf16 v[48:51], v[148:151], v[172:175], v[48:51]
	v_mfma_f32_16x16x32_bf16 v[36:39], v[140:143], v[196:199], v[36:39]
	v_mfma_f32_16x16x32_bf16 v[32:35], v[148:151], v[196:199], v[32:35]
	v_mfma_f32_16x16x32_bf16 v[20:23], v[140:143], v[204:207], v[20:23]
	v_mfma_f32_16x16x32_bf16 v[16:19], v[148:151], v[204:207], v[16:19]
	s_barrier
	s_add_i32 s4, s5, s23
	s_mov_b32 m0, s4
	s_nop 0
	s_add_u32 vcc_lo, s20, s54
	s_addc_u32 vcc_hi, s21, s55
	global_load_lds_dwordx4 v164, vcc
	s_add_i32 m0, s4, 0x2000
	s_nop 0
	s_add_u32 vcc_lo, s20, s58
	s_addc_u32 vcc_hi, s21, s59
	global_load_lds_dwordx4 v164, vcc
	s_add_i32 s15, s15, 2
	s_add_u32 s2, s2, 0x100
	s_addc_u32 s3, s3, 0
	s_add_u32 s6, s6, 0x100
	s_addc_u32 s7, s7, 0
	s_cmp_gt_u32 s15, 13
	s_waitcnt vmcnt(6)
	s_barrier
	v_mfma_f32_16x16x32_bf16 v[60:63], v[208:211], v[152:155], v[60:63]
	v_mfma_f32_16x16x32_bf16 v[56:59], v[216:219], v[152:155], v[56:59]
	v_mfma_f32_16x16x32_bf16 v[44:47], v[208:211], v[160:163], v[44:47]
	v_mfma_f32_16x16x32_bf16 v[40:43], v[216:219], v[160:163], v[40:43]
	v_mfma_f32_16x16x32_bf16 v[28:31], v[208:211], v[176:179], v[28:31]
	v_mfma_f32_16x16x32_bf16 v[24:27], v[216:219], v[176:179], v[24:27]
	v_mfma_f32_16x16x32_bf16 v[12:15], v[208:211], v[200:203], v[12:15]
	v_mfma_f32_16x16x32_bf16 v[8:11], v[216:219], v[200:203], v[8:11]
	v_mfma_f32_16x16x32_bf16 v[60:63], v[212:215], v[156:159], v[60:63]
	v_mfma_f32_16x16x32_bf16 v[56:59], v[220:223], v[156:159], v[56:59]
	v_mfma_f32_16x16x32_bf16 v[44:47], v[212:215], v[172:175], v[44:47]
	v_mfma_f32_16x16x32_bf16 v[40:43], v[220:223], v[172:175], v[40:43]
	v_mfma_f32_16x16x32_bf16 v[28:31], v[212:215], v[196:199], v[28:31]
	v_mfma_f32_16x16x32_bf16 v[24:27], v[220:223], v[196:199], v[24:27]
	v_mfma_f32_16x16x32_bf16 v[12:15], v[212:215], v[204:207], v[12:15]
	v_mfma_f32_16x16x32_bf16 v[8:11], v[220:223], v[204:207], v[8:11]
	s_cbranch_scc0 .Ldb_WOUT_cont
	v_readfirstlane_b32 s101, v186
	s_cmpk_gt_u32 s101, 0xff
	s_cbranch_scc1 .Ldb_WOUT_young
	s_barrier
	s_mov_b32 s101, 1
	s_branch .Ldb_WOUT_exit

; #define G_STAGE(bufoff, gbase, o0, h64) do { \
;         __builtin_amdgcn_global_load_lds((const unsigned*)((const char*)(gbase) + (o0)), (LAS unsigned*)(lds + (bufoff) + ldsw), 16, 0, 0); \
;         __builtin_amdgcn_global_load_lds((const unsigned*)((const char*)(gbase) + (h64) + (o0)), (LAS unsigned*)(lds + (bufoff) + ldsw + 8192), 16, 0, 0); } while (0)
; #define G_LDA(dst, b, h) do { _Pragma("unroll") for (int m = 0; m < 4; ++m) _Pragma("unroll") for (int k = 0; k < 2; ++k) dst[m][k] = *(const LAS bf16x8*)(lds + G_SA(b, h) + aoff + m * 2048 + k * 1024); } while (0)
; #define G_LDB(dst, b, h) do { _Pragma("unroll") for (int n = 0; n < 2; ++n) _Pragma("unroll") for (int k = 0; k < 2; ++k) dst[n][k] = *(const LAS bf16x8*)(lds + G_SB(b, h) + boff + n * 2048 + k * 1024); } while (0)
; #define G_WAIT_L(n) asm volatile("s_waitcnt lgkmcnt(" #n ")" ::: "memory")
; #define G_BAR __builtin_amdgcn_s_barrier()
; #define G_SCHED __builtin_amdgcn_sched_barrier(0)
;     ...
;     for (;;) {
;         const bool has_next = sched_next<PH, SUB>(E.ws, E.layer, ui + 1, nxt, E.x);
;         if (!has_next) nxt = cur;
;         const char* nA = nxt.A; const char* nB = nxt.B;
; #pragma unroll 1
;         for (int t = 0; t < nt; t += 2) {
;             const bool last = (t == nt - 2);
;             const char* a1 = cA + (size_t)(t + 1) * ckA;
;             const char* a2 = last ? nA : cA + (size_t)(t + 2) * ckA; const char* b2 = last ? nB : cB + (size_t)(t + 2) * kB;
;             const char* a3 = a2 + ckA; const char* b3 = b2 + kB;
;             G_LDB(B0, 0, 0); G_SCHED; G_LDA(At, 0, 0); G_STAGE(G_SA(1, 1), a1 + chA, cA0, qA);
;             G_WAIT_L(8); G_BAR; G_WAIT_L(0); G_MMA(0, 0, At, B0); G_BAR; G_SCHED;
;             G_LDB(B1, 0, 1); G_STAGE(G_SB(0, 0), b2, cB0, qB);
;             G_BAR; G_WAIT_L(0); G_MMA(0, 1, At, B1); G_BAR;
;     ...
; #pragma unroll
;         for (int a = 0; a < 2; ++a)
; #pragma unroll
;             for (int b = 0; b < 2; ++b)
; #pragma unroll
;                 for (int m = 0; m < 4; ++m)
; #pragma unroll
;                     for (int n = 0; n < 2; ++n) acc[a][b][m][n] = (f32x4){0.f, 0.f, 0.f, 0.f};
;         cur = nxt; cA = nA; cB = nB; ++ui;
.LBB0_1119:
	s_add_u32 s2, s16, 0x40080
	s_addc_u32 s3, s17, 0
	s_add_u32 s16, s18, 0x100
	v_mov_b64_e32 v[8:9], 0
	s_addc_u32 s17, s19, 0
	s_mov_b32 s18, -2
	v_mov_b64_e32 v[10:11], 0
	v_mov_b64_e32 v[16:17], 0
	v_mov_b64_e32 v[18:19], 0
	v_mov_b64_e32 v[24:25], 0
	v_mov_b64_e32 v[26:27], 0
	v_mov_b64_e32 v[32:33], 0
	v_mov_b64_e32 v[34:35], 0
	v_mov_b64_e32 v[40:41], 0
	v_mov_b64_e32 v[42:43], 0
	v_mov_b64_e32 v[48:49], 0
	v_mov_b64_e32 v[50:51], 0
	v_mov_b64_e32 v[56:57], 0
	v_mov_b64_e32 v[58:59], 0
	v_mov_b64_e32 v[64:65], 0
	v_mov_b64_e32 v[66:67], 0
	v_mov_b64_e32 v[12:13], 0
	v_mov_b64_e32 v[14:15], 0
	v_mov_b64_e32 v[20:21], 0
	v_mov_b64_e32 v[22:23], 0
	v_mov_b64_e32 v[28:29], 0
	v_mov_b64_e32 v[30:31], 0
	v_mov_b64_e32 v[36:37], 0
	v_mov_b64_e32 v[38:39], 0
	v_mov_b64_e32 v[44:45], 0
	v_mov_b64_e32 v[46:47], 0
	v_mov_b64_e32 v[52:53], 0
	v_mov_b64_e32 v[54:55], 0
	v_mov_b64_e32 v[60:61], 0
	v_mov_b64_e32 v[62:63], 0
	v_mov_b64_e32 v[68:69], 0
	v_mov_b64_e32 v[70:71], 0
	v_mov_b64_e32 v[72:73], 0
	v_mov_b64_e32 v[74:75], 0
	v_mov_b64_e32 v[80:81], 0
	v_mov_b64_e32 v[82:83], 0
	v_mov_b64_e32 v[88:89], 0
	v_mov_b64_e32 v[90:91], 0
	v_mov_b64_e32 v[96:97], 0
	v_mov_b64_e32 v[98:99], 0
	v_mov_b64_e32 v[104:105], 0
	v_mov_b64_e32 v[106:107], 0
	v_mov_b64_e32 v[112:113], 0
	v_mov_b64_e32 v[114:115], 0
	v_mov_b64_e32 v[120:121], 0
	v_mov_b64_e32 v[122:123], 0
	v_mov_b64_e32 v[128:129], 0
	v_mov_b64_e32 v[130:131], 0
	v_mov_b64_e32 v[76:77], 0
	v_mov_b64_e32 v[78:79], 0
	v_mov_b64_e32 v[84:85], 0
	v_mov_b64_e32 v[86:87], 0
	v_mov_b64_e32 v[92:93], 0
	v_mov_b64_e32 v[94:95], 0
	v_mov_b64_e32 v[100:101], 0
	v_mov_b64_e32 v[102:103], 0
	v_mov_b64_e32 v[108:109], 0
	v_mov_b64_e32 v[110:111], 0
	v_mov_b64_e32 v[116:117], 0
	v_mov_b64_e32 v[118:119], 0
	v_mov_b64_e32 v[124:125], 0
	v_mov_b64_e32 v[126:127], 0
	v_mov_b64_e32 v[132:133], 0
	v_mov_b64_e32 v[134:135], 0
	s_mov_b64 s[42:43], 0x40000
	s_mov_b64 s[50:51], 0x60000
	s_mov_b64 s[52:53], 0x20080
	s_mov_b64 s[54:55], 0x40080
	s_mov_b64 s[58:59], 0x60080
	s_cmp_eq_u32 s101, 2
	s_cselect_b32 s101, 0, s101
	v_add_u32_e32 v235, 0x10000, v149
.LBB0_1120:
	s_add_u32 s4, s2, 0xfffc0080
	s_addc_u32 s5, s3, -1
	s_add_i32 s19, 0, 0x10000
	ds_read_b128 v[140:143], v235 offset:0
	ds_read_b128 v[144:147], v235 offset:1024
	ds_read_b128 v[152:155], v235 offset:2048
	ds_read_b128 v[156:159], v235 offset:3072
	s_cmp_eq_u32 s18, 12
	s_cselect_b32 s5, s13, s5
	s_cselect_b32 s4, s12, s4
	s_cselect_b32 s41, s15, s17
	s_cselect_b32 s40, s14, s16
	s_add_i32 m0, s26, 0xc000
	ds_read_b128 v[160:163], v150
	ds_read_b128 v[164:167], v150 offset:1024
	ds_read_b128 v[172:175], v150 offset:2048
	ds_read_b128 v[176:179], v150 offset:3072
	ds_read_b128 v[180:183], v150 offset:4096
	ds_read_b128 v[196:199], v150 offset:5120
	ds_read_b128 v[200:203], v150 offset:6144
	ds_read_b128 v[204:207], v150 offset:7168
	global_load_lds_dwordx4 v138, s[2:3]
	s_add_i32 m0, s26, 0xe000
	s_nop 0
	s_add_u32 vcc_lo, s2, s0
	s_addc_u32 vcc_hi, s3, s1
	global_load_lds_dwordx4 v138, vcc
	s_waitcnt lgkmcnt(8)
	s_cmp_eq_u32 s101, 1
	s_cbranch_scc1 .Ldb_FFI_sk
	s_barrier
.Ldb_FFI_sk:
	s_mov_b32 s101, 0
	s_waitcnt lgkmcnt(0)
	v_mfma_f32_16x16x32_bf16 v[132:135], v[140:143], v[160:163], v[132:135]
	v_mfma_f32_16x16x32_bf16 v[124:127], v[152:155], v[160:163], v[124:127]
	v_mfma_f32_16x16x32_bf16 v[116:119], v[140:143], v[172:175], v[116:119]
	v_mfma_f32_16x16x32_bf16 v[108:111], v[152:155], v[172:175], v[108:111]
	v_mfma_f32_16x16x32_bf16 v[100:103], v[140:143], v[180:183], v[100:103]
	v_mfma_f32_16x16x32_bf16 v[92:95], v[152:155], v[180:183], v[92:95]
	v_mfma_f32_16x16x32_bf16 v[84:87], v[140:143], v[200:203], v[84:87]
	v_mfma_f32_16x16x32_bf16 v[76:79], v[152:155], v[200:203], v[76:79]
	v_mfma_f32_16x16x32_bf16 v[132:135], v[144:147], v[164:167], v[132:135]
	v_mfma_f32_16x16x32_bf16 v[124:127], v[156:159], v[164:167], v[124:127]
	v_mfma_f32_16x16x32_bf16 v[116:119], v[144:147], v[176:179], v[116:119]
	v_mfma_f32_16x16x32_bf16 v[108:111], v[156:159], v[176:179], v[108:111]
	v_mfma_f32_16x16x32_bf16 v[100:103], v[144:147], v[196:199], v[100:103]
	v_mfma_f32_16x16x32_bf16 v[92:95], v[156:159], v[196:199], v[92:95]
	v_mfma_f32_16x16x32_bf16 v[84:87], v[144:147], v[204:207], v[84:87]
	v_mfma_f32_16x16x32_bf16 v[76:79], v[156:159], v[204:207], v[76:79]
	s_barrier
	s_add_i32 s39, 0, 0x14000
	s_add_i32 s19, s19, s21
	s_mov_b32 m0, s19
	ds_read_b128 v[208:211], v235 offset:16384
	ds_read_b128 v[212:215], v235 offset:17408
	ds_read_b128 v[216:219], v235 offset:18432
	ds_read_b128 v[220:223], v235 offset:19456
	global_load_lds_dwordx4 v2, s[40:41]
	s_add_i32 m0, s19, 0x2000
	s_nop 0
	s_add_u32 vcc_lo, s40, s0
	s_addc_u32 vcc_hi, s41, s1
	global_load_lds_dwordx4 v2, vcc
	s_barrier
	s_waitcnt lgkmcnt(0)
	v_mfma_f32_16x16x32_bf16 v[128:131], v[208:211], v[160:163], v[128:131]
	v_mfma_f32_16x16x32_bf16 v[120:123], v[216:219], v[160:163], v[120:123]
	v_mfma_f32_16x16x32_bf16 v[112:115], v[208:211], v[172:175], v[112:115]
	v_mfma_f32_16x16x32_bf16 v[104:107], v[216:219], v[172:175], v[104:107]
	v_mfma_f32_16x16x32_bf16 v[96:99], v[208:211], v[180:183], v[96:99]
	v_mfma_f32_16x16x32_bf16 v[88:91], v[216:219], v[180:183], v[88:91]
	v_mfma_f32_16x16x32_bf16 v[80:83], v[208:211], v[200:203], v[80:83]
	v_mfma_f32_16x16x32_bf16 v[72:75], v[216:219], v[200:203], v[72:75]
	v_mfma_f32_16x16x32_bf16 v[128:131], v[212:215], v[164:167], v[128:131]
	v_mfma_f32_16x16x32_bf16 v[120:123], v[220:223], v[164:167], v[120:123]
	v_mfma_f32_16x16x32_bf16 v[112:115], v[212:215], v[176:179], v[112:115]
	v_mfma_f32_16x16x32_bf16 v[104:107], v[220:223], v[176:179], v[104:107]
	v_mfma_f32_16x16x32_bf16 v[96:99], v[212:215], v[196:199], v[96:99]
	v_mfma_f32_16x16x32_bf16 v[88:91], v[220:223], v[196:199], v[88:91]
	v_mfma_f32_16x16x32_bf16 v[80:83], v[212:215], v[204:207], v[80:83]
	v_mfma_f32_16x16x32_bf16 v[72:75], v[220:223], v[204:207], v[72:75]
	s_barrier
; #define G_STAGE(bufoff, gbase, o0, h64) do { \
;         __builtin_amdgcn_global_load_lds((const unsigned*)((const char*)(gbase) + (o0)), (LAS unsigned*)(lds + (bufoff) + ldsw), 16, 0, 0); \
;         __builtin_amdgcn_global_load_lds((const unsigned*)((const char*)(gbase) + (h64) + (o0)), (LAS unsigned*)(lds + (bufoff) + ldsw + 8192), 16, 0, 0); } while (0)
; #define G_LDA(dst, b, h) do { _Pragma("unroll") for (int m = 0; m < 4; ++m) _Pragma("unroll") for (int k = 0; k < 2; ++k) dst[m][k] = *(const LAS bf16x8*)(lds + G_SA(b, h) + aoff + m * 2048 + k * 1024); } while (0)
; #define G_LDB(dst, b, h) do { _Pragma("unroll") for (int n = 0; n < 2; ++n) _Pragma("unroll") for (int k = 0; k < 2; ++k) dst[n][k] = *(const LAS bf16x8*)(lds + G_SB(b, h) + boff + n * 2048 + k * 1024); } while (0)
; #define G_WAIT_V(n) asm volatile("s_waitcnt vmcnt(" #n ")" ::: "memory")
; #define G_WAIT_L(n) asm volatile("s_waitcnt lgkmcnt(" #n ")" ::: "memory")
; #define G_BAR __builtin_amdgcn_s_barrier()
; #define G_SCHED __builtin_amdgcn_sched_barrier(0)
;     ...
;             G_LDB(B1, 0, 1); G_STAGE(G_SB(0, 0), b2, cB0, qB);
;             G_BAR; G_WAIT_L(0); G_MMA(0, 1, At, B1); G_BAR;
;             G_LDA(At, 0, 1); G_STAGE(G_SA(0, 0), a2, cA0, qA);
;             G_BAR; G_WAIT_L(0); G_MMA(1, 0, At, B0); G_BAR; G_SCHED;
;             G_STAGE(G_SB(0, 1), b2 + chB, cB0, qB);
;             G_WAIT_V(6); G_BAR; G_MMA(1, 1, At, B1); G_BAR;
;             G_LDB(B0, 1, 0); G_SCHED; G_LDA(At, 1, 0); G_STAGE(G_SA(0, 1), a2 + chA, cA0, qA);
;             G_WAIT_L(8); G_BAR; G_WAIT_L(0); G_MMA(0, 0, At, B0); G_BAR; G_SCHED;
;             G_LDB(B1, 1, 1); G_STAGE(G_SB(1, 0), b3, cB0, qB);
	s_mov_b32 m0, s26
	v_lshl_add_u64 v[224:225], s[4:5], 0, v[136:137]
	ds_read_b128 v[160:163], v150 offset:16384
	ds_read_b128 v[164:167], v150 offset:17408
	ds_read_b128 v[172:175], v150 offset:18432
	ds_read_b128 v[176:179], v150 offset:19456
	ds_read_b128 v[180:183], v150 offset:20480
	ds_read_b128 v[196:199], v150 offset:21504
	ds_read_b128 v[200:203], v150 offset:22528
	ds_read_b128 v[204:207], v150 offset:23552
	global_load_lds_dwordx4 v136, s[4:5]
	s_mov_b32 m0, s27
	s_nop 0
	s_add_u32 vcc_lo, s4, s0
	s_addc_u32 vcc_hi, s5, s1
	global_load_lds_dwordx4 v136, vcc
	s_barrier
	s_waitcnt lgkmcnt(0)
	v_mfma_f32_16x16x32_bf16 v[68:71], v[140:143], v[160:163], v[68:71]
	v_mfma_f32_16x16x32_bf16 v[60:63], v[152:155], v[160:163], v[60:63]
	v_mfma_f32_16x16x32_bf16 v[52:55], v[140:143], v[172:175], v[52:55]
	v_mfma_f32_16x16x32_bf16 v[44:47], v[152:155], v[172:175], v[44:47]
	v_mfma_f32_16x16x32_bf16 v[36:39], v[140:143], v[180:183], v[36:39]
	v_mfma_f32_16x16x32_bf16 v[28:31], v[152:155], v[180:183], v[28:31]
	v_mfma_f32_16x16x32_bf16 v[20:23], v[140:143], v[200:203], v[20:23]
	v_mfma_f32_16x16x32_bf16 v[12:15], v[152:155], v[200:203], v[12:15]
	v_mfma_f32_16x16x32_bf16 v[68:71], v[144:147], v[164:167], v[68:71]
	v_mfma_f32_16x16x32_bf16 v[60:63], v[156:159], v[164:167], v[60:63]
	v_mfma_f32_16x16x32_bf16 v[52:55], v[144:147], v[176:179], v[52:55]
	v_mfma_f32_16x16x32_bf16 v[44:47], v[156:159], v[176:179], v[44:47]
	v_mfma_f32_16x16x32_bf16 v[36:39], v[144:147], v[196:199], v[36:39]
	v_mfma_f32_16x16x32_bf16 v[28:31], v[156:159], v[196:199], v[28:31]
	v_mfma_f32_16x16x32_bf16 v[20:23], v[144:147], v[204:207], v[20:23]
	v_mfma_f32_16x16x32_bf16 v[12:15], v[156:159], v[204:207], v[12:15]
	s_barrier
	s_add_i32 s100, s39, s21
	s_mov_b32 m0, s100
	s_nop 0
	s_add_u32 vcc_lo, s40, s42
	s_addc_u32 vcc_hi, s41, s43
	global_load_lds_dwordx4 v2, vcc
	s_add_i32 m0, s100, 0x2000
	s_nop 0
	s_add_u32 vcc_lo, s40, s50
	s_addc_u32 vcc_hi, s41, s51
	global_load_lds_dwordx4 v2, vcc
	s_waitcnt vmcnt(6)
	s_barrier
	v_mfma_f32_16x16x32_bf16 v[64:67], v[208:211], v[160:163], v[64:67]
	v_mfma_f32_16x16x32_bf16 v[56:59], v[216:219], v[160:163], v[56:59]
	v_mfma_f32_16x16x32_bf16 v[48:51], v[208:211], v[172:175], v[48:51]
	v_mfma_f32_16x16x32_bf16 v[40:43], v[216:219], v[172:175], v[40:43]
	v_mfma_f32_16x16x32_bf16 v[32:35], v[208:211], v[180:183], v[32:35]
	v_mfma_f32_16x16x32_bf16 v[24:27], v[216:219], v[180:183], v[24:27]
	v_mfma_f32_16x16x32_bf16 v[16:19], v[208:211], v[200:203], v[16:19]
	v_mfma_f32_16x16x32_bf16 v[8:11], v[216:219], v[200:203], v[8:11]
	v_mfma_f32_16x16x32_bf16 v[64:67], v[212:215], v[164:167], v[64:67]
	v_mfma_f32_16x16x32_bf16 v[56:59], v[220:223], v[164:167], v[56:59]
	v_mfma_f32_16x16x32_bf16 v[48:51], v[212:215], v[176:179], v[48:51]
	v_mfma_f32_16x16x32_bf16 v[40:43], v[220:223], v[176:179], v[40:43]
	v_mfma_f32_16x16x32_bf16 v[32:35], v[212:215], v[196:199], v[32:35]
	v_mfma_f32_16x16x32_bf16 v[24:27], v[220:223], v[196:199], v[24:27]
	v_mfma_f32_16x16x32_bf16 v[16:19], v[212:215], v[204:207], v[16:19]
	v_mfma_f32_16x16x32_bf16 v[8:11], v[220:223], v[204:207], v[8:11]
	s_barrier
	s_add_i32 s100, 0, 0x18000
	ds_read_b128 v[140:143], v235 offset:32768
	ds_read_b128 v[144:147], v235 offset:33792
	ds_read_b128 v[152:155], v235 offset:34816
	ds_read_b128 v[156:159], v235 offset:35840
	s_mov_b32 m0, s29
	ds_read_b128 v[160:163], v150 offset:32768
	ds_read_b128 v[164:167], v150 offset:33792
	ds_read_b128 v[172:175], v150 offset:34816
	ds_read_b128 v[176:179], v150 offset:35840
	ds_read_b128 v[180:183], v150 offset:36864
	ds_read_b128 v[196:199], v150 offset:37888
	ds_read_b128 v[200:203], v150 offset:38912
	ds_read_b128 v[204:207], v150 offset:39936
	s_add_u32 vcc_lo, s4, s42
	s_addc_u32 vcc_hi, s5, s43
	global_load_lds_dwordx4 v136, vcc
	s_mov_b32 m0, s30
	s_nop 0
	s_add_u32 vcc_lo, s4, s50
	s_addc_u32 vcc_hi, s5, s51
	global_load_lds_dwordx4 v136, vcc
	s_waitcnt lgkmcnt(8)
	s_barrier
	s_waitcnt lgkmcnt(0)
	v_mfma_f32_16x16x32_bf16 v[132:135], v[140:143], v[160:163], v[132:135]
	v_mfma_f32_16x16x32_bf16 v[124:127], v[152:155], v[160:163], v[124:127]
	v_mfma_f32_16x16x32_bf16 v[116:119], v[140:143], v[172:175], v[116:119]
	v_mfma_f32_16x16x32_bf16 v[108:111], v[152:155], v[172:175], v[108:111]
	v_mfma_f32_16x16x32_bf16 v[100:103], v[140:143], v[180:183], v[100:103]
	v_mfma_f32_16x16x32_bf16 v[92:95], v[152:155], v[180:183], v[92:95]
	v_mfma_f32_16x16x32_bf16 v[84:87], v[140:143], v[200:203], v[84:87]
	v_mfma_f32_16x16x32_bf16 v[76:79], v[152:155], v[200:203], v[76:79]
	v_mfma_f32_16x16x32_bf16 v[132:135], v[144:147], v[164:167], v[132:135]
	v_mfma_f32_16x16x32_bf16 v[124:127], v[156:159], v[164:167], v[124:127]
	v_mfma_f32_16x16x32_bf16 v[116:119], v[144:147], v[176:179], v[116:119]
	v_mfma_f32_16x16x32_bf16 v[108:111], v[156:159], v[176:179], v[108:111]
	v_mfma_f32_16x16x32_bf16 v[100:103], v[144:147], v[196:199], v[100:103]
	v_mfma_f32_16x16x32_bf16 v[92:95], v[156:159], v[196:199], v[92:95]
	v_mfma_f32_16x16x32_bf16 v[84:87], v[144:147], v[204:207], v[84:87]
	v_mfma_f32_16x16x32_bf16 v[76:79], v[156:159], v[204:207], v[76:79]
	s_barrier
; #define G_STAGE(bufoff, gbase, o0, h64) do { \
;         __builtin_amdgcn_global_load_lds((const unsigned*)((const char*)(gbase) + (o0)), (LAS unsigned*)(lds + (bufoff) + ldsw), 16, 0, 0); \
;         __builtin_amdgcn_global_load_lds((const unsigned*)((const char*)(gbase) + (h64) + (o0)), (LAS unsigned*)(lds + (bufoff) + ldsw + 8192), 16, 0, 0); } while (0)
; #define G_LDA(dst, b, h) do { _Pragma("unroll") for (int m = 0; m < 4; ++m) _Pragma("unroll") for (int k = 0; k < 2; ++k) dst[m][k] = *(const LAS bf16x8*)(lds + G_SA(b, h) + aoff + m * 2048 + k * 1024); } while (0)
; #define G_LDB(dst, b, h) do { _Pragma("unroll") for (int n = 0; n < 2; ++n) _Pragma("unroll") for (int k = 0; k < 2; ++k) dst[n][k] = *(const LAS bf16x8*)(lds + G_SB(b, h) + boff + n * 2048 + k * 1024); } while (0)
; #define G_WAIT_V(n) asm volatile("s_waitcnt vmcnt(" #n ")" ::: "memory")
; #define G_WAIT_L(n) asm volatile("s_waitcnt lgkmcnt(" #n ")" ::: "memory")
; #define G_BAR __builtin_amdgcn_s_barrier()
; #define G_SCHED __builtin_amdgcn_sched_barrier(0)
;     ...
;             G_LDB(B1, 1, 1); G_STAGE(G_SB(1, 0), b3, cB0, qB);
;             G_BAR; G_WAIT_L(0); G_MMA(0, 1, At, B1); G_BAR;
;             G_LDA(At, 1, 1); G_STAGE(G_SA(1, 0), a3, cA0, qA);
;             G_BAR; G_WAIT_L(0); G_MMA(1, 0, At, B0); G_BAR; G_SCHED;
;             G_STAGE(G_SB(1, 1), b3 + chB, cB0, qB);
;             G_WAIT_V(6); G_BAR; G_MMA(1, 1, At, B1); G_BAR;
;         }
	s_add_i32 s5, 0, 0x1c000
	s_add_i32 s4, s100, s21
	s_mov_b32 m0, s4
	ds_read_b128 v[208:211], v235 offset:49152
	ds_read_b128 v[212:215], v235 offset:50176
	ds_read_b128 v[216:219], v235 offset:51200
	ds_read_b128 v[220:223], v235 offset:52224
	s_add_u32 vcc_lo, s40, s46
	s_addc_u32 vcc_hi, s41, s47
	global_load_lds_dwordx4 v2, vcc
	s_add_i32 m0, s4, 0x2000
	s_nop 0
	s_add_u32 vcc_lo, s40, s52
	s_addc_u32 vcc_hi, s41, s53
	global_load_lds_dwordx4 v2, vcc
	s_barrier
	s_waitcnt lgkmcnt(0)
	v_mfma_f32_16x16x32_bf16 v[128:131], v[208:211], v[160:163], v[128:131]
	v_mfma_f32_16x16x32_bf16 v[120:123], v[216:219], v[160:163], v[120:123]
	v_mfma_f32_16x16x32_bf16 v[112:115], v[208:211], v[172:175], v[112:115]
	v_mfma_f32_16x16x32_bf16 v[104:107], v[216:219], v[172:175], v[104:107]
	v_mfma_f32_16x16x32_bf16 v[96:99], v[208:211], v[180:183], v[96:99]
	v_mfma_f32_16x16x32_bf16 v[88:91], v[216:219], v[180:183], v[88:91]
	v_mfma_f32_16x16x32_bf16 v[80:83], v[208:211], v[200:203], v[80:83]
	v_mfma_f32_16x16x32_bf16 v[72:75], v[216:219], v[200:203], v[72:75]
	v_mfma_f32_16x16x32_bf16 v[128:131], v[212:215], v[164:167], v[128:131]
	v_mfma_f32_16x16x32_bf16 v[120:123], v[220:223], v[164:167], v[120:123]
	v_mfma_f32_16x16x32_bf16 v[112:115], v[212:215], v[176:179], v[112:115]
	v_mfma_f32_16x16x32_bf16 v[104:107], v[220:223], v[176:179], v[104:107]
	v_mfma_f32_16x16x32_bf16 v[96:99], v[212:215], v[196:199], v[96:99]
	v_mfma_f32_16x16x32_bf16 v[88:91], v[220:223], v[196:199], v[88:91]
	v_mfma_f32_16x16x32_bf16 v[80:83], v[212:215], v[204:207], v[80:83]
	v_mfma_f32_16x16x32_bf16 v[72:75], v[220:223], v[204:207], v[72:75]
	s_barrier
	s_mov_b32 m0, s31
	v_lshl_add_u64 v[226:227], v[224:225], 0, s[46:47]
	ds_read_b128 v[160:163], v150 offset:49152
	ds_read_b128 v[164:167], v150 offset:50176
	ds_read_b128 v[172:175], v150 offset:51200
	ds_read_b128 v[176:179], v150 offset:52224
	ds_read_b128 v[180:183], v150 offset:53248
	ds_read_b128 v[196:199], v150 offset:54272
	ds_read_b128 v[200:203], v150 offset:55296
	ds_read_b128 v[204:207], v150 offset:56320
	global_load_lds_dwordx4 v[226:227], off
	v_lshl_add_u64 v[224:225], v[224:225], 0, s[52:53]
	s_mov_b32 m0, s34
	s_nop 0
	global_load_lds_dwordx4 v[224:225], off
	s_barrier
	s_waitcnt lgkmcnt(0)
	v_mfma_f32_16x16x32_bf16 v[68:71], v[140:143], v[160:163], v[68:71]
	v_mfma_f32_16x16x32_bf16 v[60:63], v[152:155], v[160:163], v[60:63]
	v_mfma_f32_16x16x32_bf16 v[52:55], v[140:143], v[172:175], v[52:55]
	v_mfma_f32_16x16x32_bf16 v[44:47], v[152:155], v[172:175], v[44:47]
	v_mfma_f32_16x16x32_bf16 v[36:39], v[140:143], v[180:183], v[36:39]
	v_mfma_f32_16x16x32_bf16 v[28:31], v[152:155], v[180:183], v[28:31]
	v_mfma_f32_16x16x32_bf16 v[20:23], v[140:143], v[200:203], v[20:23]
	v_mfma_f32_16x16x32_bf16 v[12:15], v[152:155], v[200:203], v[12:15]
	v_mfma_f32_16x16x32_bf16 v[68:71], v[144:147], v[164:167], v[68:71]
	v_mfma_f32_16x16x32_bf16 v[60:63], v[156:159], v[164:167], v[60:63]
	v_mfma_f32_16x16x32_bf16 v[52:55], v[144:147], v[176:179], v[52:55]
	v_mfma_f32_16x16x32_bf16 v[44:47], v[156:159], v[176:179], v[44:47]
	v_mfma_f32_16x16x32_bf16 v[36:39], v[144:147], v[196:199], v[36:39]
	v_mfma_f32_16x16x32_bf16 v[28:31], v[156:159], v[196:199], v[28:31]
	v_mfma_f32_16x16x32_bf16 v[20:23], v[144:147], v[204:207], v[20:23]
	v_mfma_f32_16x16x32_bf16 v[12:15], v[156:159], v[204:207], v[12:15]
	s_barrier
	s_add_i32 s4, s5, s21
	s_mov_b32 m0, s4
	s_nop 0
	s_add_u32 vcc_lo, s40, s54
	s_addc_u32 vcc_hi, s41, s55
	global_load_lds_dwordx4 v2, vcc
	s_add_i32 m0, s4, 0x2000
	s_nop 0
	s_add_u32 vcc_lo, s40, s58
	s_addc_u32 vcc_hi, s41, s59
	global_load_lds_dwordx4 v2, vcc
	s_add_i32 s18, s18, 2
	s_add_u32 s2, s2, 0x100
	s_addc_u32 s3, s3, 0
	s_add_u32 s16, s16, 0x100
	s_addc_u32 s17, s17, 0
	s_cmp_gt_u32 s18, 13
	s_waitcnt vmcnt(6)
	s_barrier
	v_mfma_f32_16x16x32_bf16 v[64:67], v[208:211], v[160:163], v[64:67]
	v_mfma_f32_16x16x32_bf16 v[56:59], v[216:219], v[160:163], v[56:59]
	v_mfma_f32_16x16x32_bf16 v[48:51], v[208:211], v[172:175], v[48:51]
	v_mfma_f32_16x16x32_bf16 v[40:43], v[216:219], v[172:175], v[40:43]
	v_mfma_f32_16x16x32_bf16 v[32:35], v[208:211], v[180:183], v[32:35]
	v_mfma_f32_16x16x32_bf16 v[24:27], v[216:219], v[180:183], v[24:27]
	v_mfma_f32_16x16x32_bf16 v[16:19], v[208:211], v[200:203], v[16:19]
	v_mfma_f32_16x16x32_bf16 v[8:11], v[216:219], v[200:203], v[8:11]
	v_mfma_f32_16x16x32_bf16 v[64:67], v[212:215], v[164:167], v[64:67]
	v_mfma_f32_16x16x32_bf16 v[56:59], v[220:223], v[164:167], v[56:59]
	v_mfma_f32_16x16x32_bf16 v[48:51], v[212:215], v[176:179], v[48:51]
	v_mfma_f32_16x16x32_bf16 v[40:43], v[220:223], v[176:179], v[40:43]
	v_mfma_f32_16x16x32_bf16 v[32:35], v[212:215], v[196:199], v[32:35]
	v_mfma_f32_16x16x32_bf16 v[24:27], v[220:223], v[196:199], v[24:27]
	v_mfma_f32_16x16x32_bf16 v[16:19], v[212:215], v[204:207], v[16:19]
	v_mfma_f32_16x16x32_bf16 v[8:11], v[220:223], v[204:207], v[8:11]
	s_cbranch_scc0 .Ldb_FFI_cont
	v_readfirstlane_b32 s101, v186
	s_cmpk_gt_u32 s101, 0xff
	s_cbranch_scc1 .Ldb_FFI_young
	s_barrier
	s_mov_b32 s101, 1
	s_branch .Ldb_FFI_exit

; #define G_STAGE(bufoff, gbase, o0, h64) do { \
;         __builtin_amdgcn_global_load_lds((const unsigned*)((const char*)(gbase) + (o0)), (LAS unsigned*)(lds + (bufoff) + ldsw), 16, 0, 0); \
;         __builtin_amdgcn_global_load_lds((const unsigned*)((const char*)(gbase) + (h64) + (o0)), (LAS unsigned*)(lds + (bufoff) + ldsw + 8192), 16, 0, 0); } while (0)
; #define G_LDA(dst, b, h) do { _Pragma("unroll") for (int m = 0; m < 4; ++m) _Pragma("unroll") for (int k = 0; k < 2; ++k) dst[m][k] = *(const LAS bf16x8*)(lds + G_SA(b, h) + aoff + m * 2048 + k * 1024); } while (0)
; #define G_LDB(dst, b, h) do { _Pragma("unroll") for (int n = 0; n < 2; ++n) _Pragma("unroll") for (int k = 0; k < 2; ++k) dst[n][k] = *(const LAS bf16x8*)(lds + G_SB(b, h) + boff + n * 2048 + k * 1024); } while (0)
; #define G_WAIT_L(n) asm volatile("s_waitcnt lgkmcnt(" #n ")" ::: "memory")
; #define G_BAR __builtin_amdgcn_s_barrier()
; #define G_SCHED __builtin_amdgcn_sched_barrier(0)
;     ...
;     for (;;) {
;         const bool has_next = sched_next<PH, SUB>(E.ws, E.layer, ui + 1, nxt, E.x);
;         if (!has_next) nxt = cur;
;         const char* nA = nxt.A; const char* nB = nxt.B;
; #pragma unroll 1
;         for (int t = 0; t < nt; t += 2) {
;             const bool last = (t == nt - 2);
;             const char* a1 = cA + (size_t)(t + 1) * ckA;
;             const char* a2 = last ? nA : cA + (size_t)(t + 2) * ckA; const char* b2 = last ? nB : cB + (size_t)(t + 2) * kB;
;             const char* a3 = a2 + ckA; const char* b3 = b2 + kB;
;             G_LDB(B0, 0, 0); G_SCHED; G_LDA(At, 0, 0); G_STAGE(G_SA(1, 1), a1 + chA, cA0, qA);
;             G_WAIT_L(8); G_BAR; G_WAIT_L(0); G_MMA(0, 0, At, B0); G_BAR; G_SCHED;
;             G_LDB(B1, 0, 1); G_STAGE(G_SB(0, 0), b2, cB0, qB);
;             G_BAR; G_WAIT_L(0); G_MMA(0, 1, At, B1); G_BAR;
;     ...
; #pragma unroll
;         for (int a = 0; a < 2; ++a)
; #pragma unroll
;             for (int b = 0; b < 2; ++b)
; #pragma unroll
;                 for (int m = 0; m < 4; ++m)
; #pragma unroll
;                     for (int n = 0; n < 2; ++n) acc[a][b][m][n] = (f32x4){0.f, 0.f, 0.f, 0.f};
;         cur = nxt; cA = nA; cB = nB; ++ui;
.LBB0_1184:
	s_add_u32 s2, s2, 0xb0080
	s_addc_u32 s3, s3, 0
	s_add_u32 s6, s6, 0x100
	s_waitcnt lgkmcnt(0)
	v_mov_b64_e32 v[8:9], 0
	s_addc_u32 s7, s7, 0
	s_mov_b32 s21, -2
	v_mov_b64_e32 v[10:11], 0
	v_mov_b64_e32 v[12:13], 0
	v_mov_b64_e32 v[14:15], 0
	v_mov_b64_e32 v[24:25], 0
	v_mov_b64_e32 v[26:27], 0
	v_mov_b64_e32 v[28:29], 0
	v_mov_b64_e32 v[30:31], 0
	v_mov_b64_e32 v[40:41], 0
	v_mov_b64_e32 v[42:43], 0
	v_mov_b64_e32 v[44:45], 0
	v_mov_b64_e32 v[46:47], 0
	v_mov_b64_e32 v[56:57], 0
	v_mov_b64_e32 v[58:59], 0
	v_mov_b64_e32 v[60:61], 0
	v_mov_b64_e32 v[62:63], 0
	v_mov_b64_e32 v[16:17], 0
	v_mov_b64_e32 v[18:19], 0
	v_mov_b64_e32 v[20:21], 0
	v_mov_b64_e32 v[22:23], 0
	v_mov_b64_e32 v[32:33], 0
	v_mov_b64_e32 v[34:35], 0
	v_mov_b64_e32 v[36:37], 0
	v_mov_b64_e32 v[38:39], 0
	v_mov_b64_e32 v[48:49], 0
	v_mov_b64_e32 v[50:51], 0
	v_mov_b64_e32 v[52:53], 0
	v_mov_b64_e32 v[54:55], 0
	v_mov_b64_e32 v[64:65], 0
	v_mov_b64_e32 v[66:67], 0
	v_mov_b64_e32 v[68:69], 0
	v_mov_b64_e32 v[70:71], 0
	v_mov_b64_e32 v[72:73], 0
	v_mov_b64_e32 v[74:75], 0
	v_mov_b64_e32 v[76:77], 0
	v_mov_b64_e32 v[78:79], 0
	v_mov_b64_e32 v[88:89], 0
	v_mov_b64_e32 v[90:91], 0
	v_mov_b64_e32 v[92:93], 0
	v_mov_b64_e32 v[94:95], 0
	v_mov_b64_e32 v[104:105], 0
	v_mov_b64_e32 v[106:107], 0
	v_mov_b64_e32 v[108:109], 0
	v_mov_b64_e32 v[110:111], 0
	v_mov_b64_e32 v[120:121], 0
	v_mov_b64_e32 v[122:123], 0
	v_mov_b64_e32 v[124:125], 0
	v_mov_b64_e32 v[126:127], 0
	v_mov_b64_e32 v[80:81], 0
	v_mov_b64_e32 v[82:83], 0
	v_mov_b64_e32 v[84:85], 0
	v_mov_b64_e32 v[86:87], 0
	v_mov_b64_e32 v[96:97], 0
	v_mov_b64_e32 v[98:99], 0
	v_mov_b64_e32 v[100:101], 0
	v_mov_b64_e32 v[102:103], 0
	v_mov_b64_e32 v[112:113], 0
	v_mov_b64_e32 v[114:115], 0
	v_mov_b64_e32 v[116:117], 0
	v_mov_b64_e32 v[118:119], 0
	v_mov_b64_e32 v[128:129], 0
	v_mov_b64_e32 v[130:131], 0
	v_mov_b64_e32 v[132:133], 0
	v_mov_b64_e32 v[134:135], 0
	s_mov_b64 s[52:53], 0xb0080
	s_mov_b64 s[54:55], 0x108080
	s_cmp_eq_u32 s101, 2
	s_cselect_b32 s101, 0, s101
	v_add_u32_e32 v255, 0x10000, v185
.LBB0_1185:
	s_add_u32 s4, s2, 0xfff50080
	s_addc_u32 s5, s3, -1
	s_add_i32 s33, 0, 0x10000
	ds_read_b128 v[136:139], v255 offset:0
	ds_read_b128 v[140:143], v255 offset:1024
	ds_read_b128 v[144:147], v255 offset:2048
	ds_read_b128 v[148:151], v255 offset:3072
	s_cmp_eq_u32 s21, 40
	s_cselect_b32 s5, s17, s5
	s_cselect_b32 s4, s16, s4
	s_cselect_b32 s23, s19, s7
	s_cselect_b32 s22, s18, s6
	s_add_i32 m0, s26, 0xc000
	ds_read_b128 v[152:155], v195
	ds_read_b128 v[156:159], v195 offset:1024
	ds_read_b128 v[160:163], v195 offset:2048
	ds_read_b128 v[164:167], v195 offset:3072
	ds_read_b128 v[176:179], v195 offset:4096
	ds_read_b128 v[180:183], v195 offset:5120
	ds_read_b128 v[196:199], v195 offset:6144
	ds_read_b128 v[200:203], v195 offset:7168
	global_load_lds_dwordx4 v174, s[2:3]
	s_add_i32 m0, s26, 0xe000
	s_nop 0
	s_add_u32 vcc_lo, s2, s86
	s_addc_u32 vcc_hi, s3, s87
	global_load_lds_dwordx4 v174, vcc
	s_waitcnt lgkmcnt(8)
	s_cmp_eq_u32 s101, 1
	s_cbranch_scc1 .Ldb_FFO_sk
	s_barrier
.Ldb_FFO_sk:
	s_mov_b32 s101, 0
	s_waitcnt lgkmcnt(0)
	v_mfma_f32_16x16x32_bf16 v[132:135], v[136:139], v[152:155], v[132:135]
	v_mfma_f32_16x16x32_bf16 v[128:131], v[144:147], v[152:155], v[128:131]
	v_mfma_f32_16x16x32_bf16 v[116:119], v[136:139], v[160:163], v[116:119]
	v_mfma_f32_16x16x32_bf16 v[112:115], v[144:147], v[160:163], v[112:115]
	v_mfma_f32_16x16x32_bf16 v[100:103], v[136:139], v[176:179], v[100:103]
	v_mfma_f32_16x16x32_bf16 v[96:99], v[144:147], v[176:179], v[96:99]
	v_mfma_f32_16x16x32_bf16 v[84:87], v[136:139], v[196:199], v[84:87]
	v_mfma_f32_16x16x32_bf16 v[80:83], v[144:147], v[196:199], v[80:83]
	v_mfma_f32_16x16x32_bf16 v[132:135], v[140:143], v[156:159], v[132:135]
	v_mfma_f32_16x16x32_bf16 v[128:131], v[148:151], v[156:159], v[128:131]
	v_mfma_f32_16x16x32_bf16 v[116:119], v[140:143], v[164:167], v[116:119]
	v_mfma_f32_16x16x32_bf16 v[112:115], v[148:151], v[164:167], v[112:115]
	v_mfma_f32_16x16x32_bf16 v[100:103], v[140:143], v[180:183], v[100:103]
	v_mfma_f32_16x16x32_bf16 v[96:99], v[148:151], v[180:183], v[96:99]
	v_mfma_f32_16x16x32_bf16 v[84:87], v[140:143], v[200:203], v[84:87]
	v_mfma_f32_16x16x32_bf16 v[80:83], v[148:151], v[200:203], v[80:83]
	s_barrier
	s_add_i32 s44, 0, 0x14000
	s_add_i32 s100, s33, s25
	s_mov_b32 m0, s100
	ds_read_b128 v[204:207], v255 offset:16384
	ds_read_b128 v[208:211], v255 offset:17408
	ds_read_b128 v[212:215], v255 offset:18432
	ds_read_b128 v[216:219], v255 offset:19456
	global_load_lds_dwordx4 v172, s[22:23]
	s_add_i32 m0, s100, 0x2000
	s_nop 0
	s_add_u32 vcc_lo, s22, s86
	s_addc_u32 vcc_hi, s23, s87
	global_load_lds_dwordx4 v172, vcc
	s_barrier
	s_waitcnt lgkmcnt(0)
	v_mfma_f32_16x16x32_bf16 v[124:127], v[204:207], v[152:155], v[124:127]
	v_mfma_f32_16x16x32_bf16 v[120:123], v[212:215], v[152:155], v[120:123]
	v_mfma_f32_16x16x32_bf16 v[108:111], v[204:207], v[160:163], v[108:111]
	v_mfma_f32_16x16x32_bf16 v[104:107], v[212:215], v[160:163], v[104:107]
	v_mfma_f32_16x16x32_bf16 v[92:95], v[204:207], v[176:179], v[92:95]
	v_mfma_f32_16x16x32_bf16 v[88:91], v[212:215], v[176:179], v[88:91]
	v_mfma_f32_16x16x32_bf16 v[76:79], v[204:207], v[196:199], v[76:79]
	v_mfma_f32_16x16x32_bf16 v[72:75], v[212:215], v[196:199], v[72:75]
	v_mfma_f32_16x16x32_bf16 v[124:127], v[208:211], v[156:159], v[124:127]
	v_mfma_f32_16x16x32_bf16 v[120:123], v[216:219], v[156:159], v[120:123]
	v_mfma_f32_16x16x32_bf16 v[108:111], v[208:211], v[164:167], v[108:111]
	v_mfma_f32_16x16x32_bf16 v[104:107], v[216:219], v[164:167], v[104:107]
	v_mfma_f32_16x16x32_bf16 v[92:95], v[208:211], v[180:183], v[92:95]
	v_mfma_f32_16x16x32_bf16 v[88:91], v[216:219], v[180:183], v[88:91]
	v_mfma_f32_16x16x32_bf16 v[76:79], v[208:211], v[200:203], v[76:79]
	v_mfma_f32_16x16x32_bf16 v[72:75], v[216:219], v[200:203], v[72:75]
	s_barrier
; #define G_STAGE(bufoff, gbase, o0, h64) do { \
;         __builtin_amdgcn_global_load_lds((const unsigned*)((const char*)(gbase) + (o0)), (LAS unsigned*)(lds + (bufoff) + ldsw), 16, 0, 0); \
;         __builtin_amdgcn_global_load_lds((const unsigned*)((const char*)(gbase) + (h64) + (o0)), (LAS unsigned*)(lds + (bufoff) + ldsw + 8192), 16, 0, 0); } while (0)
; #define G_LDA(dst, b, h) do { _Pragma("unroll") for (int m = 0; m < 4; ++m) _Pragma("unroll") for (int k = 0; k < 2; ++k) dst[m][k] = *(const LAS bf16x8*)(lds + G_SA(b, h) + aoff + m * 2048 + k * 1024); } while (0)
; #define G_LDB(dst, b, h) do { _Pragma("unroll") for (int n = 0; n < 2; ++n) _Pragma("unroll") for (int k = 0; k < 2; ++k) dst[n][k] = *(const LAS bf16x8*)(lds + G_SB(b, h) + boff + n * 2048 + k * 1024); } while (0)
; #define G_WAIT_V(n) asm volatile("s_waitcnt vmcnt(" #n ")" ::: "memory")
; #define G_WAIT_L(n) asm volatile("s_waitcnt lgkmcnt(" #n ")" ::: "memory")
; #define G_BAR __builtin_amdgcn_s_barrier()
; #define G_SCHED __builtin_amdgcn_sched_barrier(0)
;     ...
;             G_LDB(B1, 0, 1); G_STAGE(G_SB(0, 0), b2, cB0, qB);
;             G_BAR; G_WAIT_L(0); G_MMA(0, 1, At, B1); G_BAR;
;             G_LDA(At, 0, 1); G_STAGE(G_SA(0, 0), a2, cA0, qA);
;             G_BAR; G_WAIT_L(0); G_MMA(1, 0, At, B0); G_BAR; G_SCHED;
;             G_STAGE(G_SB(0, 1), b2 + chB, cB0, qB);
;             G_WAIT_V(6); G_BAR; G_MMA(1, 1, At, B1); G_BAR;
;             G_LDB(B0, 1, 0); G_SCHED; G_LDA(At, 1, 0); G_STAGE(G_SA(0, 1), a2 + chA, cA0, qA);
;             G_WAIT_L(8); G_BAR; G_WAIT_L(0); G_MMA(0, 0, At, B0); G_BAR; G_SCHED;
;             G_LDB(B1, 1, 1); G_STAGE(G_SB(1, 0), b3, cB0, qB);
	s_mov_b32 m0, s26
	v_lshl_add_u64 v[222:223], s[4:5], 0, v[2:3]
	ds_read_b128 v[152:155], v195 offset:16384
	ds_read_b128 v[156:159], v195 offset:17408
	ds_read_b128 v[160:163], v195 offset:18432
	ds_read_b128 v[164:167], v195 offset:19456
	ds_read_b128 v[176:179], v195 offset:20480
	ds_read_b128 v[180:183], v195 offset:21504
	ds_read_b128 v[196:199], v195 offset:22528
	ds_read_b128 v[200:203], v195 offset:23552
	global_load_lds_dwordx4 v2, s[4:5]
	s_mov_b32 m0, s27
	s_nop 0
	s_add_u32 vcc_lo, s4, s86
	s_addc_u32 vcc_hi, s5, s87
	global_load_lds_dwordx4 v2, vcc
	s_barrier
	s_waitcnt lgkmcnt(0)
	v_mfma_f32_16x16x32_bf16 v[68:71], v[136:139], v[152:155], v[68:71]
	v_mfma_f32_16x16x32_bf16 v[64:67], v[144:147], v[152:155], v[64:67]
	v_mfma_f32_16x16x32_bf16 v[52:55], v[136:139], v[160:163], v[52:55]
	v_mfma_f32_16x16x32_bf16 v[48:51], v[144:147], v[160:163], v[48:51]
	v_mfma_f32_16x16x32_bf16 v[36:39], v[136:139], v[176:179], v[36:39]
	v_mfma_f32_16x16x32_bf16 v[32:35], v[144:147], v[176:179], v[32:35]
	v_mfma_f32_16x16x32_bf16 v[20:23], v[136:139], v[196:199], v[20:23]
	v_mfma_f32_16x16x32_bf16 v[16:19], v[144:147], v[196:199], v[16:19]
	v_mfma_f32_16x16x32_bf16 v[68:71], v[140:143], v[156:159], v[68:71]
	v_mfma_f32_16x16x32_bf16 v[64:67], v[148:151], v[156:159], v[64:67]
	v_mfma_f32_16x16x32_bf16 v[52:55], v[140:143], v[164:167], v[52:55]
	v_mfma_f32_16x16x32_bf16 v[48:51], v[148:151], v[164:167], v[48:51]
	v_mfma_f32_16x16x32_bf16 v[36:39], v[140:143], v[180:183], v[36:39]
	v_mfma_f32_16x16x32_bf16 v[32:35], v[148:151], v[180:183], v[32:35]
	v_mfma_f32_16x16x32_bf16 v[20:23], v[140:143], v[200:203], v[20:23]
	v_mfma_f32_16x16x32_bf16 v[16:19], v[148:151], v[200:203], v[16:19]
	s_barrier
	s_add_i32 s100, s44, s25
	s_mov_b32 m0, s100
	s_nop 0
	s_add_u32 vcc_lo, s22, s88
	s_addc_u32 vcc_hi, s23, s89
	global_load_lds_dwordx4 v172, vcc
	s_add_i32 m0, s100, 0x2000
	s_nop 0
	s_add_u32 vcc_lo, s22, s64
	s_addc_u32 vcc_hi, s23, s65
	global_load_lds_dwordx4 v172, vcc
	s_waitcnt vmcnt(6)
	s_barrier
	v_mfma_f32_16x16x32_bf16 v[60:63], v[204:207], v[152:155], v[60:63]
	v_mfma_f32_16x16x32_bf16 v[56:59], v[212:215], v[152:155], v[56:59]
	v_mfma_f32_16x16x32_bf16 v[44:47], v[204:207], v[160:163], v[44:47]
	v_mfma_f32_16x16x32_bf16 v[40:43], v[212:215], v[160:163], v[40:43]
	v_mfma_f32_16x16x32_bf16 v[28:31], v[204:207], v[176:179], v[28:31]
	v_mfma_f32_16x16x32_bf16 v[24:27], v[212:215], v[176:179], v[24:27]
	v_mfma_f32_16x16x32_bf16 v[12:15], v[204:207], v[196:199], v[12:15]
	v_mfma_f32_16x16x32_bf16 v[8:11], v[212:215], v[196:199], v[8:11]
	v_mfma_f32_16x16x32_bf16 v[60:63], v[208:211], v[156:159], v[60:63]
	v_mfma_f32_16x16x32_bf16 v[56:59], v[216:219], v[156:159], v[56:59]
	v_mfma_f32_16x16x32_bf16 v[44:47], v[208:211], v[164:167], v[44:47]
	v_mfma_f32_16x16x32_bf16 v[40:43], v[216:219], v[164:167], v[40:43]
	v_mfma_f32_16x16x32_bf16 v[28:31], v[208:211], v[180:183], v[28:31]
	v_mfma_f32_16x16x32_bf16 v[24:27], v[216:219], v[180:183], v[24:27]
	v_mfma_f32_16x16x32_bf16 v[12:15], v[208:211], v[200:203], v[12:15]
	v_mfma_f32_16x16x32_bf16 v[8:11], v[216:219], v[200:203], v[8:11]
	s_barrier
	s_add_i32 s100, 0, 0x18000
	ds_read_b128 v[136:139], v255 offset:32768
	ds_read_b128 v[140:143], v255 offset:33792
	ds_read_b128 v[144:147], v255 offset:34816
	ds_read_b128 v[148:151], v255 offset:35840
	s_mov_b32 m0, s29
	ds_read_b128 v[152:155], v195 offset:32768
	ds_read_b128 v[156:159], v195 offset:33792
	ds_read_b128 v[160:163], v195 offset:34816
	ds_read_b128 v[164:167], v195 offset:35840
	ds_read_b128 v[176:179], v195 offset:36864
	ds_read_b128 v[180:183], v195 offset:37888
	ds_read_b128 v[196:199], v195 offset:38912
	ds_read_b128 v[200:203], v195 offset:39936
	s_add_u32 vcc_lo, s4, s88
	s_addc_u32 vcc_hi, s5, s89
	global_load_lds_dwordx4 v2, vcc
	s_mov_b32 m0, s30
	s_nop 0
	s_add_u32 vcc_lo, s4, s64
	s_addc_u32 vcc_hi, s5, s65
	global_load_lds_dwordx4 v2, vcc
	s_waitcnt lgkmcnt(8)
	s_barrier
	s_waitcnt lgkmcnt(0)
	v_mfma_f32_16x16x32_bf16 v[132:135], v[136:139], v[152:155], v[132:135]
	v_mfma_f32_16x16x32_bf16 v[128:131], v[144:147], v[152:155], v[128:131]
	v_mfma_f32_16x16x32_bf16 v[116:119], v[136:139], v[160:163], v[116:119]
	v_mfma_f32_16x16x32_bf16 v[112:115], v[144:147], v[160:163], v[112:115]
	v_mfma_f32_16x16x32_bf16 v[100:103], v[136:139], v[176:179], v[100:103]
	v_mfma_f32_16x16x32_bf16 v[96:99], v[144:147], v[176:179], v[96:99]
	v_mfma_f32_16x16x32_bf16 v[84:87], v[136:139], v[196:199], v[84:87]
	v_mfma_f32_16x16x32_bf16 v[80:83], v[144:147], v[196:199], v[80:83]
	v_mfma_f32_16x16x32_bf16 v[132:135], v[140:143], v[156:159], v[132:135]
	v_mfma_f32_16x16x32_bf16 v[128:131], v[148:151], v[156:159], v[128:131]
	v_mfma_f32_16x16x32_bf16 v[116:119], v[140:143], v[164:167], v[116:119]
	v_mfma_f32_16x16x32_bf16 v[112:115], v[148:151], v[164:167], v[112:115]
	v_mfma_f32_16x16x32_bf16 v[100:103], v[140:143], v[180:183], v[100:103]
	v_mfma_f32_16x16x32_bf16 v[96:99], v[148:151], v[180:183], v[96:99]
	v_mfma_f32_16x16x32_bf16 v[84:87], v[140:143], v[200:203], v[84:87]
	v_mfma_f32_16x16x32_bf16 v[80:83], v[148:151], v[200:203], v[80:83]
	s_barrier
; #define G_STAGE(bufoff, gbase, o0, h64) do { \
;         __builtin_amdgcn_global_load_lds((const unsigned*)((const char*)(gbase) + (o0)), (LAS unsigned*)(lds + (bufoff) + ldsw), 16, 0, 0); \
;         __builtin_amdgcn_global_load_lds((const unsigned*)((const char*)(gbase) + (h64) + (o0)), (LAS unsigned*)(lds + (bufoff) + ldsw + 8192), 16, 0, 0); } while (0)
; #define G_LDA(dst, b, h) do { _Pragma("unroll") for (int m = 0; m < 4; ++m) _Pragma("unroll") for (int k = 0; k < 2; ++k) dst[m][k] = *(const LAS bf16x8*)(lds + G_SA(b, h) + aoff + m * 2048 + k * 1024); } while (0)
; #define G_LDB(dst, b, h) do { _Pragma("unroll") for (int n = 0; n < 2; ++n) _Pragma("unroll") for (int k = 0; k < 2; ++k) dst[n][k] = *(const LAS bf16x8*)(lds + G_SB(b, h) + boff + n * 2048 + k * 1024); } while (0)
; #define G_WAIT_V(n) asm volatile("s_waitcnt vmcnt(" #n ")" ::: "memory")
; #define G_WAIT_L(n) asm volatile("s_waitcnt lgkmcnt(" #n ")" ::: "memory")
; #define G_BAR __builtin_amdgcn_s_barrier()
; #define G_SCHED __builtin_amdgcn_sched_barrier(0)
;     ...
;             G_LDB(B1, 1, 1); G_STAGE(G_SB(1, 0), b3, cB0, qB);
;             G_BAR; G_WAIT_L(0); G_MMA(0, 1, At, B1); G_BAR;
;             G_LDA(At, 1, 1); G_STAGE(G_SA(1, 0), a3, cA0, qA);
;             G_BAR; G_WAIT_L(0); G_MMA(1, 0, At, B0); G_BAR; G_SCHED;
;             G_STAGE(G_SB(1, 1), b3 + chB, cB0, qB);
;             G_WAIT_V(6); G_BAR; G_MMA(1, 1, At, B1); G_BAR;
;         }
	s_add_i32 s5, 0, 0x1c000
	s_add_i32 s4, s100, s25
	s_mov_b32 m0, s4
	ds_read_b128 v[204:207], v255 offset:49152
	ds_read_b128 v[208:211], v255 offset:50176
	ds_read_b128 v[212:215], v255 offset:51200
	ds_read_b128 v[216:219], v255 offset:52224
	s_add_u32 vcc_lo, s22, s46
	s_addc_u32 vcc_hi, s23, s47
	global_load_lds_dwordx4 v172, vcc
	s_add_i32 m0, s4, 0x2000
	s_nop 0
	s_add_u32 vcc_lo, s22, s66
	s_addc_u32 vcc_hi, s23, s67
	global_load_lds_dwordx4 v172, vcc
	s_barrier
	s_waitcnt lgkmcnt(0)
	v_mfma_f32_16x16x32_bf16 v[124:127], v[204:207], v[152:155], v[124:127]
	v_mfma_f32_16x16x32_bf16 v[120:123], v[212:215], v[152:155], v[120:123]
	v_mfma_f32_16x16x32_bf16 v[108:111], v[204:207], v[160:163], v[108:111]
	v_mfma_f32_16x16x32_bf16 v[104:107], v[212:215], v[160:163], v[104:107]
	v_mfma_f32_16x16x32_bf16 v[92:95], v[204:207], v[176:179], v[92:95]
	v_mfma_f32_16x16x32_bf16 v[88:91], v[212:215], v[176:179], v[88:91]
	v_mfma_f32_16x16x32_bf16 v[76:79], v[204:207], v[196:199], v[76:79]
	v_mfma_f32_16x16x32_bf16 v[72:75], v[212:215], v[196:199], v[72:75]
	v_mfma_f32_16x16x32_bf16 v[124:127], v[208:211], v[156:159], v[124:127]
	v_mfma_f32_16x16x32_bf16 v[120:123], v[216:219], v[156:159], v[120:123]
	v_mfma_f32_16x16x32_bf16 v[108:111], v[208:211], v[164:167], v[108:111]
	v_mfma_f32_16x16x32_bf16 v[104:107], v[216:219], v[164:167], v[104:107]
	v_mfma_f32_16x16x32_bf16 v[92:95], v[208:211], v[180:183], v[92:95]
	v_mfma_f32_16x16x32_bf16 v[88:91], v[216:219], v[180:183], v[88:91]
	v_mfma_f32_16x16x32_bf16 v[76:79], v[208:211], v[200:203], v[76:79]
	v_mfma_f32_16x16x32_bf16 v[72:75], v[216:219], v[200:203], v[72:75]
	s_barrier
	s_mov_b32 m0, s31
	v_lshl_add_u64 v[224:225], v[222:223], 0, s[46:47]
	ds_read_b128 v[152:155], v195 offset:49152
	ds_read_b128 v[156:159], v195 offset:50176
	ds_read_b128 v[160:163], v195 offset:51200
	ds_read_b128 v[164:167], v195 offset:52224
	ds_read_b128 v[176:179], v195 offset:53248
	ds_read_b128 v[180:183], v195 offset:54272
	ds_read_b128 v[196:199], v195 offset:55296
	ds_read_b128 v[200:203], v195 offset:56320
	global_load_lds_dwordx4 v[224:225], off
	v_lshl_add_u64 v[222:223], v[222:223], 0, s[66:67]
	s_mov_b32 m0, s34
	s_nop 0
	global_load_lds_dwordx4 v[222:223], off
	s_barrier
	s_waitcnt lgkmcnt(0)
	v_mfma_f32_16x16x32_bf16 v[68:71], v[136:139], v[152:155], v[68:71]
	v_mfma_f32_16x16x32_bf16 v[64:67], v[144:147], v[152:155], v[64:67]
	v_mfma_f32_16x16x32_bf16 v[52:55], v[136:139], v[160:163], v[52:55]
	v_mfma_f32_16x16x32_bf16 v[48:51], v[144:147], v[160:163], v[48:51]
	v_mfma_f32_16x16x32_bf16 v[36:39], v[136:139], v[176:179], v[36:39]
	v_mfma_f32_16x16x32_bf16 v[32:35], v[144:147], v[176:179], v[32:35]
	v_mfma_f32_16x16x32_bf16 v[20:23], v[136:139], v[196:199], v[20:23]
	v_mfma_f32_16x16x32_bf16 v[16:19], v[144:147], v[196:199], v[16:19]
	v_mfma_f32_16x16x32_bf16 v[68:71], v[140:143], v[156:159], v[68:71]
	v_mfma_f32_16x16x32_bf16 v[64:67], v[148:151], v[156:159], v[64:67]
	v_mfma_f32_16x16x32_bf16 v[52:55], v[140:143], v[164:167], v[52:55]
	v_mfma_f32_16x16x32_bf16 v[48:51], v[148:151], v[164:167], v[48:51]
	v_mfma_f32_16x16x32_bf16 v[36:39], v[140:143], v[180:183], v[36:39]
	v_mfma_f32_16x16x32_bf16 v[32:35], v[148:151], v[180:183], v[32:35]
	v_mfma_f32_16x16x32_bf16 v[20:23], v[140:143], v[200:203], v[20:23]
	v_mfma_f32_16x16x32_bf16 v[16:19], v[148:151], v[200:203], v[16:19]
	s_barrier
	s_add_i32 s4, s5, s25
	s_mov_b32 m0, s4
	s_nop 0
	s_add_u32 vcc_lo, s22, s52
	s_addc_u32 vcc_hi, s23, s53
	global_load_lds_dwordx4 v172, vcc
	s_add_i32 m0, s4, 0x2000
	s_nop 0
	s_add_u32 vcc_lo, s22, s54
	s_addc_u32 vcc_hi, s23, s55
	global_load_lds_dwordx4 v172, vcc
	s_add_i32 s21, s21, 2
	s_add_u32 s2, s2, 0x100
	s_addc_u32 s3, s3, 0
	s_add_u32 s6, s6, 0x100
	s_addc_u32 s7, s7, 0
	s_cmp_gt_u32 s21, 41
	s_waitcnt vmcnt(6)
	s_barrier
	v_mfma_f32_16x16x32_bf16 v[60:63], v[204:207], v[152:155], v[60:63]
	v_mfma_f32_16x16x32_bf16 v[56:59], v[212:215], v[152:155], v[56:59]
	v_mfma_f32_16x16x32_bf16 v[44:47], v[204:207], v[160:163], v[44:47]
	v_mfma_f32_16x16x32_bf16 v[40:43], v[212:215], v[160:163], v[40:43]
	v_mfma_f32_16x16x32_bf16 v[28:31], v[204:207], v[176:179], v[28:31]
	v_mfma_f32_16x16x32_bf16 v[24:27], v[212:215], v[176:179], v[24:27]
	v_mfma_f32_16x16x32_bf16 v[12:15], v[204:207], v[196:199], v[12:15]
	v_mfma_f32_16x16x32_bf16 v[8:11], v[212:215], v[196:199], v[8:11]
	v_mfma_f32_16x16x32_bf16 v[60:63], v[208:211], v[156:159], v[60:63]
	v_mfma_f32_16x16x32_bf16 v[56:59], v[216:219], v[156:159], v[56:59]
	v_mfma_f32_16x16x32_bf16 v[44:47], v[208:211], v[164:167], v[44:47]
	v_mfma_f32_16x16x32_bf16 v[40:43], v[216:219], v[164:167], v[40:43]
	v_mfma_f32_16x16x32_bf16 v[28:31], v[208:211], v[180:183], v[28:31]
	v_mfma_f32_16x16x32_bf16 v[24:27], v[216:219], v[180:183], v[24:27]
	v_mfma_f32_16x16x32_bf16 v[12:15], v[208:211], v[200:203], v[12:15]
	v_mfma_f32_16x16x32_bf16 v[8:11], v[216:219], v[200:203], v[8:11]
	s_cbranch_scc0 .Ldb_FFO_cont
	v_readfirstlane_b32 s101, v186
	s_cmpk_gt_u32 s101, 0xff
	s_cbranch_scc1 .Ldb_FFO_young
	s_barrier
	s_mov_b32 s101, 1
	s_branch .Ldb_FFO_exit

; #define G_STAGE(bufoff, gbase, o0, h64) do { \
;         __builtin_amdgcn_global_load_lds((const unsigned*)((const char*)(gbase) + (o0)), (LAS unsigned*)(lds + (bufoff) + ldsw), 16, 0, 0); \
;         __builtin_amdgcn_global_load_lds((const unsigned*)((const char*)(gbase) + (h64) + (o0)), (LAS unsigned*)(lds + (bufoff) + ldsw + 8192), 16, 0, 0); } while (0)
; #define G_LDA(dst, b, h) do { _Pragma("unroll") for (int m = 0; m < 4; ++m) _Pragma("unroll") for (int k = 0; k < 2; ++k) dst[m][k] = *(const LAS bf16x8*)(lds + G_SA(b, h) + aoff + m * 2048 + k * 1024); } while (0)
; #define G_LDB(dst, b, h) do { _Pragma("unroll") for (int n = 0; n < 2; ++n) _Pragma("unroll") for (int k = 0; k < 2; ++k) dst[n][k] = *(const LAS bf16x8*)(lds + G_SB(b, h) + boff + n * 2048 + k * 1024); } while (0)
; #define G_WAIT_L(n) asm volatile("s_waitcnt lgkmcnt(" #n ")" ::: "memory")
; #define G_BAR __builtin_amdgcn_s_barrier()
; #define G_SCHED __builtin_amdgcn_sched_barrier(0)
;     ...
;     for (;;) {
;         const bool has_next = sched_next<PH, SUB>(E.ws, E.layer, ui + 1, nxt, E.x);
;         if (!has_next) nxt = cur;
;         const char* nA = nxt.A; const char* nB = nxt.B;
; #pragma unroll 1
;         for (int t = 0; t < nt; t += 2) {
;             const bool last = (t == nt - 2);
;             const char* a1 = cA + (size_t)(t + 1) * ckA;
;             const char* a2 = last ? nA : cA + (size_t)(t + 2) * ckA; const char* b2 = last ? nB : cB + (size_t)(t + 2) * kB;
;             const char* a3 = a2 + ckA; const char* b3 = b2 + kB;
;             G_LDB(B0, 0, 0); G_SCHED; G_LDA(At, 0, 0); G_STAGE(G_SA(1, 1), a1 + chA, cA0, qA);
;             G_WAIT_L(8); G_BAR; G_WAIT_L(0); G_MMA(0, 0, At, B0); G_BAR; G_SCHED;
;             G_LDB(B1, 0, 1); G_STAGE(G_SB(0, 0), b2, cB0, qB);
;             G_BAR; G_WAIT_L(0); G_MMA(0, 1, At, B1); G_BAR;
;     ...
; #pragma unroll
;         for (int a = 0; a < 2; ++a)
; #pragma unroll
;             for (int b = 0; b < 2; ++b)
; #pragma unroll
;                 for (int m = 0; m < 4; ++m)
; #pragma unroll
;                     for (int n = 0; n < 2; ++n) acc[a][b][m][n] = (f32x4){0.f, 0.f, 0.f, 0.f};
;         cur = nxt; cA = nA; cB = nB; ++ui;
.LBB0_1259:
	v_mov_b64_e32 v[8:9], 0
	s_mov_b64 s[18:19], 0
	s_mov_b64 s[14:15], -1
	s_mov_b64 s[16:17], 0
	v_mov_b64_e32 v[10:11], 0
	v_mov_b64_e32 v[12:13], 0
	v_mov_b64_e32 v[14:15], 0
	v_mov_b64_e32 v[16:17], 0
	v_mov_b64_e32 v[18:19], 0
	v_mov_b64_e32 v[24:25], 0
	v_mov_b64_e32 v[26:27], 0
	v_mov_b64_e32 v[32:33], 0
	v_mov_b64_e32 v[34:35], 0
	v_mov_b64_e32 v[40:41], 0
	v_mov_b64_e32 v[42:43], 0
	v_mov_b64_e32 v[48:49], 0
	v_mov_b64_e32 v[50:51], 0
	v_mov_b64_e32 v[56:57], 0
	v_mov_b64_e32 v[58:59], 0
	v_mov_b64_e32 v[20:21], 0
	v_mov_b64_e32 v[22:23], 0
	v_mov_b64_e32 v[28:29], 0
	v_mov_b64_e32 v[30:31], 0
	v_mov_b64_e32 v[36:37], 0
	v_mov_b64_e32 v[38:39], 0
	v_mov_b64_e32 v[44:45], 0
	v_mov_b64_e32 v[46:47], 0
	v_mov_b64_e32 v[52:53], 0
	v_mov_b64_e32 v[54:55], 0
	v_mov_b64_e32 v[60:61], 0
	v_mov_b64_e32 v[62:63], 0
	v_mov_b64_e32 v[64:65], 0
	v_mov_b64_e32 v[66:67], 0
	v_mov_b64_e32 v[68:69], 0
	v_mov_b64_e32 v[70:71], 0
	v_mov_b64_e32 v[72:73], 0
	v_mov_b64_e32 v[74:75], 0
	v_mov_b64_e32 v[76:77], 0
	v_mov_b64_e32 v[78:79], 0
	v_mov_b64_e32 v[80:81], 0
	v_mov_b64_e32 v[82:83], 0
	v_mov_b64_e32 v[88:89], 0
	v_mov_b64_e32 v[90:91], 0
	v_mov_b64_e32 v[96:97], 0
	v_mov_b64_e32 v[98:99], 0
	v_mov_b64_e32 v[104:105], 0
	v_mov_b64_e32 v[106:107], 0
	v_mov_b64_e32 v[112:113], 0
	v_mov_b64_e32 v[114:115], 0
	v_mov_b64_e32 v[120:121], 0
	v_mov_b64_e32 v[122:123], 0
	v_mov_b64_e32 v[84:85], 0
	v_mov_b64_e32 v[86:87], 0
	v_mov_b64_e32 v[92:93], 0
	v_mov_b64_e32 v[94:95], 0
	v_mov_b64_e32 v[100:101], 0
	v_mov_b64_e32 v[102:103], 0
	v_mov_b64_e32 v[108:109], 0
	v_mov_b64_e32 v[110:111], 0
	v_mov_b64_e32 v[116:117], 0
	v_mov_b64_e32 v[118:119], 0
	v_mov_b64_e32 v[124:125], 0
	v_mov_b64_e32 v[126:127], 0
	v_mov_b64_e32 v[128:129], 0
	v_mov_b64_e32 v[130:131], 0
	v_mov_b64_e32 v[132:133], 0
	v_mov_b64_e32 v[134:135], 0
	s_mov_b64 s[58:59], 0x10000
	s_cmp_eq_u32 s101, 2
	s_cselect_b32 s101, 0, s101
	v_add_u32_e32 v255, 0x10000, v137
.LBB0_1260:
	s_add_u32 s22, s10, s18
	s_addc_u32 s23, s11, s19
	s_add_u32 s20, s22, 0x100
	s_addc_u32 s21, s23, 0
	s_and_b64 s[4:5], s[16:17], exec
	s_cselect_b32 s20, s6, s20
	s_cselect_b32 s21, s7, s21
	s_add_u32 s4, s12, s18
	s_addc_u32 s5, s13, s19
	s_add_u32 s18, s4, 0x100
	s_addc_u32 s19, s5, 0
	s_add_i32 s44, 0, 0x10000
	ds_read_b128 v[140:143], v255 offset:0
	ds_read_b128 v[144:147], v255 offset:1024
	ds_read_b128 v[148:151], v255 offset:2048
	ds_read_b128 v[152:155], v255 offset:3072
	s_and_b64 s[4:5], s[16:17], exec
	s_cselect_b32 s16, s8, s18
	s_cselect_b32 s17, s9, s19
	s_add_i32 s5, 0, 0x14000
	s_add_i32 s43, 0, 0x18000
	s_add_i32 s18, 0, 0x1c000
	s_add_i32 s45, s44, s25
	s_add_i32 s51, s5, s25
	s_add_i32 s19, s43, s25
	s_add_i32 s53, s18, s25
	s_mov_b64 s[64:65], 0x8000
	s_mov_b64 s[62:63], 0x10080
	s_add_i32 m0, s31, 0xc000
	s_add_i32 s4, s31, 0xe000
	s_add_i32 s54, s45, 0x2000
	s_add_i32 s50, s51, 0x2000
	s_add_i32 s44, s19, 0x2000
	s_add_i32 s52, s53, 0x2000
	ds_read_b128 v[156:159], v138
	ds_read_b128 v[160:163], v138 offset:1024
	ds_read_b128 v[164:167], v138 offset:2048
	ds_read_b128 v[172:175], v138 offset:3072
	ds_read_b128 v[176:179], v138 offset:4096
	ds_read_b128 v[180:183], v138 offset:5120
	ds_read_b128 v[196:199], v138 offset:6144
	ds_read_b128 v[200:203], v138 offset:7168
	s_add_u32 vcc_lo, s22, s62
	s_addc_u32 vcc_hi, s23, s63
	global_load_lds_dwordx4 v2, vcc
	s_mov_b32 m0, s4
	s_nop 0
	s_add_u32 vcc_lo, s22, s68
	s_addc_u32 vcc_hi, s23, s69
	global_load_lds_dwordx4 v2, vcc
	s_waitcnt lgkmcnt(8)
	s_cmp_eq_u32 s101, 1
	s_cbranch_scc1 .Ldb_PLE0_sk
	s_barrier
.Ldb_PLE0_sk:
	s_mov_b32 s101, 0
	s_waitcnt lgkmcnt(0)
	v_mfma_f32_16x16x32_bf16 v[132:135], v[140:143], v[156:159], v[132:135]
	v_mfma_f32_16x16x32_bf16 v[128:131], v[148:151], v[156:159], v[128:131]
	v_mfma_f32_16x16x32_bf16 v[124:127], v[140:143], v[164:167], v[124:127]
	v_mfma_f32_16x16x32_bf16 v[116:119], v[148:151], v[164:167], v[116:119]
	v_mfma_f32_16x16x32_bf16 v[108:111], v[140:143], v[176:179], v[108:111]
	v_mfma_f32_16x16x32_bf16 v[100:103], v[148:151], v[176:179], v[100:103]
	v_mfma_f32_16x16x32_bf16 v[92:95], v[140:143], v[196:199], v[92:95]
	v_mfma_f32_16x16x32_bf16 v[84:87], v[148:151], v[196:199], v[84:87]
	v_mfma_f32_16x16x32_bf16 v[132:135], v[144:147], v[160:163], v[132:135]
	v_mfma_f32_16x16x32_bf16 v[128:131], v[152:155], v[160:163], v[128:131]
	v_mfma_f32_16x16x32_bf16 v[124:127], v[144:147], v[172:175], v[124:127]
	v_mfma_f32_16x16x32_bf16 v[116:119], v[152:155], v[172:175], v[116:119]
	v_mfma_f32_16x16x32_bf16 v[108:111], v[144:147], v[180:183], v[108:111]
	v_mfma_f32_16x16x32_bf16 v[100:103], v[152:155], v[180:183], v[100:103]
	v_mfma_f32_16x16x32_bf16 v[92:95], v[144:147], v[200:203], v[92:95]
	v_mfma_f32_16x16x32_bf16 v[84:87], v[152:155], v[200:203], v[84:87]
	s_barrier
	s_mov_b32 m0, s45
	v_lshl_add_u64 v[184:185], s[16:17], 0, v[0:1]
	ds_read_b128 v[204:207], v255 offset:16384
	ds_read_b128 v[208:211], v255 offset:17408
	ds_read_b128 v[212:215], v255 offset:18432
	ds_read_b128 v[216:219], v255 offset:19456
	global_load_lds_dwordx4 v0, s[16:17]
	s_mov_b32 m0, s54
	s_nop 0
	s_add_u32 vcc_lo, s16, s64
	s_addc_u32 vcc_hi, s17, s65
	global_load_lds_dwordx4 v0, vcc
	s_barrier
; #define G_STAGE(bufoff, gbase, o0, h64) do { \
;         __builtin_amdgcn_global_load_lds((const unsigned*)((const char*)(gbase) + (o0)), (LAS unsigned*)(lds + (bufoff) + ldsw), 16, 0, 0); \
;         __builtin_amdgcn_global_load_lds((const unsigned*)((const char*)(gbase) + (h64) + (o0)), (LAS unsigned*)(lds + (bufoff) + ldsw + 8192), 16, 0, 0); } while (0)
; #define G_LDA(dst, b, h) do { _Pragma("unroll") for (int m = 0; m < 4; ++m) _Pragma("unroll") for (int k = 0; k < 2; ++k) dst[m][k] = *(const LAS bf16x8*)(lds + G_SA(b, h) + aoff + m * 2048 + k * 1024); } while (0)
; #define G_LDB(dst, b, h) do { _Pragma("unroll") for (int n = 0; n < 2; ++n) _Pragma("unroll") for (int k = 0; k < 2; ++k) dst[n][k] = *(const LAS bf16x8*)(lds + G_SB(b, h) + boff + n * 2048 + k * 1024); } while (0)
; #define G_WAIT_V(n) asm volatile("s_waitcnt vmcnt(" #n ")" ::: "memory")
; #define G_WAIT_L(n) asm volatile("s_waitcnt lgkmcnt(" #n ")" ::: "memory")
; #define G_BAR __builtin_amdgcn_s_barrier()
; #define G_SCHED __builtin_amdgcn_sched_barrier(0)
;     ...
;             G_LDB(B1, 0, 1); G_STAGE(G_SB(0, 0), b2, cB0, qB);
;             G_BAR; G_WAIT_L(0); G_MMA(0, 1, At, B1); G_BAR;
;             G_LDA(At, 0, 1); G_STAGE(G_SA(0, 0), a2, cA0, qA);
;             G_BAR; G_WAIT_L(0); G_MMA(1, 0, At, B0); G_BAR; G_SCHED;
;             G_STAGE(G_SB(0, 1), b2 + chB, cB0, qB);
;             G_WAIT_V(6); G_BAR; G_MMA(1, 1, At, B1); G_BAR;
;             G_LDB(B0, 1, 0); G_SCHED; G_LDA(At, 1, 0); G_STAGE(G_SA(0, 1), a2 + chA, cA0, qA);
;             G_WAIT_L(8); G_BAR; G_WAIT_L(0); G_MMA(0, 0, At, B0); G_BAR; G_SCHED;
;             G_LDB(B1, 1, 1); G_STAGE(G_SB(1, 0), b3, cB0, qB);
	s_waitcnt lgkmcnt(0)
	v_mfma_f32_16x16x32_bf16 v[120:123], v[204:207], v[156:159], v[120:123]
	v_mfma_f32_16x16x32_bf16 v[112:115], v[212:215], v[156:159], v[112:115]
	v_mfma_f32_16x16x32_bf16 v[104:107], v[204:207], v[164:167], v[104:107]
	v_mfma_f32_16x16x32_bf16 v[96:99], v[212:215], v[164:167], v[96:99]
	v_mfma_f32_16x16x32_bf16 v[88:91], v[204:207], v[176:179], v[88:91]
	v_mfma_f32_16x16x32_bf16 v[80:83], v[212:215], v[176:179], v[80:83]
	v_mfma_f32_16x16x32_bf16 v[76:79], v[204:207], v[196:199], v[76:79]
	v_mfma_f32_16x16x32_bf16 v[72:75], v[212:215], v[196:199], v[72:75]
	v_mfma_f32_16x16x32_bf16 v[120:123], v[208:211], v[160:163], v[120:123]
	v_mfma_f32_16x16x32_bf16 v[112:115], v[216:219], v[160:163], v[112:115]
	v_mfma_f32_16x16x32_bf16 v[104:107], v[208:211], v[172:175], v[104:107]
	v_mfma_f32_16x16x32_bf16 v[96:99], v[216:219], v[172:175], v[96:99]
	v_mfma_f32_16x16x32_bf16 v[88:91], v[208:211], v[180:183], v[88:91]
	v_mfma_f32_16x16x32_bf16 v[80:83], v[216:219], v[180:183], v[80:83]
	v_mfma_f32_16x16x32_bf16 v[76:79], v[208:211], v[200:203], v[76:79]
	v_mfma_f32_16x16x32_bf16 v[72:75], v[216:219], v[200:203], v[72:75]
	s_barrier
	s_mov_b32 m0, s31
	v_lshl_add_u64 v[220:221], s[20:21], 0, v[2:3]
	s_mov_b64 s[4:5], 0x8000
	ds_read_b128 v[156:159], v138 offset:16384
	ds_read_b128 v[160:163], v138 offset:17408
	ds_read_b128 v[164:167], v138 offset:18432
	ds_read_b128 v[172:175], v138 offset:19456
	ds_read_b128 v[176:179], v138 offset:20480
	ds_read_b128 v[180:183], v138 offset:21504
	ds_read_b128 v[196:199], v138 offset:22528
	ds_read_b128 v[200:203], v138 offset:23552
	global_load_lds_dwordx4 v2, s[20:21]
	s_mov_b32 m0, s33
	s_mov_b64 s[16:17], 0x18000
	s_add_u32 vcc_lo, s20, s4
	s_addc_u32 vcc_hi, s21, s5
	global_load_lds_dwordx4 v2, vcc
	s_barrier
	s_waitcnt lgkmcnt(0)
	s_mov_b64 s[20:21], 0x8080
	s_waitcnt lgkmcnt(0)
	v_mfma_f32_16x16x32_bf16 v[68:71], v[140:143], v[156:159], v[68:71]
	v_mfma_f32_16x16x32_bf16 v[64:67], v[148:151], v[156:159], v[64:67]
	v_mfma_f32_16x16x32_bf16 v[60:63], v[140:143], v[164:167], v[60:63]
	v_mfma_f32_16x16x32_bf16 v[52:55], v[148:151], v[164:167], v[52:55]
	v_mfma_f32_16x16x32_bf16 v[44:47], v[140:143], v[176:179], v[44:47]
	v_mfma_f32_16x16x32_bf16 v[36:39], v[148:151], v[176:179], v[36:39]
	v_mfma_f32_16x16x32_bf16 v[28:31], v[140:143], v[196:199], v[28:31]
	v_mfma_f32_16x16x32_bf16 v[20:23], v[148:151], v[196:199], v[20:23]
	v_mfma_f32_16x16x32_bf16 v[68:71], v[144:147], v[160:163], v[68:71]
	v_mfma_f32_16x16x32_bf16 v[64:67], v[152:155], v[160:163], v[64:67]
	v_mfma_f32_16x16x32_bf16 v[60:63], v[144:147], v[172:175], v[60:63]
	v_mfma_f32_16x16x32_bf16 v[52:55], v[152:155], v[172:175], v[52:55]
	v_mfma_f32_16x16x32_bf16 v[44:47], v[144:147], v[180:183], v[44:47]
	v_mfma_f32_16x16x32_bf16 v[36:39], v[152:155], v[180:183], v[36:39]
	v_mfma_f32_16x16x32_bf16 v[28:31], v[144:147], v[200:203], v[28:31]
	v_mfma_f32_16x16x32_bf16 v[20:23], v[152:155], v[200:203], v[20:23]
	s_barrier
	s_mov_b32 m0, s51
	v_lshl_add_u64 v[140:141], v[184:185], 0, s[58:59]
	global_load_lds_dwordx4 v[140:141], off
	v_lshl_add_u64 v[140:141], v[184:185], 0, s[16:17]
	s_mov_b32 m0, s50
	s_nop 0
	global_load_lds_dwordx4 v[140:141], off
	s_waitcnt vmcnt(6)
	s_barrier
	v_mfma_f32_16x16x32_bf16 v[56:59], v[204:207], v[156:159], v[56:59]
	v_mfma_f32_16x16x32_bf16 v[48:51], v[212:215], v[156:159], v[48:51]
	v_mfma_f32_16x16x32_bf16 v[40:43], v[204:207], v[164:167], v[40:43]
	v_mfma_f32_16x16x32_bf16 v[32:35], v[212:215], v[164:167], v[32:35]
	v_mfma_f32_16x16x32_bf16 v[24:27], v[204:207], v[176:179], v[24:27]
	v_mfma_f32_16x16x32_bf16 v[16:19], v[212:215], v[176:179], v[16:19]
	v_mfma_f32_16x16x32_bf16 v[12:15], v[204:207], v[196:199], v[12:15]
	v_mfma_f32_16x16x32_bf16 v[8:11], v[212:215], v[196:199], v[8:11]
	v_mfma_f32_16x16x32_bf16 v[56:59], v[208:211], v[160:163], v[56:59]
	v_mfma_f32_16x16x32_bf16 v[48:51], v[216:219], v[160:163], v[48:51]
	v_mfma_f32_16x16x32_bf16 v[40:43], v[208:211], v[172:175], v[40:43]
	v_mfma_f32_16x16x32_bf16 v[32:35], v[216:219], v[172:175], v[32:35]
	v_mfma_f32_16x16x32_bf16 v[24:27], v[208:211], v[180:183], v[24:27]
	v_mfma_f32_16x16x32_bf16 v[16:19], v[216:219], v[180:183], v[16:19]
	v_mfma_f32_16x16x32_bf16 v[12:15], v[208:211], v[200:203], v[12:15]
	v_mfma_f32_16x16x32_bf16 v[8:11], v[216:219], v[200:203], v[8:11]
	s_barrier
	ds_read_b128 v[140:143], v255 offset:32768
	ds_read_b128 v[144:147], v255 offset:33792
	ds_read_b128 v[148:151], v255 offset:34816
	ds_read_b128 v[152:155], v255 offset:35840
	s_mov_b32 m0, s34
	v_lshl_add_u64 v[204:205], v[220:221], 0, s[58:59]
	ds_read_b128 v[156:159], v138 offset:32768
	ds_read_b128 v[160:163], v138 offset:33792
	ds_read_b128 v[164:167], v138 offset:34816
	ds_read_b128 v[172:175], v138 offset:35840
	ds_read_b128 v[176:179], v138 offset:36864
	ds_read_b128 v[180:183], v138 offset:37888
	ds_read_b128 v[196:199], v138 offset:38912
	ds_read_b128 v[200:203], v138 offset:39936
	global_load_lds_dwordx4 v[204:205], off
	v_lshl_add_u64 v[204:205], v[220:221], 0, s[16:17]
	s_mov_b32 m0, s35
	s_nop 0
	global_load_lds_dwordx4 v[204:205], off
	s_waitcnt lgkmcnt(8)
	s_barrier
; #define G_STAGE(bufoff, gbase, o0, h64) do { \
;         __builtin_amdgcn_global_load_lds((const unsigned*)((const char*)(gbase) + (o0)), (LAS unsigned*)(lds + (bufoff) + ldsw), 16, 0, 0); \
;         __builtin_amdgcn_global_load_lds((const unsigned*)((const char*)(gbase) + (h64) + (o0)), (LAS unsigned*)(lds + (bufoff) + ldsw + 8192), 16, 0, 0); } while (0)
; #define G_LDA(dst, b, h) do { _Pragma("unroll") for (int m = 0; m < 4; ++m) _Pragma("unroll") for (int k = 0; k < 2; ++k) dst[m][k] = *(const LAS bf16x8*)(lds + G_SA(b, h) + aoff + m * 2048 + k * 1024); } while (0)
; #define G_LDB(dst, b, h) do { _Pragma("unroll") for (int n = 0; n < 2; ++n) _Pragma("unroll") for (int k = 0; k < 2; ++k) dst[n][k] = *(const LAS bf16x8*)(lds + G_SB(b, h) + boff + n * 2048 + k * 1024); } while (0)
; #define G_WAIT_V(n) asm volatile("s_waitcnt vmcnt(" #n ")" ::: "memory")
; #define G_WAIT_L(n) asm volatile("s_waitcnt lgkmcnt(" #n ")" ::: "memory")
; #define G_BAR __builtin_amdgcn_s_barrier()
; #define G_SCHED __builtin_amdgcn_sched_barrier(0)
;     ...
;             G_LDB(B1, 1, 1); G_STAGE(G_SB(1, 0), b3, cB0, qB);
;             G_BAR; G_WAIT_L(0); G_MMA(0, 1, At, B1); G_BAR;
;             G_LDA(At, 1, 1); G_STAGE(G_SA(1, 0), a3, cA0, qA);
;             G_BAR; G_WAIT_L(0); G_MMA(1, 0, At, B0); G_BAR; G_SCHED;
;             G_STAGE(G_SB(1, 1), b3 + chB, cB0, qB);
;             G_WAIT_V(6); G_BAR; G_MMA(1, 1, At, B1); G_BAR;
;         }
	s_waitcnt lgkmcnt(0)
	v_mfma_f32_16x16x32_bf16 v[132:135], v[140:143], v[156:159], v[132:135]
	v_mfma_f32_16x16x32_bf16 v[128:131], v[148:151], v[156:159], v[128:131]
	v_mfma_f32_16x16x32_bf16 v[124:127], v[140:143], v[164:167], v[124:127]
	v_mfma_f32_16x16x32_bf16 v[116:119], v[148:151], v[164:167], v[116:119]
	v_mfma_f32_16x16x32_bf16 v[108:111], v[140:143], v[176:179], v[108:111]
	v_mfma_f32_16x16x32_bf16 v[100:103], v[148:151], v[176:179], v[100:103]
	v_mfma_f32_16x16x32_bf16 v[92:95], v[140:143], v[196:199], v[92:95]
	v_mfma_f32_16x16x32_bf16 v[84:87], v[148:151], v[196:199], v[84:87]
	v_mfma_f32_16x16x32_bf16 v[132:135], v[144:147], v[160:163], v[132:135]
	v_mfma_f32_16x16x32_bf16 v[128:131], v[152:155], v[160:163], v[128:131]
	v_mfma_f32_16x16x32_bf16 v[124:127], v[144:147], v[172:175], v[124:127]
	v_mfma_f32_16x16x32_bf16 v[116:119], v[152:155], v[172:175], v[116:119]
	v_mfma_f32_16x16x32_bf16 v[108:111], v[144:147], v[180:183], v[108:111]
	v_mfma_f32_16x16x32_bf16 v[100:103], v[152:155], v[180:183], v[100:103]
	v_mfma_f32_16x16x32_bf16 v[92:95], v[144:147], v[200:203], v[92:95]
	v_mfma_f32_16x16x32_bf16 v[84:87], v[152:155], v[200:203], v[84:87]
	s_barrier
	s_mov_b32 m0, s19
	v_lshl_add_u64 v[222:223], v[184:185], 0, s[46:47]
	ds_read_b128 v[204:207], v255 offset:49152
	ds_read_b128 v[208:211], v255 offset:50176
	ds_read_b128 v[212:215], v255 offset:51200
	ds_read_b128 v[216:219], v255 offset:52224
	global_load_lds_dwordx4 v[222:223], off
	v_lshl_add_u64 v[222:223], v[184:185], 0, s[20:21]
	s_mov_b32 m0, s44
	s_mov_b64 s[4:5], 0x10080
	global_load_lds_dwordx4 v[222:223], off
	s_barrier
	s_waitcnt lgkmcnt(0)
	v_mfma_f32_16x16x32_bf16 v[120:123], v[204:207], v[156:159], v[120:123]
	v_mfma_f32_16x16x32_bf16 v[112:115], v[212:215], v[156:159], v[112:115]
	v_mfma_f32_16x16x32_bf16 v[104:107], v[204:207], v[164:167], v[104:107]
	v_mfma_f32_16x16x32_bf16 v[96:99], v[212:215], v[164:167], v[96:99]
	v_mfma_f32_16x16x32_bf16 v[88:91], v[204:207], v[176:179], v[88:91]
	v_mfma_f32_16x16x32_bf16 v[80:83], v[212:215], v[176:179], v[80:83]
	v_mfma_f32_16x16x32_bf16 v[76:79], v[204:207], v[196:199], v[76:79]
	v_mfma_f32_16x16x32_bf16 v[72:75], v[212:215], v[196:199], v[72:75]
	v_mfma_f32_16x16x32_bf16 v[120:123], v[208:211], v[160:163], v[120:123]
	v_mfma_f32_16x16x32_bf16 v[112:115], v[216:219], v[160:163], v[112:115]
	v_mfma_f32_16x16x32_bf16 v[104:107], v[208:211], v[172:175], v[104:107]
	v_mfma_f32_16x16x32_bf16 v[96:99], v[216:219], v[172:175], v[96:99]
	v_mfma_f32_16x16x32_bf16 v[88:91], v[208:211], v[180:183], v[88:91]
	v_mfma_f32_16x16x32_bf16 v[80:83], v[216:219], v[180:183], v[80:83]
	v_mfma_f32_16x16x32_bf16 v[76:79], v[208:211], v[200:203], v[76:79]
	v_mfma_f32_16x16x32_bf16 v[72:75], v[216:219], v[200:203], v[72:75]
	s_barrier
	s_mov_b32 m0, s36
	v_lshl_add_u64 v[222:223], v[220:221], 0, s[46:47]
	ds_read_b128 v[156:159], v138 offset:49152
	ds_read_b128 v[160:163], v138 offset:50176
	ds_read_b128 v[164:167], v138 offset:51200
	ds_read_b128 v[172:175], v138 offset:52224
	ds_read_b128 v[176:179], v138 offset:53248
	ds_read_b128 v[180:183], v138 offset:54272
	ds_read_b128 v[196:199], v138 offset:55296
	ds_read_b128 v[200:203], v138 offset:56320
	global_load_lds_dwordx4 v[222:223], off
	v_lshl_add_u64 v[220:221], v[220:221], 0, s[20:21]
	s_mov_b32 m0, s37
	s_nop 0
	global_load_lds_dwordx4 v[220:221], off
	s_barrier
	s_waitcnt lgkmcnt(0)
	v_mfma_f32_16x16x32_bf16 v[68:71], v[140:143], v[156:159], v[68:71]
	v_mfma_f32_16x16x32_bf16 v[64:67], v[148:151], v[156:159], v[64:67]
	v_mfma_f32_16x16x32_bf16 v[60:63], v[140:143], v[164:167], v[60:63]
	v_mfma_f32_16x16x32_bf16 v[52:55], v[148:151], v[164:167], v[52:55]
	v_mfma_f32_16x16x32_bf16 v[44:47], v[140:143], v[176:179], v[44:47]
	v_mfma_f32_16x16x32_bf16 v[36:39], v[148:151], v[176:179], v[36:39]
	v_mfma_f32_16x16x32_bf16 v[28:31], v[140:143], v[196:199], v[28:31]
	v_mfma_f32_16x16x32_bf16 v[20:23], v[148:151], v[196:199], v[20:23]
	v_mfma_f32_16x16x32_bf16 v[68:71], v[144:147], v[160:163], v[68:71]
	v_mfma_f32_16x16x32_bf16 v[64:67], v[152:155], v[160:163], v[64:67]
	v_mfma_f32_16x16x32_bf16 v[60:63], v[144:147], v[172:175], v[60:63]
	v_mfma_f32_16x16x32_bf16 v[52:55], v[152:155], v[172:175], v[52:55]
	v_mfma_f32_16x16x32_bf16 v[44:47], v[144:147], v[180:183], v[44:47]
	v_mfma_f32_16x16x32_bf16 v[36:39], v[152:155], v[180:183], v[36:39]
	v_mfma_f32_16x16x32_bf16 v[28:31], v[144:147], v[200:203], v[28:31]
	v_mfma_f32_16x16x32_bf16 v[20:23], v[152:155], v[200:203], v[20:23]
	s_barrier
	s_mov_b32 m0, s53
	v_lshl_add_u64 v[140:141], v[184:185], 0, s[4:5]
	global_load_lds_dwordx4 v[140:141], off
	v_lshl_add_u64 v[140:141], v[184:185], 0, s[68:69]
	s_mov_b32 m0, s52
	s_nop 0
	global_load_lds_dwordx4 v[140:141], off
	s_waitcnt vmcnt(6)
	s_barrier
	v_mfma_f32_16x16x32_bf16 v[56:59], v[204:207], v[156:159], v[56:59]
	v_mfma_f32_16x16x32_bf16 v[48:51], v[212:215], v[156:159], v[48:51]
	v_mfma_f32_16x16x32_bf16 v[40:43], v[204:207], v[164:167], v[40:43]
	v_mfma_f32_16x16x32_bf16 v[32:35], v[212:215], v[164:167], v[32:35]
	v_mfma_f32_16x16x32_bf16 v[24:27], v[204:207], v[176:179], v[24:27]
	v_mfma_f32_16x16x32_bf16 v[16:19], v[212:215], v[176:179], v[16:19]
	v_mfma_f32_16x16x32_bf16 v[12:15], v[204:207], v[196:199], v[12:15]
	v_mfma_f32_16x16x32_bf16 v[8:11], v[212:215], v[196:199], v[8:11]
	v_mfma_f32_16x16x32_bf16 v[56:59], v[208:211], v[160:163], v[56:59]
	v_mfma_f32_16x16x32_bf16 v[48:51], v[216:219], v[160:163], v[48:51]
	v_mfma_f32_16x16x32_bf16 v[40:43], v[208:211], v[172:175], v[40:43]
	v_mfma_f32_16x16x32_bf16 v[32:35], v[216:219], v[172:175], v[32:35]
	v_mfma_f32_16x16x32_bf16 v[24:27], v[208:211], v[180:183], v[24:27]
	v_mfma_f32_16x16x32_bf16 v[16:19], v[216:219], v[180:183], v[16:19]
	v_mfma_f32_16x16x32_bf16 v[12:15], v[208:211], v[200:203], v[12:15]
	v_mfma_f32_16x16x32_bf16 v[8:11], v[216:219], v[200:203], v[8:11]
	s_andn2_b64 vcc, exec, s[14:15]
	s_mov_b64 s[16:17], -1
	s_mov_b64 s[14:15], 0
	s_mov_b64 s[18:19], 0x100
	s_cbranch_vccz .Ldb_PLE0_cont
	v_readfirstlane_b32 s101, v186
	s_cmpk_gt_u32 s101, 0xff
	s_cbranch_scc1 .Ldb_PLE0_young
	s_barrier
	s_mov_b32 s101, 1
	s_branch .Ldb_PLE0_exit

; #define G_STAGE(bufoff, gbase, o0, h64) do { \
;         __builtin_amdgcn_global_load_lds((const unsigned*)((const char*)(gbase) + (o0)), (LAS unsigned*)(lds + (bufoff) + ldsw), 16, 0, 0); \
;         __builtin_amdgcn_global_load_lds((const unsigned*)((const char*)(gbase) + (h64) + (o0)), (LAS unsigned*)(lds + (bufoff) + ldsw + 8192), 16, 0, 0); } while (0)
; #define G_LDA(dst, b, h) do { _Pragma("unroll") for (int m = 0; m < 4; ++m) _Pragma("unroll") for (int k = 0; k < 2; ++k) dst[m][k] = *(const LAS bf16x8*)(lds + G_SA(b, h) + aoff + m * 2048 + k * 1024); } while (0)
; #define G_LDB(dst, b, h) do { _Pragma("unroll") for (int n = 0; n < 2; ++n) _Pragma("unroll") for (int k = 0; k < 2; ++k) dst[n][k] = *(const LAS bf16x8*)(lds + G_SB(b, h) + boff + n * 2048 + k * 1024); } while (0)
; #define G_WAIT_L(n) asm volatile("s_waitcnt lgkmcnt(" #n ")" ::: "memory")
; #define G_BAR __builtin_amdgcn_s_barrier()
; #define G_SCHED __builtin_amdgcn_sched_barrier(0)
;     ...
;     for (;;) {
;         const bool has_next = sched_next<PH, SUB>(E.ws, E.layer, ui + 1, nxt, E.x);
;         if (!has_next) nxt = cur;
;         const char* nA = nxt.A; const char* nB = nxt.B;
; #pragma unroll 1
;         for (int t = 0; t < nt; t += 2) {
;             const bool last = (t == nt - 2);
;             const char* a1 = cA + (size_t)(t + 1) * ckA;
;             const char* a2 = last ? nA : cA + (size_t)(t + 2) * ckA; const char* b2 = last ? nB : cB + (size_t)(t + 2) * kB;
;             const char* a3 = a2 + ckA; const char* b3 = b2 + kB;
;             G_LDB(B0, 0, 0); G_SCHED; G_LDA(At, 0, 0); G_STAGE(G_SA(1, 1), a1 + chA, cA0, qA);
;             G_WAIT_L(8); G_BAR; G_WAIT_L(0); G_MMA(0, 0, At, B0); G_BAR; G_SCHED;
;             G_LDB(B1, 0, 1); G_STAGE(G_SB(0, 0), b2, cB0, qB);
;             G_BAR; G_WAIT_L(0); G_MMA(0, 1, At, B1); G_BAR;
;     ...
; #pragma unroll
;         for (int a = 0; a < 2; ++a)
; #pragma unroll
;             for (int b = 0; b < 2; ++b)
; #pragma unroll
;                 for (int m = 0; m < 4; ++m)
; #pragma unroll
;                     for (int n = 0; n < 2; ++n) acc[a][b][m][n] = (f32x4){0.f, 0.f, 0.f, 0.f};
;         cur = nxt; cA = nA; cB = nB; ++ui;
.LBB0_1282:
	s_add_u32 s2, s24, 0x40080
	s_addc_u32 s3, s25, 0
	s_add_u32 s22, s22, 0x100
	s_waitcnt lgkmcnt(0)
	v_mov_b64_e32 v[8:9], 0
	s_addc_u32 s23, s23, 0
	s_mov_b32 s24, -2
	v_mov_b64_e32 v[10:11], 0
	v_mov_b64_e32 v[12:13], 0
	v_mov_b64_e32 v[14:15], 0
	v_mov_b64_e32 v[24:25], 0
	v_mov_b64_e32 v[26:27], 0
	v_mov_b64_e32 v[28:29], 0
	v_mov_b64_e32 v[30:31], 0
	v_mov_b64_e32 v[40:41], 0
	v_mov_b64_e32 v[42:43], 0
	v_mov_b64_e32 v[44:45], 0
	v_mov_b64_e32 v[46:47], 0
	v_mov_b64_e32 v[56:57], 0
	v_mov_b64_e32 v[58:59], 0
	v_mov_b64_e32 v[60:61], 0
	v_mov_b64_e32 v[62:63], 0
	v_mov_b64_e32 v[16:17], 0
	v_mov_b64_e32 v[18:19], 0
	v_mov_b64_e32 v[20:21], 0
	v_mov_b64_e32 v[22:23], 0
	v_mov_b64_e32 v[32:33], 0
	v_mov_b64_e32 v[34:35], 0
	v_mov_b64_e32 v[36:37], 0
	v_mov_b64_e32 v[38:39], 0
	v_mov_b64_e32 v[48:49], 0
	v_mov_b64_e32 v[50:51], 0
	v_mov_b64_e32 v[52:53], 0
	v_mov_b64_e32 v[54:55], 0
	v_mov_b64_e32 v[64:65], 0
	v_mov_b64_e32 v[66:67], 0
	v_mov_b64_e32 v[68:69], 0
	v_mov_b64_e32 v[70:71], 0
	v_mov_b64_e32 v[72:73], 0
	v_mov_b64_e32 v[74:75], 0
	v_mov_b64_e32 v[76:77], 0
	v_mov_b64_e32 v[78:79], 0
	v_mov_b64_e32 v[88:89], 0
	v_mov_b64_e32 v[90:91], 0
	v_mov_b64_e32 v[92:93], 0
	v_mov_b64_e32 v[94:95], 0
	v_mov_b64_e32 v[104:105], 0
	v_mov_b64_e32 v[106:107], 0
	v_mov_b64_e32 v[108:109], 0
	v_mov_b64_e32 v[110:111], 0
	v_mov_b64_e32 v[120:121], 0
	v_mov_b64_e32 v[122:123], 0
	v_mov_b64_e32 v[124:125], 0
	v_mov_b64_e32 v[126:127], 0
	v_mov_b64_e32 v[80:81], 0
	v_mov_b64_e32 v[82:83], 0
	v_mov_b64_e32 v[84:85], 0
	v_mov_b64_e32 v[86:87], 0
	v_mov_b64_e32 v[96:97], 0
	v_mov_b64_e32 v[98:99], 0
	v_mov_b64_e32 v[100:101], 0
	v_mov_b64_e32 v[102:103], 0
	v_mov_b64_e32 v[112:113], 0
	v_mov_b64_e32 v[114:115], 0
	v_mov_b64_e32 v[116:117], 0
	v_mov_b64_e32 v[118:119], 0
	v_mov_b64_e32 v[128:129], 0
	v_mov_b64_e32 v[130:131], 0
	v_mov_b64_e32 v[132:133], 0
	v_mov_b64_e32 v[134:135], 0
	s_mov_b64 s[54:55], 0x40000
	s_mov_b64 s[58:59], 0x60000
	s_mov_b64 s[62:63], 0x20080
	s_mov_b64 s[64:65], 0x40080
	s_mov_b64 s[66:67], 0x60080
	s_cmp_eq_u32 s101, 2
	s_cselect_b32 s101, 0, s101
	v_add_u32_e32 v255, 0x10000, v181
.LBB0_1283:
	s_add_u32 s4, s2, 0xfffc0080
	s_addc_u32 s5, s3, -1
	s_add_i32 s25, 0, 0x10000
	ds_read_b128 v[136:139], v255 offset:0
	ds_read_b128 v[140:143], v255 offset:1024
	ds_read_b128 v[144:147], v255 offset:2048
	ds_read_b128 v[148:151], v255 offset:3072
	s_cmp_eq_u32 s24, 12
	s_cselect_b32 s5, s19, s5
	s_cselect_b32 s4, s18, s4
	s_cselect_b32 s41, s21, s23
	s_cselect_b32 s40, s20, s22
	s_add_i32 m0, s29, 0xc000
	ds_read_b128 v[152:155], v182
	ds_read_b128 v[160:163], v182 offset:1024
	ds_read_b128 v[164:167], v182 offset:2048
	ds_read_b128 v[172:175], v182 offset:3072
	ds_read_b128 v[176:179], v182 offset:4096
	ds_read_b128 v[196:199], v182 offset:5120
	ds_read_b128 v[200:203], v182 offset:6144
	ds_read_b128 v[204:207], v182 offset:7168
	global_load_lds_dwordx4 v158, s[2:3]
	s_add_i32 m0, s29, 0xe000
	s_nop 0
	s_add_u32 vcc_lo, s2, s0
	s_addc_u32 vcc_hi, s3, s1
	global_load_lds_dwordx4 v158, vcc
	s_waitcnt lgkmcnt(8)
	s_cmp_eq_u32 s101, 1
	s_cbranch_scc1 .Ldb_PLE1_sk
	s_barrier
.Ldb_PLE1_sk:
	s_mov_b32 s101, 0
	s_waitcnt lgkmcnt(0)
	v_mfma_f32_16x16x32_bf16 v[132:135], v[136:139], v[152:155], v[132:135]
	v_mfma_f32_16x16x32_bf16 v[128:131], v[144:147], v[152:155], v[128:131]
	v_mfma_f32_16x16x32_bf16 v[116:119], v[136:139], v[164:167], v[116:119]
	v_mfma_f32_16x16x32_bf16 v[112:115], v[144:147], v[164:167], v[112:115]
	v_mfma_f32_16x16x32_bf16 v[100:103], v[136:139], v[176:179], v[100:103]
	v_mfma_f32_16x16x32_bf16 v[96:99], v[144:147], v[176:179], v[96:99]
	v_mfma_f32_16x16x32_bf16 v[84:87], v[136:139], v[200:203], v[84:87]
	v_mfma_f32_16x16x32_bf16 v[80:83], v[144:147], v[200:203], v[80:83]
	v_mfma_f32_16x16x32_bf16 v[132:135], v[140:143], v[160:163], v[132:135]
	v_mfma_f32_16x16x32_bf16 v[128:131], v[148:151], v[160:163], v[128:131]
	v_mfma_f32_16x16x32_bf16 v[116:119], v[140:143], v[172:175], v[116:119]
	v_mfma_f32_16x16x32_bf16 v[112:115], v[148:151], v[172:175], v[112:115]
	v_mfma_f32_16x16x32_bf16 v[100:103], v[140:143], v[196:199], v[100:103]
	v_mfma_f32_16x16x32_bf16 v[96:99], v[148:151], v[196:199], v[96:99]
	v_mfma_f32_16x16x32_bf16 v[84:87], v[140:143], v[204:207], v[84:87]
	v_mfma_f32_16x16x32_bf16 v[80:83], v[148:151], v[204:207], v[80:83]
	s_barrier
	s_add_i32 s44, 0, 0x14000
	s_add_i32 s25, s25, s27
	s_mov_b32 m0, s25
	ds_read_b128 v[208:211], v255 offset:16384
	ds_read_b128 v[212:215], v255 offset:17408
	ds_read_b128 v[216:219], v255 offset:18432
	ds_read_b128 v[220:223], v255 offset:19456
	global_load_lds_dwordx4 v156, s[40:41]
	s_add_i32 m0, s25, 0x2000
	s_nop 0
	s_add_u32 vcc_lo, s40, s0
	s_addc_u32 vcc_hi, s41, s1
	global_load_lds_dwordx4 v156, vcc
	s_barrier
	s_waitcnt lgkmcnt(0)
	v_mfma_f32_16x16x32_bf16 v[124:127], v[208:211], v[152:155], v[124:127]
	v_mfma_f32_16x16x32_bf16 v[120:123], v[216:219], v[152:155], v[120:123]
	v_mfma_f32_16x16x32_bf16 v[108:111], v[208:211], v[164:167], v[108:111]
	v_mfma_f32_16x16x32_bf16 v[104:107], v[216:219], v[164:167], v[104:107]
	v_mfma_f32_16x16x32_bf16 v[92:95], v[208:211], v[176:179], v[92:95]
	v_mfma_f32_16x16x32_bf16 v[88:91], v[216:219], v[176:179], v[88:91]
	v_mfma_f32_16x16x32_bf16 v[76:79], v[208:211], v[200:203], v[76:79]
	v_mfma_f32_16x16x32_bf16 v[72:75], v[216:219], v[200:203], v[72:75]
	v_mfma_f32_16x16x32_bf16 v[124:127], v[212:215], v[160:163], v[124:127]
	v_mfma_f32_16x16x32_bf16 v[120:123], v[220:223], v[160:163], v[120:123]
	v_mfma_f32_16x16x32_bf16 v[108:111], v[212:215], v[172:175], v[108:111]
	v_mfma_f32_16x16x32_bf16 v[104:107], v[220:223], v[172:175], v[104:107]
	v_mfma_f32_16x16x32_bf16 v[92:95], v[212:215], v[196:199], v[92:95]
	v_mfma_f32_16x16x32_bf16 v[88:91], v[220:223], v[196:199], v[88:91]
	v_mfma_f32_16x16x32_bf16 v[76:79], v[212:215], v[204:207], v[76:79]
	v_mfma_f32_16x16x32_bf16 v[72:75], v[220:223], v[204:207], v[72:75]
	s_barrier
; #define G_STAGE(bufoff, gbase, o0, h64) do { \
;         __builtin_amdgcn_global_load_lds((const unsigned*)((const char*)(gbase) + (o0)), (LAS unsigned*)(lds + (bufoff) + ldsw), 16, 0, 0); \
;         __builtin_amdgcn_global_load_lds((const unsigned*)((const char*)(gbase) + (h64) + (o0)), (LAS unsigned*)(lds + (bufoff) + ldsw + 8192), 16, 0, 0); } while (0)
; #define G_LDA(dst, b, h) do { _Pragma("unroll") for (int m = 0; m < 4; ++m) _Pragma("unroll") for (int k = 0; k < 2; ++k) dst[m][k] = *(const LAS bf16x8*)(lds + G_SA(b, h) + aoff + m * 2048 + k * 1024); } while (0)
; #define G_LDB(dst, b, h) do { _Pragma("unroll") for (int n = 0; n < 2; ++n) _Pragma("unroll") for (int k = 0; k < 2; ++k) dst[n][k] = *(const LAS bf16x8*)(lds + G_SB(b, h) + boff + n * 2048 + k * 1024); } while (0)
; #define G_WAIT_V(n) asm volatile("s_waitcnt vmcnt(" #n ")" ::: "memory")
; #define G_WAIT_L(n) asm volatile("s_waitcnt lgkmcnt(" #n ")" ::: "memory")
; #define G_BAR __builtin_amdgcn_s_barrier()
; #define G_SCHED __builtin_amdgcn_sched_barrier(0)
;     ...
;             G_LDB(B1, 0, 1); G_STAGE(G_SB(0, 0), b2, cB0, qB);
;             G_BAR; G_WAIT_L(0); G_MMA(0, 1, At, B1); G_BAR;
;             G_LDA(At, 0, 1); G_STAGE(G_SA(0, 0), a2, cA0, qA);
;             G_BAR; G_WAIT_L(0); G_MMA(1, 0, At, B0); G_BAR; G_SCHED;
;             G_STAGE(G_SB(0, 1), b2 + chB, cB0, qB);
;             G_WAIT_V(6); G_BAR; G_MMA(1, 1, At, B1); G_BAR;
;             G_LDB(B0, 1, 0); G_SCHED; G_LDA(At, 1, 0); G_STAGE(G_SA(0, 1), a2 + chA, cA0, qA);
;             G_WAIT_L(8); G_BAR; G_WAIT_L(0); G_MMA(0, 0, At, B0); G_BAR; G_SCHED;
;             G_LDB(B1, 1, 1); G_STAGE(G_SB(1, 0), b3, cB0, qB);
	s_mov_b32 m0, s29
	v_lshl_add_u64 v[224:225], s[4:5], 0, v[2:3]
	ds_read_b128 v[152:155], v182 offset:16384
	ds_read_b128 v[160:163], v182 offset:17408
	ds_read_b128 v[164:167], v182 offset:18432
	ds_read_b128 v[172:175], v182 offset:19456
	ds_read_b128 v[176:179], v182 offset:20480
	ds_read_b128 v[196:199], v182 offset:21504
	ds_read_b128 v[200:203], v182 offset:22528
	ds_read_b128 v[204:207], v182 offset:23552
	global_load_lds_dwordx4 v2, s[4:5]
	s_mov_b32 m0, s30
	s_nop 0
	s_add_u32 vcc_lo, s4, s0
	s_addc_u32 vcc_hi, s5, s1
	global_load_lds_dwordx4 v2, vcc
	s_barrier
	s_waitcnt lgkmcnt(0)
	v_mfma_f32_16x16x32_bf16 v[68:71], v[136:139], v[152:155], v[68:71]
	v_mfma_f32_16x16x32_bf16 v[64:67], v[144:147], v[152:155], v[64:67]
	v_mfma_f32_16x16x32_bf16 v[52:55], v[136:139], v[164:167], v[52:55]
	v_mfma_f32_16x16x32_bf16 v[48:51], v[144:147], v[164:167], v[48:51]
	v_mfma_f32_16x16x32_bf16 v[36:39], v[136:139], v[176:179], v[36:39]
	v_mfma_f32_16x16x32_bf16 v[32:35], v[144:147], v[176:179], v[32:35]
	v_mfma_f32_16x16x32_bf16 v[20:23], v[136:139], v[200:203], v[20:23]
	v_mfma_f32_16x16x32_bf16 v[16:19], v[144:147], v[200:203], v[16:19]
	v_mfma_f32_16x16x32_bf16 v[68:71], v[140:143], v[160:163], v[68:71]
	v_mfma_f32_16x16x32_bf16 v[64:67], v[148:151], v[160:163], v[64:67]
	v_mfma_f32_16x16x32_bf16 v[52:55], v[140:143], v[172:175], v[52:55]
	v_mfma_f32_16x16x32_bf16 v[48:51], v[148:151], v[172:175], v[48:51]
	v_mfma_f32_16x16x32_bf16 v[36:39], v[140:143], v[196:199], v[36:39]
	v_mfma_f32_16x16x32_bf16 v[32:35], v[148:151], v[196:199], v[32:35]
	v_mfma_f32_16x16x32_bf16 v[20:23], v[140:143], v[204:207], v[20:23]
	v_mfma_f32_16x16x32_bf16 v[16:19], v[148:151], v[204:207], v[16:19]
	s_barrier
	s_add_i32 s100, s44, s27
	s_mov_b32 m0, s100
	s_nop 0
	s_add_u32 vcc_lo, s40, s54
	s_addc_u32 vcc_hi, s41, s55
	global_load_lds_dwordx4 v156, vcc
	s_add_i32 m0, s100, 0x2000
	s_nop 0
	s_add_u32 vcc_lo, s40, s58
	s_addc_u32 vcc_hi, s41, s59
	global_load_lds_dwordx4 v156, vcc
	s_waitcnt vmcnt(6)
	s_barrier
	v_mfma_f32_16x16x32_bf16 v[60:63], v[208:211], v[152:155], v[60:63]
	v_mfma_f32_16x16x32_bf16 v[56:59], v[216:219], v[152:155], v[56:59]
	v_mfma_f32_16x16x32_bf16 v[44:47], v[208:211], v[164:167], v[44:47]
	v_mfma_f32_16x16x32_bf16 v[40:43], v[216:219], v[164:167], v[40:43]
	v_mfma_f32_16x16x32_bf16 v[28:31], v[208:211], v[176:179], v[28:31]
	v_mfma_f32_16x16x32_bf16 v[24:27], v[216:219], v[176:179], v[24:27]
	v_mfma_f32_16x16x32_bf16 v[12:15], v[208:211], v[200:203], v[12:15]
	v_mfma_f32_16x16x32_bf16 v[8:11], v[216:219], v[200:203], v[8:11]
	v_mfma_f32_16x16x32_bf16 v[60:63], v[212:215], v[160:163], v[60:63]
	v_mfma_f32_16x16x32_bf16 v[56:59], v[220:223], v[160:163], v[56:59]
	v_mfma_f32_16x16x32_bf16 v[44:47], v[212:215], v[172:175], v[44:47]
	v_mfma_f32_16x16x32_bf16 v[40:43], v[220:223], v[172:175], v[40:43]
	v_mfma_f32_16x16x32_bf16 v[28:31], v[212:215], v[196:199], v[28:31]
	v_mfma_f32_16x16x32_bf16 v[24:27], v[220:223], v[196:199], v[24:27]
	v_mfma_f32_16x16x32_bf16 v[12:15], v[212:215], v[204:207], v[12:15]
	v_mfma_f32_16x16x32_bf16 v[8:11], v[220:223], v[204:207], v[8:11]
	s_barrier
	s_add_i32 s100, 0, 0x18000
	ds_read_b128 v[136:139], v255 offset:32768
	ds_read_b128 v[140:143], v255 offset:33792
	ds_read_b128 v[144:147], v255 offset:34816
	ds_read_b128 v[148:151], v255 offset:35840
	s_mov_b32 m0, s31
	ds_read_b128 v[152:155], v182 offset:32768
	ds_read_b128 v[160:163], v182 offset:33792
	ds_read_b128 v[164:167], v182 offset:34816
	ds_read_b128 v[172:175], v182 offset:35840
	ds_read_b128 v[176:179], v182 offset:36864
	ds_read_b128 v[196:199], v182 offset:37888
	ds_read_b128 v[200:203], v182 offset:38912
	ds_read_b128 v[204:207], v182 offset:39936
	s_add_u32 vcc_lo, s4, s54
	s_addc_u32 vcc_hi, s5, s55
	global_load_lds_dwordx4 v2, vcc
	s_mov_b32 m0, s34
	s_nop 0
	s_add_u32 vcc_lo, s4, s58
	s_addc_u32 vcc_hi, s5, s59
	global_load_lds_dwordx4 v2, vcc
	s_waitcnt lgkmcnt(8)
	s_barrier
	s_waitcnt lgkmcnt(0)
	v_mfma_f32_16x16x32_bf16 v[132:135], v[136:139], v[152:155], v[132:135]
	v_mfma_f32_16x16x32_bf16 v[128:131], v[144:147], v[152:155], v[128:131]
	v_mfma_f32_16x16x32_bf16 v[116:119], v[136:139], v[164:167], v[116:119]
	v_mfma_f32_16x16x32_bf16 v[112:115], v[144:147], v[164:167], v[112:115]
	v_mfma_f32_16x16x32_bf16 v[100:103], v[136:139], v[176:179], v[100:103]
	v_mfma_f32_16x16x32_bf16 v[96:99], v[144:147], v[176:179], v[96:99]
	v_mfma_f32_16x16x32_bf16 v[84:87], v[136:139], v[200:203], v[84:87]
	v_mfma_f32_16x16x32_bf16 v[80:83], v[144:147], v[200:203], v[80:83]
	v_mfma_f32_16x16x32_bf16 v[132:135], v[140:143], v[160:163], v[132:135]
	v_mfma_f32_16x16x32_bf16 v[128:131], v[148:151], v[160:163], v[128:131]
	v_mfma_f32_16x16x32_bf16 v[116:119], v[140:143], v[172:175], v[116:119]
	v_mfma_f32_16x16x32_bf16 v[112:115], v[148:151], v[172:175], v[112:115]
	v_mfma_f32_16x16x32_bf16 v[100:103], v[140:143], v[196:199], v[100:103]
	v_mfma_f32_16x16x32_bf16 v[96:99], v[148:151], v[196:199], v[96:99]
	v_mfma_f32_16x16x32_bf16 v[84:87], v[140:143], v[204:207], v[84:87]
	v_mfma_f32_16x16x32_bf16 v[80:83], v[148:151], v[204:207], v[80:83]
	s_barrier
; #define G_STAGE(bufoff, gbase, o0, h64) do { \
;         __builtin_amdgcn_global_load_lds((const unsigned*)((const char*)(gbase) + (o0)), (LAS unsigned*)(lds + (bufoff) + ldsw), 16, 0, 0); \
;         __builtin_amdgcn_global_load_lds((const unsigned*)((const char*)(gbase) + (h64) + (o0)), (LAS unsigned*)(lds + (bufoff) + ldsw + 8192), 16, 0, 0); } while (0)
; #define G_LDA(dst, b, h) do { _Pragma("unroll") for (int m = 0; m < 4; ++m) _Pragma("unroll") for (int k = 0; k < 2; ++k) dst[m][k] = *(const LAS bf16x8*)(lds + G_SA(b, h) + aoff + m * 2048 + k * 1024); } while (0)
; #define G_LDB(dst, b, h) do { _Pragma("unroll") for (int n = 0; n < 2; ++n) _Pragma("unroll") for (int k = 0; k < 2; ++k) dst[n][k] = *(const LAS bf16x8*)(lds + G_SB(b, h) + boff + n * 2048 + k * 1024); } while (0)
; #define G_WAIT_V(n) asm volatile("s_waitcnt vmcnt(" #n ")" ::: "memory")
; #define G_WAIT_L(n) asm volatile("s_waitcnt lgkmcnt(" #n ")" ::: "memory")
; #define G_BAR __builtin_amdgcn_s_barrier()
; #define G_SCHED __builtin_amdgcn_sched_barrier(0)
;     ...
;             G_LDB(B1, 1, 1); G_STAGE(G_SB(1, 0), b3, cB0, qB);
;             G_BAR; G_WAIT_L(0); G_MMA(0, 1, At, B1); G_BAR;
;             G_LDA(At, 1, 1); G_STAGE(G_SA(1, 0), a3, cA0, qA);
;             G_BAR; G_WAIT_L(0); G_MMA(1, 0, At, B0); G_BAR; G_SCHED;
;             G_STAGE(G_SB(1, 1), b3 + chB, cB0, qB);
;             G_WAIT_V(6); G_BAR; G_MMA(1, 1, At, B1); G_BAR;
;         }
	s_add_i32 s5, 0, 0x1c000
	s_add_i32 s4, s100, s27
	s_mov_b32 m0, s4
	ds_read_b128 v[208:211], v255 offset:49152
	ds_read_b128 v[212:215], v255 offset:50176
	ds_read_b128 v[216:219], v255 offset:51200
	ds_read_b128 v[220:223], v255 offset:52224
	s_add_u32 vcc_lo, s40, s46
	s_addc_u32 vcc_hi, s41, s47
	global_load_lds_dwordx4 v156, vcc
	s_add_i32 m0, s4, 0x2000
	s_nop 0
	s_add_u32 vcc_lo, s40, s62
	s_addc_u32 vcc_hi, s41, s63
	global_load_lds_dwordx4 v156, vcc
	s_barrier
	s_waitcnt lgkmcnt(0)
	v_mfma_f32_16x16x32_bf16 v[124:127], v[208:211], v[152:155], v[124:127]
	v_mfma_f32_16x16x32_bf16 v[120:123], v[216:219], v[152:155], v[120:123]
	v_mfma_f32_16x16x32_bf16 v[108:111], v[208:211], v[164:167], v[108:111]
	v_mfma_f32_16x16x32_bf16 v[104:107], v[216:219], v[164:167], v[104:107]
	v_mfma_f32_16x16x32_bf16 v[92:95], v[208:211], v[176:179], v[92:95]
	v_mfma_f32_16x16x32_bf16 v[88:91], v[216:219], v[176:179], v[88:91]
	v_mfma_f32_16x16x32_bf16 v[76:79], v[208:211], v[200:203], v[76:79]
	v_mfma_f32_16x16x32_bf16 v[72:75], v[216:219], v[200:203], v[72:75]
	v_mfma_f32_16x16x32_bf16 v[124:127], v[212:215], v[160:163], v[124:127]
	v_mfma_f32_16x16x32_bf16 v[120:123], v[220:223], v[160:163], v[120:123]
	v_mfma_f32_16x16x32_bf16 v[108:111], v[212:215], v[172:175], v[108:111]
	v_mfma_f32_16x16x32_bf16 v[104:107], v[220:223], v[172:175], v[104:107]
	v_mfma_f32_16x16x32_bf16 v[92:95], v[212:215], v[196:199], v[92:95]
	v_mfma_f32_16x16x32_bf16 v[88:91], v[220:223], v[196:199], v[88:91]
	v_mfma_f32_16x16x32_bf16 v[76:79], v[212:215], v[204:207], v[76:79]
	v_mfma_f32_16x16x32_bf16 v[72:75], v[220:223], v[204:207], v[72:75]
	s_barrier
	s_mov_b32 m0, s35
	v_lshl_add_u64 v[226:227], v[224:225], 0, s[46:47]
	ds_read_b128 v[152:155], v182 offset:49152
	ds_read_b128 v[160:163], v182 offset:50176
	ds_read_b128 v[164:167], v182 offset:51200
	ds_read_b128 v[172:175], v182 offset:52224
	ds_read_b128 v[176:179], v182 offset:53248
	ds_read_b128 v[196:199], v182 offset:54272
	ds_read_b128 v[200:203], v182 offset:55296
	ds_read_b128 v[204:207], v182 offset:56320
	global_load_lds_dwordx4 v[226:227], off
	v_lshl_add_u64 v[224:225], v[224:225], 0, s[62:63]
	s_mov_b32 m0, s36
	s_nop 0
	global_load_lds_dwordx4 v[224:225], off
	s_barrier
	s_waitcnt lgkmcnt(0)
	v_mfma_f32_16x16x32_bf16 v[68:71], v[136:139], v[152:155], v[68:71]
	v_mfma_f32_16x16x32_bf16 v[64:67], v[144:147], v[152:155], v[64:67]
	v_mfma_f32_16x16x32_bf16 v[52:55], v[136:139], v[164:167], v[52:55]
	v_mfma_f32_16x16x32_bf16 v[48:51], v[144:147], v[164:167], v[48:51]
	v_mfma_f32_16x16x32_bf16 v[36:39], v[136:139], v[176:179], v[36:39]
	v_mfma_f32_16x16x32_bf16 v[32:35], v[144:147], v[176:179], v[32:35]
	v_mfma_f32_16x16x32_bf16 v[20:23], v[136:139], v[200:203], v[20:23]
	v_mfma_f32_16x16x32_bf16 v[16:19], v[144:147], v[200:203], v[16:19]
	v_mfma_f32_16x16x32_bf16 v[68:71], v[140:143], v[160:163], v[68:71]
	v_mfma_f32_16x16x32_bf16 v[64:67], v[148:151], v[160:163], v[64:67]
	v_mfma_f32_16x16x32_bf16 v[52:55], v[140:143], v[172:175], v[52:55]
	v_mfma_f32_16x16x32_bf16 v[48:51], v[148:151], v[172:175], v[48:51]
	v_mfma_f32_16x16x32_bf16 v[36:39], v[140:143], v[196:199], v[36:39]
	v_mfma_f32_16x16x32_bf16 v[32:35], v[148:151], v[196:199], v[32:35]
	v_mfma_f32_16x16x32_bf16 v[20:23], v[140:143], v[204:207], v[20:23]
	v_mfma_f32_16x16x32_bf16 v[16:19], v[148:151], v[204:207], v[16:19]
	s_barrier
	s_add_i32 s4, s5, s27
	s_mov_b32 m0, s4
	s_nop 0
	s_add_u32 vcc_lo, s40, s64
	s_addc_u32 vcc_hi, s41, s65
	global_load_lds_dwordx4 v156, vcc
	s_add_i32 m0, s4, 0x2000
	s_nop 0
	s_add_u32 vcc_lo, s40, s66
	s_addc_u32 vcc_hi, s41, s67
	global_load_lds_dwordx4 v156, vcc
	s_add_i32 s24, s24, 2
	s_add_u32 s2, s2, 0x100
	s_addc_u32 s3, s3, 0
	s_add_u32 s22, s22, 0x100
	s_addc_u32 s23, s23, 0
	s_cmp_gt_u32 s24, 13
	s_waitcnt vmcnt(6)
	s_barrier
	v_mfma_f32_16x16x32_bf16 v[60:63], v[208:211], v[152:155], v[60:63]
	v_mfma_f32_16x16x32_bf16 v[56:59], v[216:219], v[152:155], v[56:59]
	v_mfma_f32_16x16x32_bf16 v[44:47], v[208:211], v[164:167], v[44:47]
	v_mfma_f32_16x16x32_bf16 v[40:43], v[216:219], v[164:167], v[40:43]
	v_mfma_f32_16x16x32_bf16 v[28:31], v[208:211], v[176:179], v[28:31]
	v_mfma_f32_16x16x32_bf16 v[24:27], v[216:219], v[176:179], v[24:27]
	v_mfma_f32_16x16x32_bf16 v[12:15], v[208:211], v[200:203], v[12:15]
	v_mfma_f32_16x16x32_bf16 v[8:11], v[216:219], v[200:203], v[8:11]
	v_mfma_f32_16x16x32_bf16 v[60:63], v[212:215], v[160:163], v[60:63]
	v_mfma_f32_16x16x32_bf16 v[56:59], v[220:223], v[160:163], v[56:59]
	v_mfma_f32_16x16x32_bf16 v[44:47], v[212:215], v[172:175], v[44:47]
	v_mfma_f32_16x16x32_bf16 v[40:43], v[220:223], v[172:175], v[40:43]
	v_mfma_f32_16x16x32_bf16 v[28:31], v[212:215], v[196:199], v[28:31]
	v_mfma_f32_16x16x32_bf16 v[24:27], v[220:223], v[196:199], v[24:27]
	v_mfma_f32_16x16x32_bf16 v[12:15], v[212:215], v[204:207], v[12:15]
	v_mfma_f32_16x16x32_bf16 v[8:11], v[220:223], v[204:207], v[8:11]
	s_cbranch_scc0 .Ldb_PLE1_cont
	v_readfirstlane_b32 s101, v186
	s_cmpk_gt_u32 s101, 0xff
	s_cbranch_scc1 .Ldb_PLE1_young
	s_barrier
	s_mov_b32 s101, 1
	s_branch .Ldb_PLE1_exit
